# v28 + s_setprio 1 moved before the opening s_barrier of each MFMA block and the redundant lgkmcnt(0) after it removed (MFMA block starts right at barrier release)
# baseline (speedup 1.0000x reference)
; #define PG8_STAGE(bufoff, gbase, voff) do { _Pragma("unroll") for (int _i = 0; _i < 2; ++_i) \
;         __builtin_amdgcn_global_load_lds((const unsigned*)((const char*)(gbase) + (voff)[_i]), (PG8_LAS unsigned*)(lds + (bufoff) + ldsw + _i * 8192), 16, 0, 0); } while (0)
; #define PG8_LDA(dst, b, h) do { _Pragma("unroll") for (int m = 0; m < 4; ++m) _Pragma("unroll") for (int k = 0; k < 2; ++k) dst[m][k] = *(const PG8_LAS bf16x8*)(lds + PG8_SA(b, h) + aoff + m * 2048 + k * 1024); } while (0)
; #define PG8_BAR __builtin_amdgcn_s_barrier()
; template <class Epi, class Sched, bool ALIGN_EPI = false, bool SP2 = false>
; __device__ __forceinline__ void gemm_phase(PG8_LAS unsigned char* lds, const Gemm g, const Sched& S, const Epi& E) {
;     ...
;         const char* nA = has_next ? (const char*)g.A + (size_t)nxt.pm * tstep : cA; const char* nB = has_next ? (const char*)g.Bt + (size_t)nxt.pn * tstep : cB;
;         for (int t = 0; t < nt; t += 2) {
;             const bool last = (t == nt - 2);
;             const char* a1 = cA + (size_t)(t + 1) * kstep;
;             const char* a2 = last ? nA : cA + (size_t)(t + 2) * kstep; const char* b2 = last ? nB : cB + (size_t)(t + 2) * kstep;
;             const char* a3 = a2 + kstep; const char* b3 = b2 + kstep;
;             if (last && has_next) S.a_ready(nxt);
;             if constexpr (SP2) {
;             PG8_LDB(B0, 0, 0); PG8_LDB(B1, 0, 1); PG8_SCHED; PG8_LDA(At, 0, 0); PG8_STAGE(PG8_SA(1, 1), a1 + hstep, voffA);
;             PG8_WAIT_V(8); PG8_WAIT_L(0); PG8_BAR; PG8_MMA(0, 0, At, B0); PG8_MMA(0, 1, At, B1); PG8_BAR; PG8_SCHED;
;             PG8_LDA(At, 0, 1); PG8_STAGE(PG8_SB(0, 0), b2, voffB); PG8_STAGE(PG8_SB(0, 1), b2 + hstep, voffB); PG8_STAGE(PG8_SA(0, 0), a2, voffA);
;             PG8_WAIT_V(8); PG8_WAIT_L(0); PG8_BAR; PG8_MMA(1, 0, At, B0); PG8_MMA(1, 1, At, B1); PG8_BAR; PG8_SCHED;
;             PG8_LDB(B0, 1, 0); PG8_LDB(B1, 1, 1); PG8_SCHED; PG8_LDA(At, 1, 0); PG8_STAGE(PG8_SA(0, 1), a2 + hstep, voffA);
;             PG8_WAIT_V(8); PG8_WAIT_L(0); PG8_BAR; PG8_MMA(0, 0, At, B0); PG8_MMA(0, 1, At, B1); PG8_BAR; PG8_SCHED;
;             PG8_LDA(At, 1, 1); PG8_STAGE(PG8_SB(1, 0), b3, voffB); PG8_STAGE(PG8_SB(1, 1), b3 + hstep, voffB); PG8_STAGE(PG8_SA(1, 0), a3, voffA);
;             PG8_WAIT_V(8); PG8_WAIT_L(0); PG8_BAR; PG8_MMA(1, 0, At, B0); PG8_MMA(1, 1, At, B1); PG8_BAR; PG8_SCHED;
.LBB0_367:
	s_ashr_i32 s11, s10, 31
	s_lshl_b64 s[12:13], s[10:11], 19
	s_add_u32 s12, s90, s12
	s_addc_u32 s13, s91, s13
	s_and_b64 s[14:15], s[4:5], exec
	s_cselect_b32 s11, s13, s17
	s_cselect_b32 s50, s12, s16
	s_ashr_i32 s9, s8, 31
	s_lshl_b64 s[14:15], s[8:9], 19
	s_add_u32 s14, s22, s14
	s_addc_u32 s15, s23, s15
	s_and_b64 s[20:21], s[4:5], exec
	s_cselect_b32 s9, s15, s19
	s_cselect_b32 s51, s14, s18
	s_add_u32 s16, s16, 0x40080
	s_addc_u32 s17, s17, 0
	s_add_u32 s52, s18, 0x100
	s_addc_u32 s53, s19, 0
	s_mov_b32 s55, -2
	s_add_u32 s18, s16, 0xfffc0080
	s_addc_u32 s19, s17, -1
	s_add_i32 s56, 0, 0x10000
	s_cmp_eq_u32 s55, 12
	s_cselect_b32 s21, s11, s19
	s_cselect_b32 s20, s50, s18
	s_cselect_b32 s19, s9, s53
	s_cselect_b32 s18, s51, s52
	s_add_i32 s58, 0, 0x14000
	v_lshl_add_u64 v[140:141], s[16:17], 0, v[136:137]
	s_add_i32 m0, s25, 0xc000
	global_load_lds_dwordx4 v[140:141], off
	v_lshl_add_u64 v[140:141], s[16:17], 0, v[138:139]
	s_add_i32 m0, s25, 0xe000
	s_nop 0
	global_load_lds_dwordx4 v[140:141], off
	s_waitcnt vmcnt(16)
	s_waitcnt lgkmcnt(0)
	s_setprio 1
	s_barrier
	v_mfma_f32_16x16x32_bf16 v[122:125], v[154:157], v[204:207], 0
	v_mfma_f32_16x16x32_bf16 v[114:117], v[162:165], v[204:207], 0
	v_mfma_f32_16x16x32_bf16 v[106:109], v[154:157], v[212:215], 0
	v_mfma_f32_16x16x32_bf16 v[98:101], v[162:165], v[212:215], 0
	v_mfma_f32_16x16x32_bf16 v[90:93], v[154:157], v[220:223], 0
	v_mfma_f32_16x16x32_bf16 v[82:85], v[162:165], v[220:223], 0
	v_mfma_f32_16x16x32_bf16 v[74:77], v[154:157], v[228:231], 0
	v_mfma_f32_16x16x32_bf16 v[66:69], v[162:165], v[228:231], 0
	v_mfma_f32_16x16x32_bf16 v[122:125], v[158:161], v[208:211], v[122:125]
	v_mfma_f32_16x16x32_bf16 v[114:117], v[166:169], v[208:211], v[114:117]
	v_mfma_f32_16x16x32_bf16 v[106:109], v[158:161], v[216:219], v[106:109]
	v_mfma_f32_16x16x32_bf16 v[98:101], v[166:169], v[216:219], v[98:101]
	v_mfma_f32_16x16x32_bf16 v[90:93], v[158:161], v[224:227], v[90:93]
	v_mfma_f32_16x16x32_bf16 v[82:85], v[166:169], v[224:227], v[82:85]
	v_mfma_f32_16x16x32_bf16 v[74:77], v[158:161], v[232:235], v[74:77]
	v_mfma_f32_16x16x32_bf16 v[66:69], v[166:169], v[232:235], v[66:69]
	s_setprio 0
	s_setprio 1
	v_mfma_f32_16x16x32_bf16 v[126:129], v[170:173], v[204:207], 0
	v_mfma_f32_16x16x32_bf16 v[118:121], v[178:181], v[204:207], 0
	v_mfma_f32_16x16x32_bf16 v[110:113], v[170:173], v[212:215], 0
	v_mfma_f32_16x16x32_bf16 v[102:105], v[178:181], v[212:215], 0
	v_mfma_f32_16x16x32_bf16 v[94:97], v[170:173], v[220:223], 0
	v_mfma_f32_16x16x32_bf16 v[86:89], v[178:181], v[220:223], 0
	v_mfma_f32_16x16x32_bf16 v[78:81], v[170:173], v[228:231], 0
	v_mfma_f32_16x16x32_bf16 v[70:73], v[178:181], v[228:231], 0
	v_mfma_f32_16x16x32_bf16 v[126:129], v[174:177], v[208:211], v[126:129]
	v_mfma_f32_16x16x32_bf16 v[118:121], v[200:203], v[208:211], v[118:121]
	v_mfma_f32_16x16x32_bf16 v[110:113], v[174:177], v[216:219], v[110:113]
	v_mfma_f32_16x16x32_bf16 v[102:105], v[200:203], v[216:219], v[102:105]
	v_mfma_f32_16x16x32_bf16 v[94:97], v[174:177], v[224:227], v[94:97]
	v_mfma_f32_16x16x32_bf16 v[86:89], v[200:203], v[224:227], v[86:89]
	v_mfma_f32_16x16x32_bf16 v[78:81], v[174:177], v[232:235], v[78:81]
	v_mfma_f32_16x16x32_bf16 v[70:73], v[200:203], v[232:235], v[70:73]
	s_barrier
	s_setprio 0
	s_add_i32 s56, s56, s24
	v_lshl_add_u64 v[140:141], s[18:19], 0, v[0:1]
	s_mov_b32 m0, s56
	ds_read_b128 v[204:207], v145 offset:16384
	ds_read_b128 v[208:211], v145 offset:17408
	ds_read_b128 v[212:215], v145 offset:18432
	ds_read_b128 v[216:219], v145 offset:19456
	ds_read_b128 v[220:223], v145 offset:20480
	ds_read_b128 v[224:227], v145 offset:21504
	ds_read_b128 v[228:231], v145 offset:22528
	ds_read_b128 v[232:235], v145 offset:23552
	global_load_lds_dwordx4 v[140:141], off
	s_add_i32 m0, s56, 0x2000
	s_add_u32 s56, s18, 0x40000
	v_lshl_add_u64 v[146:147], s[18:19], 0, v[130:131]
	s_addc_u32 s57, s19, 0
	s_add_i32 s58, s58, s24
	global_load_lds_dwordx4 v[146:147], off
	v_lshl_add_u64 v[148:149], s[56:57], 0, v[0:1]
	s_mov_b32 m0, s58
	v_lshl_add_u64 v[236:237], s[20:21], 0, v[132:133]
	global_load_lds_dwordx4 v[148:149], off
	v_lshl_add_u64 v[148:149], s[56:57], 0, v[130:131]
	s_add_i32 m0, s58, 0x2000
	s_nop 0
	global_load_lds_dwordx4 v[148:149], off
	v_lshl_add_u64 v[148:149], s[20:21], 0, v[134:135]
	s_mov_b32 m0, s25
	s_nop 0
	global_load_lds_dwordx4 v[148:149], off
	s_mov_b32 m0, s26
	s_nop 0
	global_load_lds_dwordx4 v[236:237], off
	s_waitcnt vmcnt(16)
	s_waitcnt lgkmcnt(0)
	s_setprio 1
	s_barrier
	v_mfma_f32_16x16x32_bf16 v[58:61], v[154:157], v[204:207], 0
	v_mfma_f32_16x16x32_bf16 v[50:53], v[162:165], v[204:207], 0
	v_mfma_f32_16x16x32_bf16 v[42:45], v[154:157], v[212:215], 0
	v_mfma_f32_16x16x32_bf16 v[34:37], v[162:165], v[212:215], 0
	v_mfma_f32_16x16x32_bf16 v[26:29], v[154:157], v[220:223], 0
	v_mfma_f32_16x16x32_bf16 v[18:21], v[162:165], v[220:223], 0
	v_mfma_f32_16x16x32_bf16 v[10:13], v[154:157], v[228:231], 0
	v_mfma_f32_16x16x32_bf16 v[2:5], v[162:165], v[228:231], 0
	v_mfma_f32_16x16x32_bf16 v[58:61], v[158:161], v[208:211], v[58:61]
	v_mfma_f32_16x16x32_bf16 v[50:53], v[166:169], v[208:211], v[50:53]
	v_mfma_f32_16x16x32_bf16 v[42:45], v[158:161], v[216:219], v[42:45]
	v_mfma_f32_16x16x32_bf16 v[34:37], v[166:169], v[216:219], v[34:37]
	v_mfma_f32_16x16x32_bf16 v[26:29], v[158:161], v[224:227], v[26:29]
	v_mfma_f32_16x16x32_bf16 v[18:21], v[166:169], v[224:227], v[18:21]
	v_mfma_f32_16x16x32_bf16 v[10:13], v[158:161], v[232:235], v[10:13]
	v_mfma_f32_16x16x32_bf16 v[2:5], v[166:169], v[232:235], v[2:5]
	s_setprio 0
	s_setprio 1
	v_mfma_f32_16x16x32_bf16 v[62:65], v[170:173], v[204:207], 0
	v_mfma_f32_16x16x32_bf16 v[54:57], v[178:181], v[204:207], 0
	v_mfma_f32_16x16x32_bf16 v[46:49], v[170:173], v[212:215], 0
	v_mfma_f32_16x16x32_bf16 v[38:41], v[178:181], v[212:215], 0
	v_mfma_f32_16x16x32_bf16 v[30:33], v[170:173], v[220:223], 0
	v_mfma_f32_16x16x32_bf16 v[22:25], v[178:181], v[220:223], 0
	v_mfma_f32_16x16x32_bf16 v[14:17], v[170:173], v[228:231], 0
	v_mfma_f32_16x16x32_bf16 v[6:9], v[178:181], v[228:231], 0
	v_mfma_f32_16x16x32_bf16 v[62:65], v[174:177], v[208:211], v[62:65]
	v_mfma_f32_16x16x32_bf16 v[54:57], v[200:203], v[208:211], v[54:57]
	v_mfma_f32_16x16x32_bf16 v[46:49], v[174:177], v[216:219], v[46:49]
	v_mfma_f32_16x16x32_bf16 v[38:41], v[200:203], v[216:219], v[38:41]
	v_mfma_f32_16x16x32_bf16 v[30:33], v[174:177], v[224:227], v[30:33]
	v_mfma_f32_16x16x32_bf16 v[22:25], v[200:203], v[224:227], v[22:25]
	v_mfma_f32_16x16x32_bf16 v[14:17], v[174:177], v[232:235], v[14:17]
	v_mfma_f32_16x16x32_bf16 v[6:9], v[200:203], v[232:235], v[6:9]
	s_barrier
; #define PG8_STAGE(bufoff, gbase, voff) do { _Pragma("unroll") for (int _i = 0; _i < 2; ++_i) \
;         __builtin_amdgcn_global_load_lds((const unsigned*)((const char*)(gbase) + (voff)[_i]), (PG8_LAS unsigned*)(lds + (bufoff) + ldsw + _i * 8192), 16, 0, 0); } while (0)
; #define PG8_LDA(dst, b, h) do { _Pragma("unroll") for (int m = 0; m < 4; ++m) _Pragma("unroll") for (int k = 0; k < 2; ++k) dst[m][k] = *(const PG8_LAS bf16x8*)(lds + PG8_SA(b, h) + aoff + m * 2048 + k * 1024); } while (0)
; #define PG8_LDB(dst, b, h) do { _Pragma("unroll") for (int n = 0; n < 2; ++n) _Pragma("unroll") for (int k = 0; k < 2; ++k) dst[n][k] = *(const PG8_LAS bf16x8*)(lds + PG8_SB(b, h) + boff + n * 2048 + k * 1024); } while (0)
; #define PG8_MMA(ai, bj, At, Bt) do { __builtin_amdgcn_s_setprio(1); _Pragma("unroll") for (int m = 0; m < 4; ++m) _Pragma("unroll") for (int n = 0; n < 2; ++n) _Pragma("unroll") for (int k = 0; k < 2; ++k) \
;         acc[ai][bj][m][n] = __builtin_amdgcn_mfma_f32_16x16x32_bf16(Bt[n][k], At[m][k], acc[ai][bj][m][n], 0, 0, 0); __builtin_amdgcn_s_setprio(0); } while (0)
; #define PG8_WAIT_V(n) asm volatile("s_waitcnt vmcnt(" #n ")" ::: "memory")
; #define PG8_WAIT_L(n) asm volatile("s_waitcnt lgkmcnt(" #n ")" ::: "memory")
; #define PG8_BAR __builtin_amdgcn_s_barrier()
; #define PG8_SCHED __builtin_amdgcn_sched_barrier(0)
; template <class Epi, class Sched, bool ALIGN_EPI = false, bool SP2 = false>
; __device__ __forceinline__ void gemm_phase(PG8_LAS unsigned char* lds, const Gemm g, const Sched& S, const Epi& E) {
;     ...
;             PG8_LDB(B0, 1, 0); PG8_LDB(B1, 1, 1); PG8_SCHED; PG8_LDA(At, 1, 0); PG8_STAGE(PG8_SA(0, 1), a2 + hstep, voffA);
;             PG8_WAIT_V(8); PG8_WAIT_L(0); PG8_BAR; PG8_MMA(0, 0, At, B0); PG8_MMA(0, 1, At, B1); PG8_BAR; PG8_SCHED;
;             PG8_LDA(At, 1, 1); PG8_STAGE(PG8_SB(1, 0), b3, voffB); PG8_STAGE(PG8_SB(1, 1), b3 + hstep, voffB); PG8_STAGE(PG8_SA(1, 0), a3, voffA);
;             PG8_WAIT_V(8); PG8_WAIT_L(0); PG8_BAR; PG8_MMA(1, 0, At, B0); PG8_MMA(1, 1, At, B1); PG8_BAR; PG8_SCHED;
	s_setprio 0
	s_add_i32 s56, 0, 0x18000
	s_add_i32 s57, 0, 0x1c000
	v_add_u32_e32 v166, s56, v143
	v_add_u32_e32 v200, s57, v143
	ds_read_b128 v[154:157], v166
	ds_read_b128 v[158:161], v166 offset:1024
	ds_read_b128 v[162:165], v166 offset:2048
	ds_read_b128 v[166:169], v166 offset:3072
	ds_read_b128 v[170:173], v200
	ds_read_b128 v[174:177], v200 offset:1024
	ds_read_b128 v[178:181], v200 offset:2048
	ds_read_b128 v[200:203], v200 offset:3072
	s_add_u32 s20, s20, 0x40000
	s_addc_u32 s21, s21, 0
	s_mov_b32 m0, s27
	v_lshl_add_u64 v[238:239], s[20:21], 0, v[134:135]
	ds_read_b128 v[204:207], v145 offset:32768
	ds_read_b128 v[208:211], v145 offset:33792
	ds_read_b128 v[212:215], v145 offset:34816
	ds_read_b128 v[216:219], v145 offset:35840
	ds_read_b128 v[220:223], v145 offset:36864
	ds_read_b128 v[224:227], v145 offset:37888
	ds_read_b128 v[228:231], v145 offset:38912
	ds_read_b128 v[232:235], v145 offset:39936
	global_load_lds_dwordx4 v[238:239], off
	v_lshl_add_u64 v[238:239], s[20:21], 0, v[132:133]
	s_mov_b32 m0, s28
	s_nop 0
	global_load_lds_dwordx4 v[238:239], off
	s_waitcnt vmcnt(8)
	s_waitcnt lgkmcnt(0)
	s_setprio 1
	s_barrier
	v_mfma_f32_16x16x32_bf16 v[122:125], v[154:157], v[204:207], v[122:125]
	v_mfma_f32_16x16x32_bf16 v[114:117], v[162:165], v[204:207], v[114:117]
	v_mfma_f32_16x16x32_bf16 v[106:109], v[154:157], v[212:215], v[106:109]
	v_mfma_f32_16x16x32_bf16 v[98:101], v[162:165], v[212:215], v[98:101]
	v_mfma_f32_16x16x32_bf16 v[90:93], v[154:157], v[220:223], v[90:93]
	v_mfma_f32_16x16x32_bf16 v[82:85], v[162:165], v[220:223], v[82:85]
	v_mfma_f32_16x16x32_bf16 v[74:77], v[154:157], v[228:231], v[74:77]
	v_mfma_f32_16x16x32_bf16 v[66:69], v[162:165], v[228:231], v[66:69]
	v_mfma_f32_16x16x32_bf16 v[122:125], v[158:161], v[208:211], v[122:125]
	v_mfma_f32_16x16x32_bf16 v[114:117], v[166:169], v[208:211], v[114:117]
	v_mfma_f32_16x16x32_bf16 v[106:109], v[158:161], v[216:219], v[106:109]
	v_mfma_f32_16x16x32_bf16 v[98:101], v[166:169], v[216:219], v[98:101]
	v_mfma_f32_16x16x32_bf16 v[90:93], v[158:161], v[224:227], v[90:93]
	v_mfma_f32_16x16x32_bf16 v[82:85], v[166:169], v[224:227], v[82:85]
	v_mfma_f32_16x16x32_bf16 v[74:77], v[158:161], v[232:235], v[74:77]
	v_mfma_f32_16x16x32_bf16 v[66:69], v[166:169], v[232:235], v[66:69]
	s_setprio 0
	s_setprio 1
	v_mfma_f32_16x16x32_bf16 v[126:129], v[170:173], v[204:207], v[126:129]
	v_mfma_f32_16x16x32_bf16 v[118:121], v[178:181], v[204:207], v[118:121]
	v_mfma_f32_16x16x32_bf16 v[110:113], v[170:173], v[212:215], v[110:113]
	v_mfma_f32_16x16x32_bf16 v[102:105], v[178:181], v[212:215], v[102:105]
	v_mfma_f32_16x16x32_bf16 v[94:97], v[170:173], v[220:223], v[94:97]
	v_mfma_f32_16x16x32_bf16 v[86:89], v[178:181], v[220:223], v[86:89]
	v_mfma_f32_16x16x32_bf16 v[78:81], v[170:173], v[228:231], v[78:81]
	v_mfma_f32_16x16x32_bf16 v[70:73], v[178:181], v[228:231], v[70:73]
	v_mfma_f32_16x16x32_bf16 v[126:129], v[174:177], v[208:211], v[126:129]
	v_mfma_f32_16x16x32_bf16 v[118:121], v[200:203], v[208:211], v[118:121]
	v_mfma_f32_16x16x32_bf16 v[110:113], v[174:177], v[216:219], v[110:113]
	v_mfma_f32_16x16x32_bf16 v[102:105], v[200:203], v[216:219], v[102:105]
	v_mfma_f32_16x16x32_bf16 v[94:97], v[174:177], v[224:227], v[94:97]
	v_mfma_f32_16x16x32_bf16 v[86:89], v[200:203], v[224:227], v[86:89]
	v_mfma_f32_16x16x32_bf16 v[78:81], v[174:177], v[232:235], v[78:81]
	v_mfma_f32_16x16x32_bf16 v[70:73], v[200:203], v[232:235], v[70:73]
	s_barrier
	s_setprio 0
	s_add_i32 s20, s56, s24
	v_lshl_add_u64 v[140:141], v[140:141], 0, s[38:39]
	s_mov_b32 m0, s20
	ds_read_b128 v[204:207], v145 offset:49152
	ds_read_b128 v[208:211], v145 offset:50176
	ds_read_b128 v[212:215], v145 offset:51200
	ds_read_b128 v[216:219], v145 offset:52224
	ds_read_b128 v[220:223], v145 offset:53248
	ds_read_b128 v[224:227], v145 offset:54272
	ds_read_b128 v[228:231], v145 offset:55296
	ds_read_b128 v[232:235], v145 offset:56320
	global_load_lds_dwordx4 v[140:141], off
	s_add_i32 m0, s20, 0x2000
	s_add_u32 s18, s18, 0x40080
	v_lshl_add_u64 v[140:141], v[146:147], 0, s[38:39]
	s_addc_u32 s19, s19, 0
	s_add_i32 s20, s57, s24
	global_load_lds_dwordx4 v[140:141], off
	v_lshl_add_u64 v[140:141], s[18:19], 0, v[0:1]
	s_mov_b32 m0, s20
	s_nop 0
	global_load_lds_dwordx4 v[140:141], off
	v_lshl_add_u64 v[140:141], s[18:19], 0, v[130:131]
	s_add_i32 m0, s20, 0x2000
	s_nop 0
	global_load_lds_dwordx4 v[140:141], off
	v_lshl_add_u64 v[140:141], v[148:149], 0, s[38:39]
	s_mov_b32 m0, s29
	s_nop 0
	global_load_lds_dwordx4 v[140:141], off
	v_lshl_add_u64 v[140:141], v[236:237], 0, s[38:39]
	s_mov_b32 m0, s30
	s_nop 0
	global_load_lds_dwordx4 v[140:141], off
	s_waitcnt vmcnt(8)
	s_waitcnt lgkmcnt(0)
	s_setprio 1
	s_barrier
; #define PG8_STAGE(bufoff, gbase, voff) do { _Pragma("unroll") for (int _i = 0; _i < 2; ++_i) \
;         __builtin_amdgcn_global_load_lds((const unsigned*)((const char*)(gbase) + (voff)[_i]), (PG8_LAS unsigned*)(lds + (bufoff) + ldsw + _i * 8192), 16, 0, 0); } while (0)
; #define PG8_LDA(dst, b, h) do { _Pragma("unroll") for (int m = 0; m < 4; ++m) _Pragma("unroll") for (int k = 0; k < 2; ++k) dst[m][k] = *(const PG8_LAS bf16x8*)(lds + PG8_SA(b, h) + aoff + m * 2048 + k * 1024); } while (0)
; #define PG8_LDB(dst, b, h) do { _Pragma("unroll") for (int n = 0; n < 2; ++n) _Pragma("unroll") for (int k = 0; k < 2; ++k) dst[n][k] = *(const PG8_LAS bf16x8*)(lds + PG8_SB(b, h) + boff + n * 2048 + k * 1024); } while (0)
; #define PG8_BAR __builtin_amdgcn_s_barrier()
; template <class Epi, class Sched, bool ALIGN_EPI = false, bool SP2 = false>
; __device__ __forceinline__ void gemm_phase(PG8_LAS unsigned char* lds, const Gemm g, const Sched& S, const Epi& E) {
;     ...
;             const bool last = (t == nt - 2);
;             const char* a1 = cA + (size_t)(t + 1) * kstep;
;             const char* a2 = last ? nA : cA + (size_t)(t + 2) * kstep; const char* b2 = last ? nB : cB + (size_t)(t + 2) * kstep;
;             const char* a3 = a2 + kstep; const char* b3 = b2 + kstep;
;             if (last && has_next) S.a_ready(nxt);
;             if constexpr (SP2) {
;             PG8_LDB(B0, 0, 0); PG8_LDB(B1, 0, 1); PG8_SCHED; PG8_LDA(At, 0, 0); PG8_STAGE(PG8_SA(1, 1), a1 + hstep, voffA);
;             PG8_WAIT_V(8); PG8_WAIT_L(0); PG8_BAR; PG8_MMA(0, 0, At, B0); PG8_MMA(0, 1, At, B1); PG8_BAR; PG8_SCHED;
;             PG8_LDA(At, 0, 1); PG8_STAGE(PG8_SB(0, 0), b2, voffB); PG8_STAGE(PG8_SB(0, 1), b2 + hstep, voffB); PG8_STAGE(PG8_SA(0, 0), a2, voffA);
;             PG8_WAIT_V(8); PG8_WAIT_L(0); PG8_BAR; PG8_MMA(1, 0, At, B0); PG8_MMA(1, 1, At, B1); PG8_BAR; PG8_SCHED;
;             PG8_LDB(B0, 1, 0); PG8_LDB(B1, 1, 1); PG8_SCHED; PG8_LDA(At, 1, 0); PG8_STAGE(PG8_SA(0, 1), a2 + hstep, voffA);
;             PG8_WAIT_V(8); PG8_WAIT_L(0); PG8_BAR; PG8_MMA(0, 0, At, B0); PG8_MMA(0, 1, At, B1); PG8_BAR; PG8_SCHED;
;             PG8_LDA(At, 1, 1); PG8_STAGE(PG8_SB(1, 0), b3, voffB); PG8_STAGE(PG8_SB(1, 1), b3 + hstep, voffB); PG8_STAGE(PG8_SA(1, 0), a3, voffA);
;             PG8_WAIT_V(8); PG8_WAIT_L(0); PG8_BAR; PG8_MMA(1, 0, At, B0); PG8_MMA(1, 1, At, B1); PG8_BAR; PG8_SCHED;
	v_mfma_f32_16x16x32_bf16 v[58:61], v[154:157], v[204:207], v[58:61]
	v_mfma_f32_16x16x32_bf16 v[50:53], v[162:165], v[204:207], v[50:53]
	v_mfma_f32_16x16x32_bf16 v[42:45], v[154:157], v[212:215], v[42:45]
	v_mfma_f32_16x16x32_bf16 v[34:37], v[162:165], v[212:215], v[34:37]
	v_mfma_f32_16x16x32_bf16 v[26:29], v[154:157], v[220:223], v[26:29]
	v_mfma_f32_16x16x32_bf16 v[18:21], v[162:165], v[220:223], v[18:21]
	v_mfma_f32_16x16x32_bf16 v[10:13], v[154:157], v[228:231], v[10:13]
	v_mfma_f32_16x16x32_bf16 v[2:5], v[162:165], v[228:231], v[2:5]
	v_mfma_f32_16x16x32_bf16 v[58:61], v[158:161], v[208:211], v[58:61]
	v_mfma_f32_16x16x32_bf16 v[50:53], v[166:169], v[208:211], v[50:53]
	v_mfma_f32_16x16x32_bf16 v[42:45], v[158:161], v[216:219], v[42:45]
	v_mfma_f32_16x16x32_bf16 v[34:37], v[166:169], v[216:219], v[34:37]
	v_mfma_f32_16x16x32_bf16 v[26:29], v[158:161], v[224:227], v[26:29]
	v_mfma_f32_16x16x32_bf16 v[18:21], v[166:169], v[224:227], v[18:21]
	v_mfma_f32_16x16x32_bf16 v[10:13], v[158:161], v[232:235], v[10:13]
	v_mfma_f32_16x16x32_bf16 v[2:5], v[166:169], v[232:235], v[2:5]
	s_setprio 0
	s_setprio 1
	v_mfma_f32_16x16x32_bf16 v[62:65], v[170:173], v[204:207], v[62:65]
	v_mfma_f32_16x16x32_bf16 v[54:57], v[178:181], v[204:207], v[54:57]
	v_mfma_f32_16x16x32_bf16 v[46:49], v[170:173], v[212:215], v[46:49]
	v_mfma_f32_16x16x32_bf16 v[38:41], v[178:181], v[212:215], v[38:41]
	v_mfma_f32_16x16x32_bf16 v[30:33], v[170:173], v[220:223], v[30:33]
	v_mfma_f32_16x16x32_bf16 v[22:25], v[178:181], v[220:223], v[22:25]
	v_mfma_f32_16x16x32_bf16 v[14:17], v[170:173], v[228:231], v[14:17]
	v_mfma_f32_16x16x32_bf16 v[6:9], v[178:181], v[228:231], v[6:9]
	v_mfma_f32_16x16x32_bf16 v[62:65], v[174:177], v[208:211], v[62:65]
	v_mfma_f32_16x16x32_bf16 v[54:57], v[200:203], v[208:211], v[54:57]
	v_mfma_f32_16x16x32_bf16 v[46:49], v[174:177], v[216:219], v[46:49]
	v_mfma_f32_16x16x32_bf16 v[38:41], v[200:203], v[216:219], v[38:41]
	v_mfma_f32_16x16x32_bf16 v[30:33], v[174:177], v[224:227], v[30:33]
	v_mfma_f32_16x16x32_bf16 v[22:25], v[200:203], v[224:227], v[22:25]
	v_mfma_f32_16x16x32_bf16 v[14:17], v[174:177], v[232:235], v[14:17]
	v_mfma_f32_16x16x32_bf16 v[6:9], v[200:203], v[232:235], v[6:9]
	s_barrier
	s_setprio 0
	s_add_i32 s55, s55, 2
	s_add_u32 s16, s16, 0x100
	s_addc_u32 s17, s17, 0
	s_add_u32 s52, s52, 0x100
	s_addc_u32 s53, s53, 0
.LBB0_368:
	s_add_u32 s18, s16, 0xfffc0080
	s_addc_u32 s19, s17, -1
	s_add_i32 s56, 0, 0x10000
	s_cmp_eq_u32 s55, 12
	s_cselect_b32 s21, s11, s19
	s_cselect_b32 s20, s50, s18
	v_add_u32_e32 v140, s56, v143
	s_cselect_b32 s19, s9, s53
	s_cselect_b32 s18, s51, s52
	s_add_i32 s58, 0, 0x14000
	ds_read_b128 v[154:157], v140
	ds_read_b128 v[158:161], v140 offset:1024
	ds_read_b128 v[162:165], v140 offset:2048
	ds_read_b128 v[166:169], v140 offset:3072
	v_add_u32_e32 v140, s58, v143
	ds_read_b128 v[170:173], v140
	ds_read_b128 v[174:177], v140 offset:1024
	ds_read_b128 v[178:181], v140 offset:2048
	ds_read_b128 v[200:203], v140 offset:3072
	v_lshl_add_u64 v[140:141], s[16:17], 0, v[136:137]
	s_add_i32 m0, s25, 0xc000
	ds_read_b128 v[204:207], v145
	ds_read_b128 v[208:211], v145 offset:1024
	ds_read_b128 v[212:215], v145 offset:2048
	ds_read_b128 v[216:219], v145 offset:3072
	ds_read_b128 v[220:223], v145 offset:4096
	ds_read_b128 v[224:227], v145 offset:5120
	ds_read_b128 v[228:231], v145 offset:6144
	ds_read_b128 v[232:235], v145 offset:7168
	global_load_lds_dwordx4 v[140:141], off
	v_lshl_add_u64 v[140:141], s[16:17], 0, v[138:139]
	s_add_i32 m0, s25, 0xe000
	s_nop 0
	global_load_lds_dwordx4 v[140:141], off
	s_waitcnt vmcnt(8)
	s_waitcnt lgkmcnt(0)
	s_setprio 1
	s_barrier
	v_mfma_f32_16x16x32_bf16 v[122:125], v[154:157], v[204:207], v[122:125]
	v_mfma_f32_16x16x32_bf16 v[114:117], v[162:165], v[204:207], v[114:117]
	v_mfma_f32_16x16x32_bf16 v[106:109], v[154:157], v[212:215], v[106:109]
	v_mfma_f32_16x16x32_bf16 v[98:101], v[162:165], v[212:215], v[98:101]
	v_mfma_f32_16x16x32_bf16 v[90:93], v[154:157], v[220:223], v[90:93]
	v_mfma_f32_16x16x32_bf16 v[82:85], v[162:165], v[220:223], v[82:85]
	v_mfma_f32_16x16x32_bf16 v[74:77], v[154:157], v[228:231], v[74:77]
	v_mfma_f32_16x16x32_bf16 v[66:69], v[162:165], v[228:231], v[66:69]
	v_mfma_f32_16x16x32_bf16 v[122:125], v[158:161], v[208:211], v[122:125]
	v_mfma_f32_16x16x32_bf16 v[114:117], v[166:169], v[208:211], v[114:117]
	v_mfma_f32_16x16x32_bf16 v[106:109], v[158:161], v[216:219], v[106:109]
	v_mfma_f32_16x16x32_bf16 v[98:101], v[166:169], v[216:219], v[98:101]
	v_mfma_f32_16x16x32_bf16 v[90:93], v[158:161], v[224:227], v[90:93]
	v_mfma_f32_16x16x32_bf16 v[82:85], v[166:169], v[224:227], v[82:85]
	v_mfma_f32_16x16x32_bf16 v[74:77], v[158:161], v[232:235], v[74:77]
	v_mfma_f32_16x16x32_bf16 v[66:69], v[166:169], v[232:235], v[66:69]
	s_setprio 0
	s_setprio 1
	v_mfma_f32_16x16x32_bf16 v[126:129], v[170:173], v[204:207], v[126:129]
	v_mfma_f32_16x16x32_bf16 v[118:121], v[178:181], v[204:207], v[118:121]
	v_mfma_f32_16x16x32_bf16 v[110:113], v[170:173], v[212:215], v[110:113]
	v_mfma_f32_16x16x32_bf16 v[102:105], v[178:181], v[212:215], v[102:105]
	v_mfma_f32_16x16x32_bf16 v[94:97], v[170:173], v[220:223], v[94:97]
	v_mfma_f32_16x16x32_bf16 v[86:89], v[178:181], v[220:223], v[86:89]
	v_mfma_f32_16x16x32_bf16 v[78:81], v[170:173], v[228:231], v[78:81]
	v_mfma_f32_16x16x32_bf16 v[70:73], v[178:181], v[228:231], v[70:73]
	v_mfma_f32_16x16x32_bf16 v[126:129], v[174:177], v[208:211], v[126:129]
	v_mfma_f32_16x16x32_bf16 v[118:121], v[200:203], v[208:211], v[118:121]
	v_mfma_f32_16x16x32_bf16 v[110:113], v[174:177], v[216:219], v[110:113]
	v_mfma_f32_16x16x32_bf16 v[102:105], v[200:203], v[216:219], v[102:105]
	v_mfma_f32_16x16x32_bf16 v[94:97], v[174:177], v[224:227], v[94:97]
	v_mfma_f32_16x16x32_bf16 v[86:89], v[200:203], v[224:227], v[86:89]
	v_mfma_f32_16x16x32_bf16 v[78:81], v[174:177], v[232:235], v[78:81]
	v_mfma_f32_16x16x32_bf16 v[70:73], v[200:203], v[232:235], v[70:73]
	s_barrier
; #define PG8_STAGE(bufoff, gbase, voff) do { _Pragma("unroll") for (int _i = 0; _i < 2; ++_i) \
;         __builtin_amdgcn_global_load_lds((const unsigned*)((const char*)(gbase) + (voff)[_i]), (PG8_LAS unsigned*)(lds + (bufoff) + ldsw + _i * 8192), 16, 0, 0); } while (0)
; #define PG8_LDA(dst, b, h) do { _Pragma("unroll") for (int m = 0; m < 4; ++m) _Pragma("unroll") for (int k = 0; k < 2; ++k) dst[m][k] = *(const PG8_LAS bf16x8*)(lds + PG8_SA(b, h) + aoff + m * 2048 + k * 1024); } while (0)
; #define PG8_LDB(dst, b, h) do { _Pragma("unroll") for (int n = 0; n < 2; ++n) _Pragma("unroll") for (int k = 0; k < 2; ++k) dst[n][k] = *(const PG8_LAS bf16x8*)(lds + PG8_SB(b, h) + boff + n * 2048 + k * 1024); } while (0)
; #define PG8_MMA(ai, bj, At, Bt) do { __builtin_amdgcn_s_setprio(1); _Pragma("unroll") for (int m = 0; m < 4; ++m) _Pragma("unroll") for (int n = 0; n < 2; ++n) _Pragma("unroll") for (int k = 0; k < 2; ++k) \
;         acc[ai][bj][m][n] = __builtin_amdgcn_mfma_f32_16x16x32_bf16(Bt[n][k], At[m][k], acc[ai][bj][m][n], 0, 0, 0); __builtin_amdgcn_s_setprio(0); } while (0)
; #define PG8_WAIT_V(n) asm volatile("s_waitcnt vmcnt(" #n ")" ::: "memory")
; #define PG8_WAIT_L(n) asm volatile("s_waitcnt lgkmcnt(" #n ")" ::: "memory")
; #define PG8_BAR __builtin_amdgcn_s_barrier()
; #define PG8_SCHED __builtin_amdgcn_sched_barrier(0)
; template <class Epi, class Sched, bool ALIGN_EPI = false, bool SP2 = false>
; __device__ __forceinline__ void gemm_phase(PG8_LAS unsigned char* lds, const Gemm g, const Sched& S, const Epi& E) {
;     ...
;             PG8_LDA(At, 0, 1); PG8_STAGE(PG8_SB(0, 0), b2, voffB); PG8_STAGE(PG8_SB(0, 1), b2 + hstep, voffB); PG8_STAGE(PG8_SA(0, 0), a2, voffA);
;             PG8_WAIT_V(8); PG8_WAIT_L(0); PG8_BAR; PG8_MMA(1, 0, At, B0); PG8_MMA(1, 1, At, B1); PG8_BAR; PG8_SCHED;
;             PG8_LDB(B0, 1, 0); PG8_LDB(B1, 1, 1); PG8_SCHED; PG8_LDA(At, 1, 0); PG8_STAGE(PG8_SA(0, 1), a2 + hstep, voffA);
;             PG8_WAIT_V(8); PG8_WAIT_L(0); PG8_BAR; PG8_MMA(0, 0, At, B0); PG8_MMA(0, 1, At, B1); PG8_BAR; PG8_SCHED;
	s_setprio 0
	s_add_i32 s56, s56, s24
	v_lshl_add_u64 v[140:141], s[18:19], 0, v[0:1]
	s_mov_b32 m0, s56
	ds_read_b128 v[204:207], v145 offset:16384
	ds_read_b128 v[208:211], v145 offset:17408
	ds_read_b128 v[212:215], v145 offset:18432
	ds_read_b128 v[216:219], v145 offset:19456
	ds_read_b128 v[220:223], v145 offset:20480
	ds_read_b128 v[224:227], v145 offset:21504
	ds_read_b128 v[228:231], v145 offset:22528
	ds_read_b128 v[232:235], v145 offset:23552
	global_load_lds_dwordx4 v[140:141], off
	s_add_i32 m0, s56, 0x2000
	s_add_u32 s56, s18, 0x40000
	v_lshl_add_u64 v[146:147], s[18:19], 0, v[130:131]
	s_addc_u32 s57, s19, 0
	s_add_i32 s58, s58, s24
	global_load_lds_dwordx4 v[146:147], off
	v_lshl_add_u64 v[148:149], s[56:57], 0, v[0:1]
	s_mov_b32 m0, s58
	v_lshl_add_u64 v[236:237], s[20:21], 0, v[132:133]
	global_load_lds_dwordx4 v[148:149], off
	v_lshl_add_u64 v[148:149], s[56:57], 0, v[130:131]
	s_add_i32 m0, s58, 0x2000
	s_nop 0
	global_load_lds_dwordx4 v[148:149], off
	v_lshl_add_u64 v[148:149], s[20:21], 0, v[134:135]
	s_mov_b32 m0, s25
	s_nop 0
	global_load_lds_dwordx4 v[148:149], off
	s_mov_b32 m0, s26
	s_nop 0
	global_load_lds_dwordx4 v[236:237], off
	s_waitcnt vmcnt(8)
	s_waitcnt lgkmcnt(0)
	s_setprio 1
	s_barrier
	v_mfma_f32_16x16x32_bf16 v[58:61], v[154:157], v[204:207], v[58:61]
	v_mfma_f32_16x16x32_bf16 v[50:53], v[162:165], v[204:207], v[50:53]
	v_mfma_f32_16x16x32_bf16 v[42:45], v[154:157], v[212:215], v[42:45]
	v_mfma_f32_16x16x32_bf16 v[34:37], v[162:165], v[212:215], v[34:37]
	v_mfma_f32_16x16x32_bf16 v[26:29], v[154:157], v[220:223], v[26:29]
	v_mfma_f32_16x16x32_bf16 v[18:21], v[162:165], v[220:223], v[18:21]
	v_mfma_f32_16x16x32_bf16 v[10:13], v[154:157], v[228:231], v[10:13]
	v_mfma_f32_16x16x32_bf16 v[2:5], v[162:165], v[228:231], v[2:5]
	v_mfma_f32_16x16x32_bf16 v[58:61], v[158:161], v[208:211], v[58:61]
	v_mfma_f32_16x16x32_bf16 v[50:53], v[166:169], v[208:211], v[50:53]
	v_mfma_f32_16x16x32_bf16 v[42:45], v[158:161], v[216:219], v[42:45]
	v_mfma_f32_16x16x32_bf16 v[34:37], v[166:169], v[216:219], v[34:37]
	v_mfma_f32_16x16x32_bf16 v[26:29], v[158:161], v[224:227], v[26:29]
	v_mfma_f32_16x16x32_bf16 v[18:21], v[166:169], v[224:227], v[18:21]
	v_mfma_f32_16x16x32_bf16 v[10:13], v[158:161], v[232:235], v[10:13]
	v_mfma_f32_16x16x32_bf16 v[2:5], v[166:169], v[232:235], v[2:5]
	s_setprio 0
	s_setprio 1
	v_mfma_f32_16x16x32_bf16 v[62:65], v[170:173], v[204:207], v[62:65]
	v_mfma_f32_16x16x32_bf16 v[54:57], v[178:181], v[204:207], v[54:57]
	v_mfma_f32_16x16x32_bf16 v[46:49], v[170:173], v[212:215], v[46:49]
	v_mfma_f32_16x16x32_bf16 v[38:41], v[178:181], v[212:215], v[38:41]
	v_mfma_f32_16x16x32_bf16 v[30:33], v[170:173], v[220:223], v[30:33]
	v_mfma_f32_16x16x32_bf16 v[22:25], v[178:181], v[220:223], v[22:25]
	v_mfma_f32_16x16x32_bf16 v[14:17], v[170:173], v[228:231], v[14:17]
	v_mfma_f32_16x16x32_bf16 v[6:9], v[178:181], v[228:231], v[6:9]
	v_mfma_f32_16x16x32_bf16 v[62:65], v[174:177], v[208:211], v[62:65]
	v_mfma_f32_16x16x32_bf16 v[54:57], v[200:203], v[208:211], v[54:57]
	v_mfma_f32_16x16x32_bf16 v[46:49], v[174:177], v[216:219], v[46:49]
	v_mfma_f32_16x16x32_bf16 v[38:41], v[200:203], v[216:219], v[38:41]
	v_mfma_f32_16x16x32_bf16 v[30:33], v[174:177], v[224:227], v[30:33]
	v_mfma_f32_16x16x32_bf16 v[22:25], v[200:203], v[224:227], v[22:25]
	v_mfma_f32_16x16x32_bf16 v[14:17], v[174:177], v[232:235], v[14:17]
	v_mfma_f32_16x16x32_bf16 v[6:9], v[200:203], v[232:235], v[6:9]
	s_barrier
	s_setprio 0
	s_add_i32 s56, 0, 0x18000
	s_add_i32 s57, 0, 0x1c000
	v_add_u32_e32 v166, s56, v143
	v_add_u32_e32 v200, s57, v143
	ds_read_b128 v[154:157], v166
	ds_read_b128 v[158:161], v166 offset:1024
	ds_read_b128 v[162:165], v166 offset:2048
	ds_read_b128 v[166:169], v166 offset:3072
	ds_read_b128 v[170:173], v200
	ds_read_b128 v[174:177], v200 offset:1024
	ds_read_b128 v[178:181], v200 offset:2048
	ds_read_b128 v[200:203], v200 offset:3072
	s_add_u32 s20, s20, 0x40000
	s_addc_u32 s21, s21, 0
	s_mov_b32 m0, s27
	v_lshl_add_u64 v[238:239], s[20:21], 0, v[134:135]
	ds_read_b128 v[204:207], v145 offset:32768
	ds_read_b128 v[208:211], v145 offset:33792
	ds_read_b128 v[212:215], v145 offset:34816
	ds_read_b128 v[216:219], v145 offset:35840
	ds_read_b128 v[220:223], v145 offset:36864
	ds_read_b128 v[224:227], v145 offset:37888
	ds_read_b128 v[228:231], v145 offset:38912
	ds_read_b128 v[232:235], v145 offset:39936
	global_load_lds_dwordx4 v[238:239], off
	v_lshl_add_u64 v[238:239], s[20:21], 0, v[132:133]
	s_mov_b32 m0, s28
	s_nop 0
	global_load_lds_dwordx4 v[238:239], off
	s_waitcnt vmcnt(8)
	s_waitcnt lgkmcnt(0)
	s_setprio 1
	s_barrier
; #define PG8_STAGE(bufoff, gbase, voff) do { _Pragma("unroll") for (int _i = 0; _i < 2; ++_i) \
;         __builtin_amdgcn_global_load_lds((const unsigned*)((const char*)(gbase) + (voff)[_i]), (PG8_LAS unsigned*)(lds + (bufoff) + ldsw + _i * 8192), 16, 0, 0); } while (0)
; #define PG8_LDA(dst, b, h) do { _Pragma("unroll") for (int m = 0; m < 4; ++m) _Pragma("unroll") for (int k = 0; k < 2; ++k) dst[m][k] = *(const PG8_LAS bf16x8*)(lds + PG8_SA(b, h) + aoff + m * 2048 + k * 1024); } while (0)
; #define PG8_MMA(ai, bj, At, Bt) do { __builtin_amdgcn_s_setprio(1); _Pragma("unroll") for (int m = 0; m < 4; ++m) _Pragma("unroll") for (int n = 0; n < 2; ++n) _Pragma("unroll") for (int k = 0; k < 2; ++k) \
;         acc[ai][bj][m][n] = __builtin_amdgcn_mfma_f32_16x16x32_bf16(Bt[n][k], At[m][k], acc[ai][bj][m][n], 0, 0, 0); __builtin_amdgcn_s_setprio(0); } while (0)
; #define PG8_WAIT_V(n) asm volatile("s_waitcnt vmcnt(" #n ")" ::: "memory")
; #define PG8_WAIT_L(n) asm volatile("s_waitcnt lgkmcnt(" #n ")" ::: "memory")
; #define PG8_BAR __builtin_amdgcn_s_barrier()
; #define PG8_SCHED __builtin_amdgcn_sched_barrier(0)
; template <class Epi, class Sched, bool ALIGN_EPI = false, bool SP2 = false>
; __device__ __forceinline__ void gemm_phase(PG8_LAS unsigned char* lds, const Gemm g, const Sched& S, const Epi& E) {
;     ...
;             PG8_WAIT_V(8); PG8_WAIT_L(0); PG8_BAR; PG8_MMA(0, 0, At, B0); PG8_MMA(0, 1, At, B1); PG8_BAR; PG8_SCHED;
;             PG8_LDA(At, 1, 1); PG8_STAGE(PG8_SB(1, 0), b3, voffB); PG8_STAGE(PG8_SB(1, 1), b3 + hstep, voffB); PG8_STAGE(PG8_SA(1, 0), a3, voffA);
;             PG8_WAIT_V(8); PG8_WAIT_L(0); PG8_BAR; PG8_MMA(1, 0, At, B0); PG8_MMA(1, 1, At, B1); PG8_BAR; PG8_SCHED;
;     ...
;         if constexpr (ALIGN_EPI) { if (wr == 0) PG8_BAR; }
	v_mfma_f32_16x16x32_bf16 v[122:125], v[154:157], v[204:207], v[122:125]
	v_mfma_f32_16x16x32_bf16 v[114:117], v[162:165], v[204:207], v[114:117]
	v_mfma_f32_16x16x32_bf16 v[106:109], v[154:157], v[212:215], v[106:109]
	v_mfma_f32_16x16x32_bf16 v[98:101], v[162:165], v[212:215], v[98:101]
	v_mfma_f32_16x16x32_bf16 v[90:93], v[154:157], v[220:223], v[90:93]
	v_mfma_f32_16x16x32_bf16 v[82:85], v[162:165], v[220:223], v[82:85]
	v_mfma_f32_16x16x32_bf16 v[74:77], v[154:157], v[228:231], v[74:77]
	v_mfma_f32_16x16x32_bf16 v[66:69], v[162:165], v[228:231], v[66:69]
	v_mfma_f32_16x16x32_bf16 v[122:125], v[158:161], v[208:211], v[122:125]
	v_mfma_f32_16x16x32_bf16 v[114:117], v[166:169], v[208:211], v[114:117]
	v_mfma_f32_16x16x32_bf16 v[106:109], v[158:161], v[216:219], v[106:109]
	v_mfma_f32_16x16x32_bf16 v[98:101], v[166:169], v[216:219], v[98:101]
	v_mfma_f32_16x16x32_bf16 v[90:93], v[158:161], v[224:227], v[90:93]
	v_mfma_f32_16x16x32_bf16 v[82:85], v[166:169], v[224:227], v[82:85]
	v_mfma_f32_16x16x32_bf16 v[74:77], v[158:161], v[232:235], v[74:77]
	v_mfma_f32_16x16x32_bf16 v[66:69], v[166:169], v[232:235], v[66:69]
	s_setprio 0
	s_setprio 1
	v_mfma_f32_16x16x32_bf16 v[126:129], v[170:173], v[204:207], v[126:129]
	v_mfma_f32_16x16x32_bf16 v[118:121], v[178:181], v[204:207], v[118:121]
	v_mfma_f32_16x16x32_bf16 v[110:113], v[170:173], v[212:215], v[110:113]
	v_mfma_f32_16x16x32_bf16 v[102:105], v[178:181], v[212:215], v[102:105]
	v_mfma_f32_16x16x32_bf16 v[94:97], v[170:173], v[220:223], v[94:97]
	v_mfma_f32_16x16x32_bf16 v[86:89], v[178:181], v[220:223], v[86:89]
	v_mfma_f32_16x16x32_bf16 v[78:81], v[170:173], v[228:231], v[78:81]
	v_mfma_f32_16x16x32_bf16 v[70:73], v[178:181], v[228:231], v[70:73]
	v_mfma_f32_16x16x32_bf16 v[126:129], v[174:177], v[208:211], v[126:129]
	v_mfma_f32_16x16x32_bf16 v[118:121], v[200:203], v[208:211], v[118:121]
	v_mfma_f32_16x16x32_bf16 v[110:113], v[174:177], v[216:219], v[110:113]
	v_mfma_f32_16x16x32_bf16 v[102:105], v[200:203], v[216:219], v[102:105]
	v_mfma_f32_16x16x32_bf16 v[94:97], v[174:177], v[224:227], v[94:97]
	v_mfma_f32_16x16x32_bf16 v[86:89], v[200:203], v[224:227], v[86:89]
	v_mfma_f32_16x16x32_bf16 v[78:81], v[174:177], v[232:235], v[78:81]
	v_mfma_f32_16x16x32_bf16 v[70:73], v[200:203], v[232:235], v[70:73]
	s_barrier
	s_setprio 0
	s_add_i32 s20, s56, s24
	v_lshl_add_u64 v[140:141], v[140:141], 0, s[38:39]
	s_mov_b32 m0, s20
	ds_read_b128 v[204:207], v145 offset:49152
	ds_read_b128 v[208:211], v145 offset:50176
	ds_read_b128 v[212:215], v145 offset:51200
	ds_read_b128 v[216:219], v145 offset:52224
	ds_read_b128 v[220:223], v145 offset:53248
	ds_read_b128 v[224:227], v145 offset:54272
	ds_read_b128 v[228:231], v145 offset:55296
	ds_read_b128 v[232:235], v145 offset:56320
	global_load_lds_dwordx4 v[140:141], off
	s_add_i32 m0, s20, 0x2000
	s_add_u32 s18, s18, 0x40080
	v_lshl_add_u64 v[140:141], v[146:147], 0, s[38:39]
	s_addc_u32 s19, s19, 0
	s_add_i32 s20, s57, s24
	global_load_lds_dwordx4 v[140:141], off
	v_lshl_add_u64 v[140:141], s[18:19], 0, v[0:1]
	s_mov_b32 m0, s20
	s_nop 0
	global_load_lds_dwordx4 v[140:141], off
	v_lshl_add_u64 v[140:141], s[18:19], 0, v[130:131]
	s_add_i32 m0, s20, 0x2000
	s_nop 0
	global_load_lds_dwordx4 v[140:141], off
	v_lshl_add_u64 v[140:141], v[148:149], 0, s[38:39]
	s_mov_b32 m0, s29
	s_nop 0
	global_load_lds_dwordx4 v[140:141], off
	v_lshl_add_u64 v[140:141], v[236:237], 0, s[38:39]
	s_mov_b32 m0, s30
	s_nop 0
	global_load_lds_dwordx4 v[140:141], off
	s_waitcnt vmcnt(8)
	s_waitcnt lgkmcnt(0)
	s_setprio 1
	s_barrier
	v_mfma_f32_16x16x32_bf16 v[58:61], v[154:157], v[204:207], v[58:61]
	v_mfma_f32_16x16x32_bf16 v[50:53], v[162:165], v[204:207], v[50:53]
	v_mfma_f32_16x16x32_bf16 v[42:45], v[154:157], v[212:215], v[42:45]
	v_mfma_f32_16x16x32_bf16 v[34:37], v[162:165], v[212:215], v[34:37]
	v_mfma_f32_16x16x32_bf16 v[26:29], v[154:157], v[220:223], v[26:29]
	v_mfma_f32_16x16x32_bf16 v[18:21], v[162:165], v[220:223], v[18:21]
	v_mfma_f32_16x16x32_bf16 v[10:13], v[154:157], v[228:231], v[10:13]
	v_mfma_f32_16x16x32_bf16 v[2:5], v[162:165], v[228:231], v[2:5]
	v_mfma_f32_16x16x32_bf16 v[58:61], v[158:161], v[208:211], v[58:61]
	v_mfma_f32_16x16x32_bf16 v[50:53], v[166:169], v[208:211], v[50:53]
	v_mfma_f32_16x16x32_bf16 v[42:45], v[158:161], v[216:219], v[42:45]
	v_mfma_f32_16x16x32_bf16 v[34:37], v[166:169], v[216:219], v[34:37]
	v_mfma_f32_16x16x32_bf16 v[26:29], v[158:161], v[224:227], v[26:29]
	v_mfma_f32_16x16x32_bf16 v[18:21], v[166:169], v[224:227], v[18:21]
	v_mfma_f32_16x16x32_bf16 v[10:13], v[158:161], v[232:235], v[10:13]
	v_mfma_f32_16x16x32_bf16 v[2:5], v[166:169], v[232:235], v[2:5]
	s_setprio 0
	s_setprio 1
	v_mfma_f32_16x16x32_bf16 v[62:65], v[170:173], v[204:207], v[62:65]
	v_mfma_f32_16x16x32_bf16 v[54:57], v[178:181], v[204:207], v[54:57]
	v_mfma_f32_16x16x32_bf16 v[46:49], v[170:173], v[212:215], v[46:49]
	v_mfma_f32_16x16x32_bf16 v[38:41], v[178:181], v[212:215], v[38:41]
	v_mfma_f32_16x16x32_bf16 v[30:33], v[170:173], v[220:223], v[30:33]
	v_mfma_f32_16x16x32_bf16 v[22:25], v[178:181], v[220:223], v[22:25]
	v_mfma_f32_16x16x32_bf16 v[14:17], v[170:173], v[228:231], v[14:17]
	v_mfma_f32_16x16x32_bf16 v[6:9], v[178:181], v[228:231], v[6:9]
	v_mfma_f32_16x16x32_bf16 v[62:65], v[174:177], v[208:211], v[62:65]
	v_mfma_f32_16x16x32_bf16 v[54:57], v[200:203], v[208:211], v[54:57]
	v_mfma_f32_16x16x32_bf16 v[46:49], v[174:177], v[216:219], v[46:49]
	v_mfma_f32_16x16x32_bf16 v[38:41], v[200:203], v[216:219], v[38:41]
	v_mfma_f32_16x16x32_bf16 v[30:33], v[174:177], v[224:227], v[30:33]
	v_mfma_f32_16x16x32_bf16 v[22:25], v[200:203], v[224:227], v[22:25]
	v_mfma_f32_16x16x32_bf16 v[14:17], v[174:177], v[232:235], v[14:17]
	v_mfma_f32_16x16x32_bf16 v[6:9], v[200:203], v[232:235], v[6:9]
	s_barrier
	s_setprio 0
	s_add_i32 s55, s55, 2
	s_add_u32 s16, s16, 0x100
	s_addc_u32 s17, s17, 0
	s_add_u32 s52, s52, 0x100
	s_addc_u32 s53, s53, 0
	s_cmp_gt_u32 s55, 13
	s_cbranch_scc0 .LBB0_368
	s_and_b64 vcc, exec, s[6:7]
	s_cbranch_vccz .LBB0_371
	s_barrier

; #define PG8_STAGE(bufoff, gbase, voff) do { _Pragma("unroll") for (int _i = 0; _i < 2; ++_i) \
;         __builtin_amdgcn_global_load_lds((const unsigned*)((const char*)(gbase) + (voff)[_i]), (PG8_LAS unsigned*)(lds + (bufoff) + ldsw + _i * 8192), 16, 0, 0); } while (0)
; #define PG8_LDA(dst, b, h) do { _Pragma("unroll") for (int m = 0; m < 4; ++m) _Pragma("unroll") for (int k = 0; k < 2; ++k) dst[m][k] = *(const PG8_LAS bf16x8*)(lds + PG8_SA(b, h) + aoff + m * 2048 + k * 1024); } while (0)
; #define PG8_LDB(dst, b, h) do { _Pragma("unroll") for (int n = 0; n < 2; ++n) _Pragma("unroll") for (int k = 0; k < 2; ++k) dst[n][k] = *(const PG8_LAS bf16x8*)(lds + PG8_SB(b, h) + boff + n * 2048 + k * 1024); } while (0)
; #define PG8_WAIT_V(n) asm volatile("s_waitcnt vmcnt(" #n ")" ::: "memory")
; #define PG8_WAIT_L(n) asm volatile("s_waitcnt lgkmcnt(" #n ")" ::: "memory")
; #define PG8_BAR __builtin_amdgcn_s_barrier()
; #define PG8_SCHED __builtin_amdgcn_sched_barrier(0)
; template <class Epi, class Sched, bool ALIGN_EPI = false, bool SP2 = false>
; __device__ __forceinline__ void gemm_phase(PG8_LAS unsigned char* lds, const Gemm g, const Sched& S, const Epi& E) {
;     ...
;         const char* nA = has_next ? (const char*)g.A + (size_t)nxt.pm * tstep : cA; const char* nB = has_next ? (const char*)g.Bt + (size_t)nxt.pn * tstep : cB;
;         for (int t = 0; t < nt; t += 2) {
;             const bool last = (t == nt - 2);
;             const char* a1 = cA + (size_t)(t + 1) * kstep;
;             const char* a2 = last ? nA : cA + (size_t)(t + 2) * kstep; const char* b2 = last ? nB : cB + (size_t)(t + 2) * kstep;
;             const char* a3 = a2 + kstep; const char* b3 = b2 + kstep;
;             if (last && has_next) S.a_ready(nxt);
;             if constexpr (SP2) {
;             PG8_LDB(B0, 0, 0); PG8_LDB(B1, 0, 1); PG8_SCHED; PG8_LDA(At, 0, 0); PG8_STAGE(PG8_SA(1, 1), a1 + hstep, voffA);
;             PG8_WAIT_V(8); PG8_WAIT_L(0); PG8_BAR; PG8_MMA(0, 0, At, B0); PG8_MMA(0, 1, At, B1); PG8_BAR; PG8_SCHED;
;             PG8_LDA(At, 0, 1); PG8_STAGE(PG8_SB(0, 0), b2, voffB); PG8_STAGE(PG8_SB(0, 1), b2 + hstep, voffB); PG8_STAGE(PG8_SA(0, 0), a2, voffA);
;             PG8_WAIT_V(8); PG8_WAIT_L(0); PG8_BAR; PG8_MMA(1, 0, At, B0); PG8_MMA(1, 1, At, B1); PG8_BAR; PG8_SCHED;
.LBB0_431:
	s_ashr_i32 s11, s10, 31
	s_lshl_b64 s[12:13], s[10:11], 21
	s_add_u32 s12, s92, s12
	s_addc_u32 s13, s93, s13
	s_and_b64 s[14:15], s[4:5], exec
	s_cselect_b32 s11, s13, s17
	s_cselect_b32 s51, s12, s16
	s_ashr_i32 s9, s8, 31
	s_lshl_b64 s[14:15], s[8:9], 21
	s_add_u32 s14, s22, s14
	s_addc_u32 s15, s23, s15
	s_and_b64 s[20:21], s[4:5], exec
	s_cselect_b32 s9, s15, s19
	s_cselect_b32 s52, s14, s18
	s_add_u32 s16, s16, 0x100080
	s_addc_u32 s17, s17, 0
	s_add_u32 s53, s18, 0x100
	s_addc_u32 s54, s19, 0
	s_mov_b32 s55, -2
	s_add_u32 s18, s16, 0xfff00080
	s_addc_u32 s19, s17, -1
	s_add_i32 s56, 0, 0x10000
	s_cmp_eq_u32 s55, 60
	s_cselect_b32 s21, s11, s19
	s_cselect_b32 s20, s51, s18
	s_cselect_b32 s19, s9, s54
	s_cselect_b32 s18, s52, s53
	s_add_i32 s58, 0, 0x14000
	v_lshl_add_u64 v[146:147], s[16:17], 0, v[160:161]
	s_add_i32 m0, s25, 0xc000
	global_load_lds_dwordx4 v[146:147], off
	v_lshl_add_u64 v[146:147], s[16:17], 0, v[162:163]
	s_add_i32 m0, s25, 0xe000
	s_nop 0
	global_load_lds_dwordx4 v[146:147], off
	s_waitcnt vmcnt(20)
	s_waitcnt lgkmcnt(0)
	s_setprio 1
	s_barrier
	v_mfma_f32_16x16x32_bf16 v[126:129], v[130:133], v[204:207], 0
	v_mfma_f32_16x16x32_bf16 v[122:125], v[138:141], v[204:207], 0
	v_mfma_f32_16x16x32_bf16 v[118:121], v[130:133], v[212:215], 0
	v_mfma_f32_16x16x32_bf16 v[114:117], v[138:141], v[212:215], 0
	v_mfma_f32_16x16x32_bf16 v[110:113], v[130:133], v[220:223], 0
	v_mfma_f32_16x16x32_bf16 v[106:109], v[138:141], v[220:223], 0
	v_mfma_f32_16x16x32_bf16 v[102:105], v[130:133], v[228:231], 0
	v_mfma_f32_16x16x32_bf16 v[98:101], v[138:141], v[228:231], 0
	v_mfma_f32_16x16x32_bf16 v[126:129], v[134:137], v[208:211], v[126:129]
	v_mfma_f32_16x16x32_bf16 v[122:125], v[142:145], v[208:211], v[122:125]
	v_mfma_f32_16x16x32_bf16 v[118:121], v[134:137], v[216:219], v[118:121]
	v_mfma_f32_16x16x32_bf16 v[114:117], v[142:145], v[216:219], v[114:117]
	v_mfma_f32_16x16x32_bf16 v[110:113], v[134:137], v[224:227], v[110:113]
	v_mfma_f32_16x16x32_bf16 v[106:109], v[142:145], v[224:227], v[106:109]
	v_mfma_f32_16x16x32_bf16 v[102:105], v[134:137], v[232:235], v[102:105]
	v_mfma_f32_16x16x32_bf16 v[98:101], v[142:145], v[232:235], v[98:101]
	s_setprio 0
	s_setprio 1
	v_mfma_f32_16x16x32_bf16 v[62:65], v[164:167], v[204:207], 0
	v_mfma_f32_16x16x32_bf16 v[58:61], v[172:175], v[204:207], 0
	v_mfma_f32_16x16x32_bf16 v[54:57], v[164:167], v[212:215], 0
	v_mfma_f32_16x16x32_bf16 v[50:53], v[172:175], v[212:215], 0
	v_mfma_f32_16x16x32_bf16 v[46:49], v[164:167], v[220:223], 0
	v_mfma_f32_16x16x32_bf16 v[42:45], v[172:175], v[220:223], 0
	v_mfma_f32_16x16x32_bf16 v[38:41], v[164:167], v[228:231], 0
	v_mfma_f32_16x16x32_bf16 v[34:37], v[172:175], v[228:231], 0
	v_mfma_f32_16x16x32_bf16 v[62:65], v[168:171], v[208:211], v[62:65]
	v_mfma_f32_16x16x32_bf16 v[58:61], v[176:179], v[208:211], v[58:61]
	v_mfma_f32_16x16x32_bf16 v[54:57], v[168:171], v[216:219], v[54:57]
	v_mfma_f32_16x16x32_bf16 v[50:53], v[176:179], v[216:219], v[50:53]
	v_mfma_f32_16x16x32_bf16 v[46:49], v[168:171], v[224:227], v[46:49]
	v_mfma_f32_16x16x32_bf16 v[42:45], v[176:179], v[224:227], v[42:45]
	v_mfma_f32_16x16x32_bf16 v[38:41], v[168:171], v[232:235], v[38:41]
	v_mfma_f32_16x16x32_bf16 v[34:37], v[176:179], v[232:235], v[34:37]
	s_barrier
	s_setprio 0
	s_add_i32 s56, s56, s24
	v_lshl_add_u64 v[146:147], s[18:19], 0, v[0:1]
	s_mov_b32 m0, s56
	ds_read_b128 v[204:207], v203 offset:16384
	ds_read_b128 v[208:211], v203 offset:17408
	ds_read_b128 v[212:215], v203 offset:18432
	ds_read_b128 v[216:219], v203 offset:19456
	ds_read_b128 v[220:223], v203 offset:20480
	ds_read_b128 v[224:227], v203 offset:21504
	ds_read_b128 v[228:231], v203 offset:22528
	ds_read_b128 v[232:235], v203 offset:23552
	global_load_lds_dwordx4 v[146:147], off
	s_add_i32 m0, s56, 0x2000
	s_add_u32 s56, s18, 0x100000
	v_lshl_add_u64 v[148:149], s[18:19], 0, v[154:155]
	s_addc_u32 s57, s19, 0
	s_add_i32 s58, s58, s24
	global_load_lds_dwordx4 v[148:149], off
	v_lshl_add_u64 v[180:181], s[56:57], 0, v[0:1]
	s_mov_b32 m0, s58
	v_lshl_add_u64 v[236:237], s[20:21], 0, v[156:157]
	global_load_lds_dwordx4 v[180:181], off
	v_lshl_add_u64 v[180:181], s[56:57], 0, v[154:155]
	s_add_i32 m0, s58, 0x2000
	s_nop 0
	global_load_lds_dwordx4 v[180:181], off
	v_lshl_add_u64 v[180:181], s[20:21], 0, v[158:159]
	s_mov_b32 m0, s25
	s_nop 0
	global_load_lds_dwordx4 v[180:181], off
	s_mov_b32 m0, s26
	s_nop 0
	global_load_lds_dwordx4 v[236:237], off
	s_waitcnt vmcnt(20)
	s_waitcnt lgkmcnt(0)
	s_setprio 1
	s_barrier
	v_mfma_f32_16x16x32_bf16 v[94:97], v[130:133], v[204:207], 0
	v_mfma_f32_16x16x32_bf16 v[90:93], v[138:141], v[204:207], 0
	v_mfma_f32_16x16x32_bf16 v[86:89], v[130:133], v[212:215], 0
	v_mfma_f32_16x16x32_bf16 v[82:85], v[138:141], v[212:215], 0
	v_mfma_f32_16x16x32_bf16 v[78:81], v[130:133], v[220:223], 0
	v_mfma_f32_16x16x32_bf16 v[74:77], v[138:141], v[220:223], 0
	v_mfma_f32_16x16x32_bf16 v[70:73], v[130:133], v[228:231], 0
	v_mfma_f32_16x16x32_bf16 v[66:69], v[138:141], v[228:231], 0
	v_mfma_f32_16x16x32_bf16 v[94:97], v[134:137], v[208:211], v[94:97]
	v_mfma_f32_16x16x32_bf16 v[90:93], v[142:145], v[208:211], v[90:93]
	v_mfma_f32_16x16x32_bf16 v[86:89], v[134:137], v[216:219], v[86:89]
	v_mfma_f32_16x16x32_bf16 v[82:85], v[142:145], v[216:219], v[82:85]
	v_mfma_f32_16x16x32_bf16 v[78:81], v[134:137], v[224:227], v[78:81]
	v_mfma_f32_16x16x32_bf16 v[74:77], v[142:145], v[224:227], v[74:77]
	v_mfma_f32_16x16x32_bf16 v[70:73], v[134:137], v[232:235], v[70:73]
	v_mfma_f32_16x16x32_bf16 v[66:69], v[142:145], v[232:235], v[66:69]
	s_setprio 0
	s_setprio 1
	v_mfma_f32_16x16x32_bf16 v[30:33], v[164:167], v[204:207], 0
	v_mfma_f32_16x16x32_bf16 v[26:29], v[172:175], v[204:207], 0
	v_mfma_f32_16x16x32_bf16 v[22:25], v[164:167], v[212:215], 0
	v_mfma_f32_16x16x32_bf16 v[18:21], v[172:175], v[212:215], 0
	v_mfma_f32_16x16x32_bf16 v[14:17], v[164:167], v[220:223], 0
	v_mfma_f32_16x16x32_bf16 v[10:13], v[172:175], v[220:223], 0
	v_mfma_f32_16x16x32_bf16 v[6:9], v[164:167], v[228:231], 0
	v_mfma_f32_16x16x32_bf16 v[2:5], v[172:175], v[228:231], 0
	v_mfma_f32_16x16x32_bf16 v[30:33], v[168:171], v[208:211], v[30:33]
	v_mfma_f32_16x16x32_bf16 v[26:29], v[176:179], v[208:211], v[26:29]
	v_mfma_f32_16x16x32_bf16 v[22:25], v[168:171], v[216:219], v[22:25]
	v_mfma_f32_16x16x32_bf16 v[18:21], v[176:179], v[216:219], v[18:21]
	v_mfma_f32_16x16x32_bf16 v[14:17], v[168:171], v[224:227], v[14:17]
	v_mfma_f32_16x16x32_bf16 v[10:13], v[176:179], v[224:227], v[10:13]
	v_mfma_f32_16x16x32_bf16 v[6:9], v[168:171], v[232:235], v[6:9]
	v_mfma_f32_16x16x32_bf16 v[2:5], v[176:179], v[232:235], v[2:5]
	s_barrier
; #define PG8_STAGE(bufoff, gbase, voff) do { _Pragma("unroll") for (int _i = 0; _i < 2; ++_i) \
;         __builtin_amdgcn_global_load_lds((const unsigned*)((const char*)(gbase) + (voff)[_i]), (PG8_LAS unsigned*)(lds + (bufoff) + ldsw + _i * 8192), 16, 0, 0); } while (0)
; #define PG8_LDA(dst, b, h) do { _Pragma("unroll") for (int m = 0; m < 4; ++m) _Pragma("unroll") for (int k = 0; k < 2; ++k) dst[m][k] = *(const PG8_LAS bf16x8*)(lds + PG8_SA(b, h) + aoff + m * 2048 + k * 1024); } while (0)
; #define PG8_LDB(dst, b, h) do { _Pragma("unroll") for (int n = 0; n < 2; ++n) _Pragma("unroll") for (int k = 0; k < 2; ++k) dst[n][k] = *(const PG8_LAS bf16x8*)(lds + PG8_SB(b, h) + boff + n * 2048 + k * 1024); } while (0)
; #define PG8_MMA(ai, bj, At, Bt) do { __builtin_amdgcn_s_setprio(1); _Pragma("unroll") for (int m = 0; m < 4; ++m) _Pragma("unroll") for (int n = 0; n < 2; ++n) _Pragma("unroll") for (int k = 0; k < 2; ++k) \
;         acc[ai][bj][m][n] = __builtin_amdgcn_mfma_f32_16x16x32_bf16(Bt[n][k], At[m][k], acc[ai][bj][m][n], 0, 0, 0); __builtin_amdgcn_s_setprio(0); } while (0)
; #define PG8_WAIT_V(n) asm volatile("s_waitcnt vmcnt(" #n ")" ::: "memory")
; #define PG8_WAIT_L(n) asm volatile("s_waitcnt lgkmcnt(" #n ")" ::: "memory")
; #define PG8_BAR __builtin_amdgcn_s_barrier()
; #define PG8_SCHED __builtin_amdgcn_sched_barrier(0)
; template <class Epi, class Sched, bool ALIGN_EPI = false, bool SP2 = false>
; __device__ __forceinline__ void gemm_phase(PG8_LAS unsigned char* lds, const Gemm g, const Sched& S, const Epi& E) {
;     ...
;             PG8_LDB(B0, 1, 0); PG8_LDB(B1, 1, 1); PG8_SCHED; PG8_LDA(At, 1, 0); PG8_STAGE(PG8_SA(0, 1), a2 + hstep, voffA);
;             PG8_WAIT_V(8); PG8_WAIT_L(0); PG8_BAR; PG8_MMA(0, 0, At, B0); PG8_MMA(0, 1, At, B1); PG8_BAR; PG8_SCHED;
;             PG8_LDA(At, 1, 1); PG8_STAGE(PG8_SB(1, 0), b3, voffB); PG8_STAGE(PG8_SB(1, 1), b3 + hstep, voffB); PG8_STAGE(PG8_SA(1, 0), a3, voffA);
;             PG8_WAIT_V(8); PG8_WAIT_L(0); PG8_BAR; PG8_MMA(1, 0, At, B0); PG8_MMA(1, 1, At, B1); PG8_BAR; PG8_SCHED;
	s_setprio 0
	s_add_i32 s56, 0, 0x18000
	s_add_i32 s57, 0, 0x1c000
	v_add_u32_e32 v142, s56, v201
	v_add_u32_e32 v176, s57, v201
	ds_read_b128 v[130:133], v142
	ds_read_b128 v[134:137], v142 offset:1024
	ds_read_b128 v[138:141], v142 offset:2048
	ds_read_b128 v[142:145], v142 offset:3072
	ds_read_b128 v[164:167], v176
	ds_read_b128 v[168:171], v176 offset:1024
	ds_read_b128 v[172:175], v176 offset:2048
	ds_read_b128 v[176:179], v176 offset:3072
	s_add_u32 s20, s20, 0x100000
	s_addc_u32 s21, s21, 0
	s_mov_b32 m0, s27
	v_lshl_add_u64 v[238:239], s[20:21], 0, v[158:159]
	ds_read_b128 v[204:207], v203 offset:32768
	ds_read_b128 v[208:211], v203 offset:33792
	ds_read_b128 v[212:215], v203 offset:34816
	ds_read_b128 v[216:219], v203 offset:35840
	ds_read_b128 v[220:223], v203 offset:36864
	ds_read_b128 v[224:227], v203 offset:37888
	ds_read_b128 v[228:231], v203 offset:38912
	ds_read_b128 v[232:235], v203 offset:39936
	global_load_lds_dwordx4 v[238:239], off
	v_lshl_add_u64 v[238:239], s[20:21], 0, v[156:157]
	s_mov_b32 m0, s28
	s_nop 0
	global_load_lds_dwordx4 v[238:239], off
	s_waitcnt vmcnt(8)
	s_waitcnt lgkmcnt(0)
	s_setprio 1
	s_barrier
	v_mfma_f32_16x16x32_bf16 v[126:129], v[130:133], v[204:207], v[126:129]
	v_mfma_f32_16x16x32_bf16 v[122:125], v[138:141], v[204:207], v[122:125]
	v_mfma_f32_16x16x32_bf16 v[118:121], v[130:133], v[212:215], v[118:121]
	v_mfma_f32_16x16x32_bf16 v[114:117], v[138:141], v[212:215], v[114:117]
	v_mfma_f32_16x16x32_bf16 v[110:113], v[130:133], v[220:223], v[110:113]
	v_mfma_f32_16x16x32_bf16 v[106:109], v[138:141], v[220:223], v[106:109]
	v_mfma_f32_16x16x32_bf16 v[102:105], v[130:133], v[228:231], v[102:105]
	v_mfma_f32_16x16x32_bf16 v[98:101], v[138:141], v[228:231], v[98:101]
	v_mfma_f32_16x16x32_bf16 v[126:129], v[134:137], v[208:211], v[126:129]
	v_mfma_f32_16x16x32_bf16 v[122:125], v[142:145], v[208:211], v[122:125]
	v_mfma_f32_16x16x32_bf16 v[118:121], v[134:137], v[216:219], v[118:121]
	v_mfma_f32_16x16x32_bf16 v[114:117], v[142:145], v[216:219], v[114:117]
	v_mfma_f32_16x16x32_bf16 v[110:113], v[134:137], v[224:227], v[110:113]
	v_mfma_f32_16x16x32_bf16 v[106:109], v[142:145], v[224:227], v[106:109]
	v_mfma_f32_16x16x32_bf16 v[102:105], v[134:137], v[232:235], v[102:105]
	v_mfma_f32_16x16x32_bf16 v[98:101], v[142:145], v[232:235], v[98:101]
	s_setprio 0
	s_setprio 1
	v_mfma_f32_16x16x32_bf16 v[62:65], v[164:167], v[204:207], v[62:65]
	v_mfma_f32_16x16x32_bf16 v[58:61], v[172:175], v[204:207], v[58:61]
	v_mfma_f32_16x16x32_bf16 v[54:57], v[164:167], v[212:215], v[54:57]
	v_mfma_f32_16x16x32_bf16 v[50:53], v[172:175], v[212:215], v[50:53]
	v_mfma_f32_16x16x32_bf16 v[46:49], v[164:167], v[220:223], v[46:49]
	v_mfma_f32_16x16x32_bf16 v[42:45], v[172:175], v[220:223], v[42:45]
	v_mfma_f32_16x16x32_bf16 v[38:41], v[164:167], v[228:231], v[38:41]
	v_mfma_f32_16x16x32_bf16 v[34:37], v[172:175], v[228:231], v[34:37]
	v_mfma_f32_16x16x32_bf16 v[62:65], v[168:171], v[208:211], v[62:65]
	v_mfma_f32_16x16x32_bf16 v[58:61], v[176:179], v[208:211], v[58:61]
	v_mfma_f32_16x16x32_bf16 v[54:57], v[168:171], v[216:219], v[54:57]
	v_mfma_f32_16x16x32_bf16 v[50:53], v[176:179], v[216:219], v[50:53]
	v_mfma_f32_16x16x32_bf16 v[46:49], v[168:171], v[224:227], v[46:49]
	v_mfma_f32_16x16x32_bf16 v[42:45], v[176:179], v[224:227], v[42:45]
	v_mfma_f32_16x16x32_bf16 v[38:41], v[168:171], v[232:235], v[38:41]
	v_mfma_f32_16x16x32_bf16 v[34:37], v[176:179], v[232:235], v[34:37]
	s_barrier
	s_setprio 0
	s_add_i32 s20, s56, s24
	v_lshl_add_u64 v[146:147], v[146:147], 0, s[38:39]
	s_mov_b32 m0, s20
	ds_read_b128 v[204:207], v203 offset:49152
	ds_read_b128 v[208:211], v203 offset:50176
	ds_read_b128 v[212:215], v203 offset:51200
	ds_read_b128 v[216:219], v203 offset:52224
	ds_read_b128 v[220:223], v203 offset:53248
	ds_read_b128 v[224:227], v203 offset:54272
	ds_read_b128 v[228:231], v203 offset:55296
	ds_read_b128 v[232:235], v203 offset:56320
	global_load_lds_dwordx4 v[146:147], off
	s_add_i32 m0, s20, 0x2000
	s_add_u32 s18, s18, 0x100080
	v_lshl_add_u64 v[146:147], v[148:149], 0, s[38:39]
	s_addc_u32 s19, s19, 0
	s_add_i32 s20, s57, s24
	global_load_lds_dwordx4 v[146:147], off
	v_lshl_add_u64 v[146:147], s[18:19], 0, v[0:1]
	s_mov_b32 m0, s20
	s_nop 0
	global_load_lds_dwordx4 v[146:147], off
	v_lshl_add_u64 v[146:147], s[18:19], 0, v[154:155]
	s_add_i32 m0, s20, 0x2000
	s_nop 0
	global_load_lds_dwordx4 v[146:147], off
	v_lshl_add_u64 v[146:147], v[180:181], 0, s[38:39]
	s_mov_b32 m0, s31
	s_nop 0
	global_load_lds_dwordx4 v[146:147], off
	v_lshl_add_u64 v[146:147], v[236:237], 0, s[38:39]
	s_mov_b32 m0, s33
	s_nop 0
	global_load_lds_dwordx4 v[146:147], off
	s_waitcnt vmcnt(8)
	s_waitcnt lgkmcnt(0)
	s_setprio 1
	s_barrier
; #define PG8_STAGE(bufoff, gbase, voff) do { _Pragma("unroll") for (int _i = 0; _i < 2; ++_i) \
;         __builtin_amdgcn_global_load_lds((const unsigned*)((const char*)(gbase) + (voff)[_i]), (PG8_LAS unsigned*)(lds + (bufoff) + ldsw + _i * 8192), 16, 0, 0); } while (0)
; #define PG8_LDA(dst, b, h) do { _Pragma("unroll") for (int m = 0; m < 4; ++m) _Pragma("unroll") for (int k = 0; k < 2; ++k) dst[m][k] = *(const PG8_LAS bf16x8*)(lds + PG8_SA(b, h) + aoff + m * 2048 + k * 1024); } while (0)
; #define PG8_LDB(dst, b, h) do { _Pragma("unroll") for (int n = 0; n < 2; ++n) _Pragma("unroll") for (int k = 0; k < 2; ++k) dst[n][k] = *(const PG8_LAS bf16x8*)(lds + PG8_SB(b, h) + boff + n * 2048 + k * 1024); } while (0)
; #define PG8_MMA(ai, bj, At, Bt) do { __builtin_amdgcn_s_setprio(1); _Pragma("unroll") for (int m = 0; m < 4; ++m) _Pragma("unroll") for (int n = 0; n < 2; ++n) _Pragma("unroll") for (int k = 0; k < 2; ++k) \
;         acc[ai][bj][m][n] = __builtin_amdgcn_mfma_f32_16x16x32_bf16(Bt[n][k], At[m][k], acc[ai][bj][m][n], 0, 0, 0); __builtin_amdgcn_s_setprio(0); } while (0)
; #define PG8_WAIT_V(n) asm volatile("s_waitcnt vmcnt(" #n ")" ::: "memory")
; template <class Epi, class Sched, bool ALIGN_EPI = false, bool SP2 = false>
; __device__ __forceinline__ void gemm_phase(PG8_LAS unsigned char* lds, const Gemm g, const Sched& S, const Epi& E) {
;     ...
;             PG8_LDB(B0, 0, 0); PG8_LDB(B1, 0, 1); PG8_SCHED; PG8_LDA(At, 0, 0); PG8_STAGE(PG8_SA(1, 1), a1 + hstep, voffA);
;             PG8_WAIT_V(8); PG8_WAIT_L(0); PG8_BAR; PG8_MMA(0, 0, At, B0); PG8_MMA(0, 1, At, B1); PG8_BAR; PG8_SCHED;
;             PG8_LDA(At, 0, 1); PG8_STAGE(PG8_SB(0, 0), b2, voffB); PG8_STAGE(PG8_SB(0, 1), b2 + hstep, voffB); PG8_STAGE(PG8_SA(0, 0), a2, voffA);
;             PG8_WAIT_V(8); PG8_WAIT_L(0); PG8_BAR; PG8_MMA(1, 0, At, B0); PG8_MMA(1, 1, At, B1); PG8_BAR; PG8_SCHED;
;             PG8_LDB(B0, 1, 0); PG8_LDB(B1, 1, 1); PG8_SCHED; PG8_LDA(At, 1, 0); PG8_STAGE(PG8_SA(0, 1), a2 + hstep, voffA);
;             PG8_WAIT_V(8); PG8_WAIT_L(0); PG8_BAR; PG8_MMA(0, 0, At, B0); PG8_MMA(0, 1, At, B1); PG8_BAR; PG8_SCHED;
;             PG8_LDA(At, 1, 1); PG8_STAGE(PG8_SB(1, 0), b3, voffB); PG8_STAGE(PG8_SB(1, 1), b3 + hstep, voffB); PG8_STAGE(PG8_SA(1, 0), a3, voffA);
;             PG8_WAIT_V(8); PG8_WAIT_L(0); PG8_BAR; PG8_MMA(1, 0, At, B0); PG8_MMA(1, 1, At, B1); PG8_BAR; PG8_SCHED;
	v_mfma_f32_16x16x32_bf16 v[94:97], v[130:133], v[204:207], v[94:97]
	v_mfma_f32_16x16x32_bf16 v[90:93], v[138:141], v[204:207], v[90:93]
	v_mfma_f32_16x16x32_bf16 v[86:89], v[130:133], v[212:215], v[86:89]
	v_mfma_f32_16x16x32_bf16 v[82:85], v[138:141], v[212:215], v[82:85]
	v_mfma_f32_16x16x32_bf16 v[78:81], v[130:133], v[220:223], v[78:81]
	v_mfma_f32_16x16x32_bf16 v[74:77], v[138:141], v[220:223], v[74:77]
	v_mfma_f32_16x16x32_bf16 v[70:73], v[130:133], v[228:231], v[70:73]
	v_mfma_f32_16x16x32_bf16 v[66:69], v[138:141], v[228:231], v[66:69]
	v_mfma_f32_16x16x32_bf16 v[94:97], v[134:137], v[208:211], v[94:97]
	v_mfma_f32_16x16x32_bf16 v[90:93], v[142:145], v[208:211], v[90:93]
	v_mfma_f32_16x16x32_bf16 v[86:89], v[134:137], v[216:219], v[86:89]
	v_mfma_f32_16x16x32_bf16 v[82:85], v[142:145], v[216:219], v[82:85]
	v_mfma_f32_16x16x32_bf16 v[78:81], v[134:137], v[224:227], v[78:81]
	v_mfma_f32_16x16x32_bf16 v[74:77], v[142:145], v[224:227], v[74:77]
	v_mfma_f32_16x16x32_bf16 v[70:73], v[134:137], v[232:235], v[70:73]
	v_mfma_f32_16x16x32_bf16 v[66:69], v[142:145], v[232:235], v[66:69]
	s_setprio 0
	s_setprio 1
	v_mfma_f32_16x16x32_bf16 v[30:33], v[164:167], v[204:207], v[30:33]
	v_mfma_f32_16x16x32_bf16 v[26:29], v[172:175], v[204:207], v[26:29]
	v_mfma_f32_16x16x32_bf16 v[22:25], v[164:167], v[212:215], v[22:25]
	v_mfma_f32_16x16x32_bf16 v[18:21], v[172:175], v[212:215], v[18:21]
	v_mfma_f32_16x16x32_bf16 v[14:17], v[164:167], v[220:223], v[14:17]
	v_mfma_f32_16x16x32_bf16 v[10:13], v[172:175], v[220:223], v[10:13]
	v_mfma_f32_16x16x32_bf16 v[6:9], v[164:167], v[228:231], v[6:9]
	v_mfma_f32_16x16x32_bf16 v[2:5], v[172:175], v[228:231], v[2:5]
	v_mfma_f32_16x16x32_bf16 v[30:33], v[168:171], v[208:211], v[30:33]
	v_mfma_f32_16x16x32_bf16 v[26:29], v[176:179], v[208:211], v[26:29]
	v_mfma_f32_16x16x32_bf16 v[22:25], v[168:171], v[216:219], v[22:25]
	v_mfma_f32_16x16x32_bf16 v[18:21], v[176:179], v[216:219], v[18:21]
	v_mfma_f32_16x16x32_bf16 v[14:17], v[168:171], v[224:227], v[14:17]
	v_mfma_f32_16x16x32_bf16 v[10:13], v[176:179], v[224:227], v[10:13]
	v_mfma_f32_16x16x32_bf16 v[6:9], v[168:171], v[232:235], v[6:9]
	v_mfma_f32_16x16x32_bf16 v[2:5], v[176:179], v[232:235], v[2:5]
	s_barrier
	s_setprio 0
	s_add_i32 s55, s55, 2
	s_add_u32 s16, s16, 0x100
	s_addc_u32 s17, s17, 0
	s_add_u32 s53, s53, 0x100
	s_addc_u32 s54, s54, 0
.LBB0_432:
	s_add_u32 s18, s16, 0xfff00080
	s_addc_u32 s19, s17, -1
	s_add_i32 s56, 0, 0x10000
	s_cmp_eq_u32 s55, 60
	s_cselect_b32 s21, s11, s19
	s_cselect_b32 s20, s51, s18
	s_cselect_b32 s19, s9, s54
	s_cselect_b32 s18, s52, s53
	s_add_i32 s58, 0, 0x14000
	v_add_u32_e32 v142, s56, v201
	v_add_u32_e32 v146, s58, v201
	ds_read_b128 v[130:133], v142
	ds_read_b128 v[134:137], v142 offset:1024
	ds_read_b128 v[138:141], v142 offset:2048
	ds_read_b128 v[142:145], v142 offset:3072
	ds_read_b128 v[164:167], v146
	ds_read_b128 v[168:171], v146 offset:1024
	ds_read_b128 v[172:175], v146 offset:2048
	ds_read_b128 v[176:179], v146 offset:3072
	v_lshl_add_u64 v[146:147], s[16:17], 0, v[160:161]
	s_add_i32 m0, s25, 0xc000
	ds_read_b128 v[204:207], v203
	ds_read_b128 v[208:211], v203 offset:1024
	ds_read_b128 v[212:215], v203 offset:2048
	ds_read_b128 v[216:219], v203 offset:3072
	ds_read_b128 v[220:223], v203 offset:4096
	ds_read_b128 v[224:227], v203 offset:5120
	ds_read_b128 v[228:231], v203 offset:6144
	ds_read_b128 v[232:235], v203 offset:7168
	global_load_lds_dwordx4 v[146:147], off
	v_lshl_add_u64 v[146:147], s[16:17], 0, v[162:163]
	s_add_i32 m0, s25, 0xe000
	s_nop 0
	global_load_lds_dwordx4 v[146:147], off
	s_waitcnt vmcnt(8)
	s_waitcnt lgkmcnt(0)
	s_setprio 1
	s_barrier
	v_mfma_f32_16x16x32_bf16 v[126:129], v[130:133], v[204:207], v[126:129]
	v_mfma_f32_16x16x32_bf16 v[122:125], v[138:141], v[204:207], v[122:125]
	v_mfma_f32_16x16x32_bf16 v[118:121], v[130:133], v[212:215], v[118:121]
	v_mfma_f32_16x16x32_bf16 v[114:117], v[138:141], v[212:215], v[114:117]
	v_mfma_f32_16x16x32_bf16 v[110:113], v[130:133], v[220:223], v[110:113]
	v_mfma_f32_16x16x32_bf16 v[106:109], v[138:141], v[220:223], v[106:109]
	v_mfma_f32_16x16x32_bf16 v[102:105], v[130:133], v[228:231], v[102:105]
	v_mfma_f32_16x16x32_bf16 v[98:101], v[138:141], v[228:231], v[98:101]
	v_mfma_f32_16x16x32_bf16 v[126:129], v[134:137], v[208:211], v[126:129]
	v_mfma_f32_16x16x32_bf16 v[122:125], v[142:145], v[208:211], v[122:125]
	v_mfma_f32_16x16x32_bf16 v[118:121], v[134:137], v[216:219], v[118:121]
	v_mfma_f32_16x16x32_bf16 v[114:117], v[142:145], v[216:219], v[114:117]
	v_mfma_f32_16x16x32_bf16 v[110:113], v[134:137], v[224:227], v[110:113]
	v_mfma_f32_16x16x32_bf16 v[106:109], v[142:145], v[224:227], v[106:109]
	v_mfma_f32_16x16x32_bf16 v[102:105], v[134:137], v[232:235], v[102:105]
	v_mfma_f32_16x16x32_bf16 v[98:101], v[142:145], v[232:235], v[98:101]
	s_setprio 0
	s_setprio 1
	v_mfma_f32_16x16x32_bf16 v[62:65], v[164:167], v[204:207], v[62:65]
	v_mfma_f32_16x16x32_bf16 v[58:61], v[172:175], v[204:207], v[58:61]
	v_mfma_f32_16x16x32_bf16 v[54:57], v[164:167], v[212:215], v[54:57]
	v_mfma_f32_16x16x32_bf16 v[50:53], v[172:175], v[212:215], v[50:53]
	v_mfma_f32_16x16x32_bf16 v[46:49], v[164:167], v[220:223], v[46:49]
	v_mfma_f32_16x16x32_bf16 v[42:45], v[172:175], v[220:223], v[42:45]
	v_mfma_f32_16x16x32_bf16 v[38:41], v[164:167], v[228:231], v[38:41]
	v_mfma_f32_16x16x32_bf16 v[34:37], v[172:175], v[228:231], v[34:37]
	v_mfma_f32_16x16x32_bf16 v[62:65], v[168:171], v[208:211], v[62:65]
	v_mfma_f32_16x16x32_bf16 v[58:61], v[176:179], v[208:211], v[58:61]
	v_mfma_f32_16x16x32_bf16 v[54:57], v[168:171], v[216:219], v[54:57]
	v_mfma_f32_16x16x32_bf16 v[50:53], v[176:179], v[216:219], v[50:53]
	v_mfma_f32_16x16x32_bf16 v[46:49], v[168:171], v[224:227], v[46:49]
	v_mfma_f32_16x16x32_bf16 v[42:45], v[176:179], v[224:227], v[42:45]
	v_mfma_f32_16x16x32_bf16 v[38:41], v[168:171], v[232:235], v[38:41]
	v_mfma_f32_16x16x32_bf16 v[34:37], v[176:179], v[232:235], v[34:37]
	s_barrier
; #define PG8_STAGE(bufoff, gbase, voff) do { _Pragma("unroll") for (int _i = 0; _i < 2; ++_i) \
;         __builtin_amdgcn_global_load_lds((const unsigned*)((const char*)(gbase) + (voff)[_i]), (PG8_LAS unsigned*)(lds + (bufoff) + ldsw + _i * 8192), 16, 0, 0); } while (0)
; #define PG8_LDA(dst, b, h) do { _Pragma("unroll") for (int m = 0; m < 4; ++m) _Pragma("unroll") for (int k = 0; k < 2; ++k) dst[m][k] = *(const PG8_LAS bf16x8*)(lds + PG8_SA(b, h) + aoff + m * 2048 + k * 1024); } while (0)
; #define PG8_LDB(dst, b, h) do { _Pragma("unroll") for (int n = 0; n < 2; ++n) _Pragma("unroll") for (int k = 0; k < 2; ++k) dst[n][k] = *(const PG8_LAS bf16x8*)(lds + PG8_SB(b, h) + boff + n * 2048 + k * 1024); } while (0)
; #define PG8_MMA(ai, bj, At, Bt) do { __builtin_amdgcn_s_setprio(1); _Pragma("unroll") for (int m = 0; m < 4; ++m) _Pragma("unroll") for (int n = 0; n < 2; ++n) _Pragma("unroll") for (int k = 0; k < 2; ++k) \
;         acc[ai][bj][m][n] = __builtin_amdgcn_mfma_f32_16x16x32_bf16(Bt[n][k], At[m][k], acc[ai][bj][m][n], 0, 0, 0); __builtin_amdgcn_s_setprio(0); } while (0)
; #define PG8_WAIT_V(n) asm volatile("s_waitcnt vmcnt(" #n ")" ::: "memory")
; #define PG8_WAIT_L(n) asm volatile("s_waitcnt lgkmcnt(" #n ")" ::: "memory")
; #define PG8_BAR __builtin_amdgcn_s_barrier()
; #define PG8_SCHED __builtin_amdgcn_sched_barrier(0)
; template <class Epi, class Sched, bool ALIGN_EPI = false, bool SP2 = false>
; __device__ __forceinline__ void gemm_phase(PG8_LAS unsigned char* lds, const Gemm g, const Sched& S, const Epi& E) {
;     ...
;             PG8_LDA(At, 0, 1); PG8_STAGE(PG8_SB(0, 0), b2, voffB); PG8_STAGE(PG8_SB(0, 1), b2 + hstep, voffB); PG8_STAGE(PG8_SA(0, 0), a2, voffA);
;             PG8_WAIT_V(8); PG8_WAIT_L(0); PG8_BAR; PG8_MMA(1, 0, At, B0); PG8_MMA(1, 1, At, B1); PG8_BAR; PG8_SCHED;
;             PG8_LDB(B0, 1, 0); PG8_LDB(B1, 1, 1); PG8_SCHED; PG8_LDA(At, 1, 0); PG8_STAGE(PG8_SA(0, 1), a2 + hstep, voffA);
;             PG8_WAIT_V(8); PG8_WAIT_L(0); PG8_BAR; PG8_MMA(0, 0, At, B0); PG8_MMA(0, 1, At, B1); PG8_BAR; PG8_SCHED;
;             PG8_LDA(At, 1, 1); PG8_STAGE(PG8_SB(1, 0), b3, voffB); PG8_STAGE(PG8_SB(1, 1), b3 + hstep, voffB); PG8_STAGE(PG8_SA(1, 0), a3, voffA);
	s_setprio 0
	s_add_i32 s56, s56, s24
	v_lshl_add_u64 v[146:147], s[18:19], 0, v[0:1]
	s_mov_b32 m0, s56
	ds_read_b128 v[204:207], v203 offset:16384
	ds_read_b128 v[208:211], v203 offset:17408
	ds_read_b128 v[212:215], v203 offset:18432
	ds_read_b128 v[216:219], v203 offset:19456
	ds_read_b128 v[220:223], v203 offset:20480
	ds_read_b128 v[224:227], v203 offset:21504
	ds_read_b128 v[228:231], v203 offset:22528
	ds_read_b128 v[232:235], v203 offset:23552
	global_load_lds_dwordx4 v[146:147], off
	s_add_i32 m0, s56, 0x2000
	s_add_u32 s56, s18, 0x100000
	v_lshl_add_u64 v[148:149], s[18:19], 0, v[154:155]
	s_addc_u32 s57, s19, 0
	s_add_i32 s58, s58, s24
	global_load_lds_dwordx4 v[148:149], off
	v_lshl_add_u64 v[180:181], s[56:57], 0, v[0:1]
	s_mov_b32 m0, s58
	v_lshl_add_u64 v[236:237], s[20:21], 0, v[156:157]
	global_load_lds_dwordx4 v[180:181], off
	v_lshl_add_u64 v[180:181], s[56:57], 0, v[154:155]
	s_add_i32 m0, s58, 0x2000
	s_nop 0
	global_load_lds_dwordx4 v[180:181], off
	v_lshl_add_u64 v[180:181], s[20:21], 0, v[158:159]
	s_mov_b32 m0, s25
	s_nop 0
	global_load_lds_dwordx4 v[180:181], off
	s_mov_b32 m0, s26
	s_nop 0
	global_load_lds_dwordx4 v[236:237], off
	s_waitcnt vmcnt(8)
	s_waitcnt lgkmcnt(0)
	s_setprio 1
	s_barrier
	v_mfma_f32_16x16x32_bf16 v[94:97], v[130:133], v[204:207], v[94:97]
	v_mfma_f32_16x16x32_bf16 v[90:93], v[138:141], v[204:207], v[90:93]
	v_mfma_f32_16x16x32_bf16 v[86:89], v[130:133], v[212:215], v[86:89]
	v_mfma_f32_16x16x32_bf16 v[82:85], v[138:141], v[212:215], v[82:85]
	v_mfma_f32_16x16x32_bf16 v[78:81], v[130:133], v[220:223], v[78:81]
	v_mfma_f32_16x16x32_bf16 v[74:77], v[138:141], v[220:223], v[74:77]
	v_mfma_f32_16x16x32_bf16 v[70:73], v[130:133], v[228:231], v[70:73]
	v_mfma_f32_16x16x32_bf16 v[66:69], v[138:141], v[228:231], v[66:69]
	v_mfma_f32_16x16x32_bf16 v[94:97], v[134:137], v[208:211], v[94:97]
	v_mfma_f32_16x16x32_bf16 v[90:93], v[142:145], v[208:211], v[90:93]
	v_mfma_f32_16x16x32_bf16 v[86:89], v[134:137], v[216:219], v[86:89]
	v_mfma_f32_16x16x32_bf16 v[82:85], v[142:145], v[216:219], v[82:85]
	v_mfma_f32_16x16x32_bf16 v[78:81], v[134:137], v[224:227], v[78:81]
	v_mfma_f32_16x16x32_bf16 v[74:77], v[142:145], v[224:227], v[74:77]
	v_mfma_f32_16x16x32_bf16 v[70:73], v[134:137], v[232:235], v[70:73]
	v_mfma_f32_16x16x32_bf16 v[66:69], v[142:145], v[232:235], v[66:69]
	s_setprio 0
	s_setprio 1
	v_mfma_f32_16x16x32_bf16 v[30:33], v[164:167], v[204:207], v[30:33]
	v_mfma_f32_16x16x32_bf16 v[26:29], v[172:175], v[204:207], v[26:29]
	v_mfma_f32_16x16x32_bf16 v[22:25], v[164:167], v[212:215], v[22:25]
	v_mfma_f32_16x16x32_bf16 v[18:21], v[172:175], v[212:215], v[18:21]
	v_mfma_f32_16x16x32_bf16 v[14:17], v[164:167], v[220:223], v[14:17]
	v_mfma_f32_16x16x32_bf16 v[10:13], v[172:175], v[220:223], v[10:13]
	v_mfma_f32_16x16x32_bf16 v[6:9], v[164:167], v[228:231], v[6:9]
	v_mfma_f32_16x16x32_bf16 v[2:5], v[172:175], v[228:231], v[2:5]
	v_mfma_f32_16x16x32_bf16 v[30:33], v[168:171], v[208:211], v[30:33]
	v_mfma_f32_16x16x32_bf16 v[26:29], v[176:179], v[208:211], v[26:29]
	v_mfma_f32_16x16x32_bf16 v[22:25], v[168:171], v[216:219], v[22:25]
	v_mfma_f32_16x16x32_bf16 v[18:21], v[176:179], v[216:219], v[18:21]
	v_mfma_f32_16x16x32_bf16 v[14:17], v[168:171], v[224:227], v[14:17]
	v_mfma_f32_16x16x32_bf16 v[10:13], v[176:179], v[224:227], v[10:13]
	v_mfma_f32_16x16x32_bf16 v[6:9], v[168:171], v[232:235], v[6:9]
	v_mfma_f32_16x16x32_bf16 v[2:5], v[176:179], v[232:235], v[2:5]
	s_barrier
	s_setprio 0
	s_add_i32 s56, 0, 0x18000
	s_add_i32 s57, 0, 0x1c000
	v_add_u32_e32 v142, s56, v201
	v_add_u32_e32 v176, s57, v201
	ds_read_b128 v[130:133], v142
	ds_read_b128 v[134:137], v142 offset:1024
	ds_read_b128 v[138:141], v142 offset:2048
	ds_read_b128 v[142:145], v142 offset:3072
	ds_read_b128 v[164:167], v176
	ds_read_b128 v[168:171], v176 offset:1024
	ds_read_b128 v[172:175], v176 offset:2048
	ds_read_b128 v[176:179], v176 offset:3072
	s_add_u32 s20, s20, 0x100000
	s_addc_u32 s21, s21, 0
	s_mov_b32 m0, s27
	v_lshl_add_u64 v[238:239], s[20:21], 0, v[158:159]
	ds_read_b128 v[204:207], v203 offset:32768
	ds_read_b128 v[208:211], v203 offset:33792
	ds_read_b128 v[212:215], v203 offset:34816
	ds_read_b128 v[216:219], v203 offset:35840
	ds_read_b128 v[220:223], v203 offset:36864
	ds_read_b128 v[224:227], v203 offset:37888
	ds_read_b128 v[228:231], v203 offset:38912
	ds_read_b128 v[232:235], v203 offset:39936
	global_load_lds_dwordx4 v[238:239], off
	v_lshl_add_u64 v[238:239], s[20:21], 0, v[156:157]
	s_mov_b32 m0, s28
	s_nop 0
	global_load_lds_dwordx4 v[238:239], off
	s_waitcnt vmcnt(8)
	s_waitcnt lgkmcnt(0)
	s_setprio 1
	s_barrier
; #define PG8_STAGE(bufoff, gbase, voff) do { _Pragma("unroll") for (int _i = 0; _i < 2; ++_i) \
;         __builtin_amdgcn_global_load_lds((const unsigned*)((const char*)(gbase) + (voff)[_i]), (PG8_LAS unsigned*)(lds + (bufoff) + ldsw + _i * 8192), 16, 0, 0); } while (0)
; #define PG8_LDA(dst, b, h) do { _Pragma("unroll") for (int m = 0; m < 4; ++m) _Pragma("unroll") for (int k = 0; k < 2; ++k) dst[m][k] = *(const PG8_LAS bf16x8*)(lds + PG8_SA(b, h) + aoff + m * 2048 + k * 1024); } while (0)
; #define PG8_LDB(dst, b, h) do { _Pragma("unroll") for (int n = 0; n < 2; ++n) _Pragma("unroll") for (int k = 0; k < 2; ++k) dst[n][k] = *(const PG8_LAS bf16x8*)(lds + PG8_SB(b, h) + boff + n * 2048 + k * 1024); } while (0)
; #define PG8_MMA(ai, bj, At, Bt) do { __builtin_amdgcn_s_setprio(1); _Pragma("unroll") for (int m = 0; m < 4; ++m) _Pragma("unroll") for (int n = 0; n < 2; ++n) _Pragma("unroll") for (int k = 0; k < 2; ++k) \
;         acc[ai][bj][m][n] = __builtin_amdgcn_mfma_f32_16x16x32_bf16(Bt[n][k], At[m][k], acc[ai][bj][m][n], 0, 0, 0); __builtin_amdgcn_s_setprio(0); } while (0)
; #define PG8_WAIT_V(n) asm volatile("s_waitcnt vmcnt(" #n ")" ::: "memory")
; #define PG8_WAIT_L(n) asm volatile("s_waitcnt lgkmcnt(" #n ")" ::: "memory")
; #define PG8_BAR __builtin_amdgcn_s_barrier()
; #define PG8_SCHED __builtin_amdgcn_sched_barrier(0)
; template <class Epi, class Sched, bool ALIGN_EPI = false, bool SP2 = false>
; __device__ __forceinline__ void gemm_phase(PG8_LAS unsigned char* lds, const Gemm g, const Sched& S, const Epi& E) {
;     ...
;             PG8_LDB(B0, 1, 0); PG8_LDB(B1, 1, 1); PG8_SCHED; PG8_LDA(At, 1, 0); PG8_STAGE(PG8_SA(0, 1), a2 + hstep, voffA);
;             PG8_WAIT_V(8); PG8_WAIT_L(0); PG8_BAR; PG8_MMA(0, 0, At, B0); PG8_MMA(0, 1, At, B1); PG8_BAR; PG8_SCHED;
;             PG8_LDA(At, 1, 1); PG8_STAGE(PG8_SB(1, 0), b3, voffB); PG8_STAGE(PG8_SB(1, 1), b3 + hstep, voffB); PG8_STAGE(PG8_SA(1, 0), a3, voffA);
;             PG8_WAIT_V(8); PG8_WAIT_L(0); PG8_BAR; PG8_MMA(1, 0, At, B0); PG8_MMA(1, 1, At, B1); PG8_BAR; PG8_SCHED;
;     ...
;         if constexpr (ALIGN_EPI) { if (wr == 0) PG8_BAR; }
	v_mfma_f32_16x16x32_bf16 v[126:129], v[130:133], v[204:207], v[126:129]
	v_mfma_f32_16x16x32_bf16 v[122:125], v[138:141], v[204:207], v[122:125]
	v_mfma_f32_16x16x32_bf16 v[118:121], v[130:133], v[212:215], v[118:121]
	v_mfma_f32_16x16x32_bf16 v[114:117], v[138:141], v[212:215], v[114:117]
	v_mfma_f32_16x16x32_bf16 v[110:113], v[130:133], v[220:223], v[110:113]
	v_mfma_f32_16x16x32_bf16 v[106:109], v[138:141], v[220:223], v[106:109]
	v_mfma_f32_16x16x32_bf16 v[102:105], v[130:133], v[228:231], v[102:105]
	v_mfma_f32_16x16x32_bf16 v[98:101], v[138:141], v[228:231], v[98:101]
	v_mfma_f32_16x16x32_bf16 v[126:129], v[134:137], v[208:211], v[126:129]
	v_mfma_f32_16x16x32_bf16 v[122:125], v[142:145], v[208:211], v[122:125]
	v_mfma_f32_16x16x32_bf16 v[118:121], v[134:137], v[216:219], v[118:121]
	v_mfma_f32_16x16x32_bf16 v[114:117], v[142:145], v[216:219], v[114:117]
	v_mfma_f32_16x16x32_bf16 v[110:113], v[134:137], v[224:227], v[110:113]
	v_mfma_f32_16x16x32_bf16 v[106:109], v[142:145], v[224:227], v[106:109]
	v_mfma_f32_16x16x32_bf16 v[102:105], v[134:137], v[232:235], v[102:105]
	v_mfma_f32_16x16x32_bf16 v[98:101], v[142:145], v[232:235], v[98:101]
	s_setprio 0
	s_setprio 1
	v_mfma_f32_16x16x32_bf16 v[62:65], v[164:167], v[204:207], v[62:65]
	v_mfma_f32_16x16x32_bf16 v[58:61], v[172:175], v[204:207], v[58:61]
	v_mfma_f32_16x16x32_bf16 v[54:57], v[164:167], v[212:215], v[54:57]
	v_mfma_f32_16x16x32_bf16 v[50:53], v[172:175], v[212:215], v[50:53]
	v_mfma_f32_16x16x32_bf16 v[46:49], v[164:167], v[220:223], v[46:49]
	v_mfma_f32_16x16x32_bf16 v[42:45], v[172:175], v[220:223], v[42:45]
	v_mfma_f32_16x16x32_bf16 v[38:41], v[164:167], v[228:231], v[38:41]
	v_mfma_f32_16x16x32_bf16 v[34:37], v[172:175], v[228:231], v[34:37]
	v_mfma_f32_16x16x32_bf16 v[62:65], v[168:171], v[208:211], v[62:65]
	v_mfma_f32_16x16x32_bf16 v[58:61], v[176:179], v[208:211], v[58:61]
	v_mfma_f32_16x16x32_bf16 v[54:57], v[168:171], v[216:219], v[54:57]
	v_mfma_f32_16x16x32_bf16 v[50:53], v[176:179], v[216:219], v[50:53]
	v_mfma_f32_16x16x32_bf16 v[46:49], v[168:171], v[224:227], v[46:49]
	v_mfma_f32_16x16x32_bf16 v[42:45], v[176:179], v[224:227], v[42:45]
	v_mfma_f32_16x16x32_bf16 v[38:41], v[168:171], v[232:235], v[38:41]
	v_mfma_f32_16x16x32_bf16 v[34:37], v[176:179], v[232:235], v[34:37]
	s_barrier
	s_setprio 0
	s_add_i32 s20, s56, s24
	v_lshl_add_u64 v[146:147], v[146:147], 0, s[38:39]
	s_mov_b32 m0, s20
	ds_read_b128 v[204:207], v203 offset:49152
	ds_read_b128 v[208:211], v203 offset:50176
	ds_read_b128 v[212:215], v203 offset:51200
	ds_read_b128 v[216:219], v203 offset:52224
	ds_read_b128 v[220:223], v203 offset:53248
	ds_read_b128 v[224:227], v203 offset:54272
	ds_read_b128 v[228:231], v203 offset:55296
	ds_read_b128 v[232:235], v203 offset:56320
	global_load_lds_dwordx4 v[146:147], off
	s_add_i32 m0, s20, 0x2000
	s_add_u32 s18, s18, 0x100080
	v_lshl_add_u64 v[146:147], v[148:149], 0, s[38:39]
	s_addc_u32 s19, s19, 0
	s_add_i32 s20, s57, s24
	global_load_lds_dwordx4 v[146:147], off
	v_lshl_add_u64 v[146:147], s[18:19], 0, v[0:1]
	s_mov_b32 m0, s20
	s_nop 0
	global_load_lds_dwordx4 v[146:147], off
	v_lshl_add_u64 v[146:147], s[18:19], 0, v[154:155]
	s_add_i32 m0, s20, 0x2000
	s_nop 0
	global_load_lds_dwordx4 v[146:147], off
	v_lshl_add_u64 v[146:147], v[180:181], 0, s[38:39]
	s_mov_b32 m0, s31
	s_nop 0
	global_load_lds_dwordx4 v[146:147], off
	v_lshl_add_u64 v[146:147], v[236:237], 0, s[38:39]
	s_mov_b32 m0, s33
	s_nop 0
	global_load_lds_dwordx4 v[146:147], off
	s_waitcnt vmcnt(8)
	s_waitcnt lgkmcnt(0)
	s_setprio 1
	s_barrier
	v_mfma_f32_16x16x32_bf16 v[94:97], v[130:133], v[204:207], v[94:97]
	v_mfma_f32_16x16x32_bf16 v[90:93], v[138:141], v[204:207], v[90:93]
	v_mfma_f32_16x16x32_bf16 v[86:89], v[130:133], v[212:215], v[86:89]
	v_mfma_f32_16x16x32_bf16 v[82:85], v[138:141], v[212:215], v[82:85]
	v_mfma_f32_16x16x32_bf16 v[78:81], v[130:133], v[220:223], v[78:81]
	v_mfma_f32_16x16x32_bf16 v[74:77], v[138:141], v[220:223], v[74:77]
	v_mfma_f32_16x16x32_bf16 v[70:73], v[130:133], v[228:231], v[70:73]
	v_mfma_f32_16x16x32_bf16 v[66:69], v[138:141], v[228:231], v[66:69]
	v_mfma_f32_16x16x32_bf16 v[94:97], v[134:137], v[208:211], v[94:97]
	v_mfma_f32_16x16x32_bf16 v[90:93], v[142:145], v[208:211], v[90:93]
	v_mfma_f32_16x16x32_bf16 v[86:89], v[134:137], v[216:219], v[86:89]
	v_mfma_f32_16x16x32_bf16 v[82:85], v[142:145], v[216:219], v[82:85]
	v_mfma_f32_16x16x32_bf16 v[78:81], v[134:137], v[224:227], v[78:81]
	v_mfma_f32_16x16x32_bf16 v[74:77], v[142:145], v[224:227], v[74:77]
	v_mfma_f32_16x16x32_bf16 v[70:73], v[134:137], v[232:235], v[70:73]
	v_mfma_f32_16x16x32_bf16 v[66:69], v[142:145], v[232:235], v[66:69]
	s_setprio 0
	s_setprio 1
	v_mfma_f32_16x16x32_bf16 v[30:33], v[164:167], v[204:207], v[30:33]
	v_mfma_f32_16x16x32_bf16 v[26:29], v[172:175], v[204:207], v[26:29]
	v_mfma_f32_16x16x32_bf16 v[22:25], v[164:167], v[212:215], v[22:25]
	v_mfma_f32_16x16x32_bf16 v[18:21], v[172:175], v[212:215], v[18:21]
	v_mfma_f32_16x16x32_bf16 v[14:17], v[164:167], v[220:223], v[14:17]
	v_mfma_f32_16x16x32_bf16 v[10:13], v[172:175], v[220:223], v[10:13]
	v_mfma_f32_16x16x32_bf16 v[6:9], v[164:167], v[228:231], v[6:9]
	v_mfma_f32_16x16x32_bf16 v[2:5], v[172:175], v[228:231], v[2:5]
	v_mfma_f32_16x16x32_bf16 v[30:33], v[168:171], v[208:211], v[30:33]
	v_mfma_f32_16x16x32_bf16 v[26:29], v[176:179], v[208:211], v[26:29]
	v_mfma_f32_16x16x32_bf16 v[22:25], v[168:171], v[216:219], v[22:25]
	v_mfma_f32_16x16x32_bf16 v[18:21], v[176:179], v[216:219], v[18:21]
	v_mfma_f32_16x16x32_bf16 v[14:17], v[168:171], v[224:227], v[14:17]
	v_mfma_f32_16x16x32_bf16 v[10:13], v[176:179], v[224:227], v[10:13]
	v_mfma_f32_16x16x32_bf16 v[6:9], v[168:171], v[232:235], v[6:9]
	v_mfma_f32_16x16x32_bf16 v[2:5], v[176:179], v[232:235], v[2:5]
	s_barrier
	s_setprio 0
	s_add_i32 s55, s55, 2
	s_add_u32 s16, s16, 0x100
	s_addc_u32 s17, s17, 0
	s_add_u32 s53, s53, 0x100
	s_addc_u32 s54, s54, 0
	s_cmp_gt_u32 s55, 61
	s_cbranch_scc0 .LBB0_432
	s_and_b64 vcc, exec, s[6:7]
	s_cbranch_vccz .LBB0_435
	s_barrier

; #define PG8_STAGE(bufoff, gbase, voff) do { _Pragma("unroll") for (int _i = 0; _i < 2; ++_i) \
;         __builtin_amdgcn_global_load_lds((const unsigned*)((const char*)(gbase) + (voff)[_i]), (PG8_LAS unsigned*)(lds + (bufoff) + ldsw + _i * 8192), 16, 0, 0); } while (0)
; #define PG8_LDA(dst, b, h) do { _Pragma("unroll") for (int m = 0; m < 4; ++m) _Pragma("unroll") for (int k = 0; k < 2; ++k) dst[m][k] = *(const PG8_LAS bf16x8*)(lds + PG8_SA(b, h) + aoff + m * 2048 + k * 1024); } while (0)
; #define PG8_LDB(dst, b, h) do { _Pragma("unroll") for (int n = 0; n < 2; ++n) _Pragma("unroll") for (int k = 0; k < 2; ++k) dst[n][k] = *(const PG8_LAS bf16x8*)(lds + PG8_SB(b, h) + boff + n * 2048 + k * 1024); } while (0)
; #define PG8_WAIT_V(n) asm volatile("s_waitcnt vmcnt(" #n ")" ::: "memory")
; #define PG8_WAIT_L(n) asm volatile("s_waitcnt lgkmcnt(" #n ")" ::: "memory")
; #define PG8_BAR __builtin_amdgcn_s_barrier()
; #define PG8_SCHED __builtin_amdgcn_sched_barrier(0)
; template <class Epi, class Sched, bool ALIGN_EPI = false, bool SP2 = false>
; __device__ __forceinline__ void gemm_phase(PG8_LAS unsigned char* lds, const Gemm g, const Sched& S, const Epi& E) {
;     ...
;         const bool has_next = S.next(ui + 1, nxt);
;         const char* nA = has_next ? (const char*)g.A + (size_t)nxt.pm * tstep : cA; const char* nB = has_next ? (const char*)g.Bt + (size_t)nxt.pn * tstep : cB;
;         for (int t = 0; t < nt; t += 2) {
;             const bool last = (t == nt - 2);
;             const char* a1 = cA + (size_t)(t + 1) * kstep;
;             const char* a2 = last ? nA : cA + (size_t)(t + 2) * kstep; const char* b2 = last ? nB : cB + (size_t)(t + 2) * kstep;
;             const char* a3 = a2 + kstep; const char* b3 = b2 + kstep;
;             if (last && has_next) S.a_ready(nxt);
;             if constexpr (SP2) {
;             PG8_LDB(B0, 0, 0); PG8_LDB(B1, 0, 1); PG8_SCHED; PG8_LDA(At, 0, 0); PG8_STAGE(PG8_SA(1, 1), a1 + hstep, voffA);
;             PG8_WAIT_V(8); PG8_WAIT_L(0); PG8_BAR; PG8_MMA(0, 0, At, B0); PG8_MMA(0, 1, At, B1); PG8_BAR; PG8_SCHED;
;             PG8_LDA(At, 0, 1); PG8_STAGE(PG8_SB(0, 0), b2, voffB); PG8_STAGE(PG8_SB(0, 1), b2 + hstep, voffB); PG8_STAGE(PG8_SA(0, 0), a2, voffA);
;             PG8_WAIT_V(8); PG8_WAIT_L(0); PG8_BAR; PG8_MMA(1, 0, At, B0); PG8_MMA(1, 1, At, B1); PG8_BAR; PG8_SCHED;
.LBB0_557:
	s_ashr_i32 s15, s14, 31
	s_lshl_b64 s[16:17], s[14:15], 19
	s_add_u32 s16, s90, s16
	s_addc_u32 s17, s91, s17
	s_and_b64 s[18:19], s[6:7], exec
	s_cselect_b32 s15, s17, s23
	s_cselect_b32 s21, s16, s22
	s_ashr_i32 s13, s12, 31
	s_lshl_b64 s[18:19], s[12:13], 19
	s_add_u32 s18, s28, s18
	s_addc_u32 s19, s29, s19
	s_and_b64 s[26:27], s[6:7], exec
	s_cselect_b32 s13, s19, s25
	s_cselect_b32 s60, s18, s24
	s_add_u32 s22, s22, 0x40080
	s_addc_u32 s23, s23, 0
	s_add_u32 s61, s24, 0x100
	s_addc_u32 s62, s25, 0
	s_mov_b32 s63, -2
	s_add_u32 s24, s22, 0xfffc0080
	s_addc_u32 s25, s23, -1
	s_add_i32 s64, 0, 0x10000
	s_cmp_eq_u32 s63, 12
	s_cselect_b32 s27, s15, s25
	s_cselect_b32 s26, s21, s24
	s_cselect_b32 s25, s13, s62
	s_cselect_b32 s24, s60, s61
	s_add_i32 s66, 0, 0x14000
	v_lshl_add_u64 v[146:147], s[22:23], 0, v[164:165]
	s_add_i32 m0, s50, 0xc000
	global_load_lds_dwordx4 v[146:147], off
	v_lshl_add_u64 v[146:147], s[22:23], 0, v[166:167]
	s_add_i32 m0, s50, 0xe000
	s_nop 0
	global_load_lds_dwordx4 v[146:147], off
	s_waitcnt vmcnt(24)
	s_waitcnt lgkmcnt(0)
	s_setprio 1
	s_barrier
	v_mfma_f32_16x16x32_bf16 v[126:129], v[130:133], v[212:215], 0
	v_mfma_f32_16x16x32_bf16 v[122:125], v[138:141], v[212:215], 0
	v_mfma_f32_16x16x32_bf16 v[114:117], v[130:133], v[220:223], 0
	v_mfma_f32_16x16x32_bf16 v[106:109], v[138:141], v[220:223], 0
	v_mfma_f32_16x16x32_bf16 v[94:97], v[130:133], v[228:231], 0
	v_mfma_f32_16x16x32_bf16 v[90:93], v[138:141], v[228:231], 0
	v_mfma_f32_16x16x32_bf16 v[82:85], v[130:133], v[236:239], 0
	v_mfma_f32_16x16x32_bf16 v[74:77], v[138:141], v[236:239], 0
	v_mfma_f32_16x16x32_bf16 v[126:129], v[134:137], v[216:219], v[126:129]
	v_mfma_f32_16x16x32_bf16 v[122:125], v[142:145], v[216:219], v[122:125]
	v_mfma_f32_16x16x32_bf16 v[114:117], v[134:137], v[224:227], v[114:117]
	v_mfma_f32_16x16x32_bf16 v[106:109], v[142:145], v[224:227], v[106:109]
	v_mfma_f32_16x16x32_bf16 v[94:97], v[134:137], v[232:235], v[94:97]
	v_mfma_f32_16x16x32_bf16 v[90:93], v[142:145], v[232:235], v[90:93]
	v_mfma_f32_16x16x32_bf16 v[82:85], v[134:137], v[240:243], v[82:85]
	v_mfma_f32_16x16x32_bf16 v[74:77], v[142:145], v[240:243], v[74:77]
	s_setprio 0
	s_setprio 1
	v_mfma_f32_16x16x32_bf16 v[118:121], v[168:171], v[212:215], 0
	v_mfma_f32_16x16x32_bf16 v[110:113], v[204:207], v[212:215], 0
	v_mfma_f32_16x16x32_bf16 v[102:105], v[168:171], v[220:223], 0
	v_mfma_f32_16x16x32_bf16 v[98:101], v[204:207], v[220:223], 0
	v_mfma_f32_16x16x32_bf16 v[86:89], v[168:171], v[228:231], 0
	v_mfma_f32_16x16x32_bf16 v[78:81], v[204:207], v[228:231], 0
	v_mfma_f32_16x16x32_bf16 v[70:73], v[168:171], v[236:239], 0
	v_mfma_f32_16x16x32_bf16 v[66:69], v[204:207], v[236:239], 0
	v_mfma_f32_16x16x32_bf16 v[118:121], v[200:203], v[216:219], v[118:121]
	v_mfma_f32_16x16x32_bf16 v[110:113], v[208:211], v[216:219], v[110:113]
	v_mfma_f32_16x16x32_bf16 v[102:105], v[200:203], v[224:227], v[102:105]
	v_mfma_f32_16x16x32_bf16 v[98:101], v[208:211], v[224:227], v[98:101]
	v_mfma_f32_16x16x32_bf16 v[86:89], v[200:203], v[232:235], v[86:89]
	v_mfma_f32_16x16x32_bf16 v[78:81], v[208:211], v[232:235], v[78:81]
	v_mfma_f32_16x16x32_bf16 v[70:73], v[200:203], v[240:243], v[70:73]
	v_mfma_f32_16x16x32_bf16 v[66:69], v[208:211], v[240:243], v[66:69]
	s_barrier
	s_setprio 0
	s_add_i32 s64, s64, s30
	v_lshl_add_u64 v[146:147], s[24:25], 0, v[158:159]
	s_mov_b32 m0, s64
	ds_read_b128 v[212:215], v177 offset:16384
	ds_read_b128 v[216:219], v177 offset:17408
	ds_read_b128 v[220:223], v177 offset:18432
	ds_read_b128 v[224:227], v177 offset:19456
	ds_read_b128 v[228:231], v177 offset:20480
	ds_read_b128 v[232:235], v177 offset:21504
	ds_read_b128 v[236:239], v177 offset:22528
	ds_read_b128 v[240:243], v177 offset:23552
	global_load_lds_dwordx4 v[146:147], off
	s_add_i32 m0, s64, 0x2000
	s_add_u32 s64, s24, 0x40000
	v_lshl_add_u64 v[148:149], s[24:25], 0, v[154:155]
	s_addc_u32 s65, s25, 0
	s_add_i32 s66, s66, s30
	global_load_lds_dwordx4 v[148:149], off
	v_lshl_add_u64 v[172:173], s[64:65], 0, v[158:159]
	s_mov_b32 m0, s66
	v_lshl_add_u64 v[180:181], s[26:27], 0, v[156:157]
	global_load_lds_dwordx4 v[172:173], off
	v_lshl_add_u64 v[172:173], s[64:65], 0, v[154:155]
	s_add_i32 m0, s66, 0x2000
	s_nop 0
	global_load_lds_dwordx4 v[172:173], off
	v_lshl_add_u64 v[172:173], s[26:27], 0, v[160:161]
	s_mov_b32 m0, s50
	s_nop 0
	global_load_lds_dwordx4 v[172:173], off
	s_mov_b32 m0, s51
	s_nop 0
	global_load_lds_dwordx4 v[180:181], off
	s_waitcnt vmcnt(24)
	s_waitcnt lgkmcnt(0)
	s_setprio 1
	s_barrier
	v_mfma_f32_16x16x32_bf16 v[62:65], v[130:133], v[212:215], 0
	v_mfma_f32_16x16x32_bf16 v[58:61], v[138:141], v[212:215], 0
	v_mfma_f32_16x16x32_bf16 v[50:53], v[130:133], v[220:223], 0
	v_mfma_f32_16x16x32_bf16 v[42:45], v[138:141], v[220:223], 0
	v_mfma_f32_16x16x32_bf16 v[30:33], v[130:133], v[228:231], 0
	v_mfma_f32_16x16x32_bf16 v[26:29], v[138:141], v[228:231], 0
	v_mfma_f32_16x16x32_bf16 v[18:21], v[130:133], v[236:239], 0
	v_mfma_f32_16x16x32_bf16 v[10:13], v[138:141], v[236:239], 0
	v_mfma_f32_16x16x32_bf16 v[62:65], v[134:137], v[216:219], v[62:65]
	v_mfma_f32_16x16x32_bf16 v[58:61], v[142:145], v[216:219], v[58:61]
	v_mfma_f32_16x16x32_bf16 v[50:53], v[134:137], v[224:227], v[50:53]
	v_mfma_f32_16x16x32_bf16 v[42:45], v[142:145], v[224:227], v[42:45]
	v_mfma_f32_16x16x32_bf16 v[30:33], v[134:137], v[232:235], v[30:33]
	v_mfma_f32_16x16x32_bf16 v[26:29], v[142:145], v[232:235], v[26:29]
	v_mfma_f32_16x16x32_bf16 v[18:21], v[134:137], v[240:243], v[18:21]
	v_mfma_f32_16x16x32_bf16 v[10:13], v[142:145], v[240:243], v[10:13]
	s_setprio 0
	s_setprio 1
	v_mfma_f32_16x16x32_bf16 v[54:57], v[168:171], v[212:215], 0
	v_mfma_f32_16x16x32_bf16 v[46:49], v[204:207], v[212:215], 0
	v_mfma_f32_16x16x32_bf16 v[38:41], v[168:171], v[220:223], 0
	v_mfma_f32_16x16x32_bf16 v[34:37], v[204:207], v[220:223], 0
	v_mfma_f32_16x16x32_bf16 v[22:25], v[168:171], v[228:231], 0
	v_mfma_f32_16x16x32_bf16 v[14:17], v[204:207], v[228:231], 0
	v_mfma_f32_16x16x32_bf16 v[6:9], v[168:171], v[236:239], 0
	v_mfma_f32_16x16x32_bf16 v[2:5], v[204:207], v[236:239], 0
	v_mfma_f32_16x16x32_bf16 v[54:57], v[200:203], v[216:219], v[54:57]
	v_mfma_f32_16x16x32_bf16 v[46:49], v[208:211], v[216:219], v[46:49]
	v_mfma_f32_16x16x32_bf16 v[38:41], v[200:203], v[224:227], v[38:41]
	v_mfma_f32_16x16x32_bf16 v[34:37], v[208:211], v[224:227], v[34:37]
	v_mfma_f32_16x16x32_bf16 v[22:25], v[200:203], v[232:235], v[22:25]
	v_mfma_f32_16x16x32_bf16 v[14:17], v[208:211], v[232:235], v[14:17]
	v_mfma_f32_16x16x32_bf16 v[6:9], v[200:203], v[240:243], v[6:9]
	v_mfma_f32_16x16x32_bf16 v[2:5], v[208:211], v[240:243], v[2:5]
	s_barrier
; #define PG8_STAGE(bufoff, gbase, voff) do { _Pragma("unroll") for (int _i = 0; _i < 2; ++_i) \
;         __builtin_amdgcn_global_load_lds((const unsigned*)((const char*)(gbase) + (voff)[_i]), (PG8_LAS unsigned*)(lds + (bufoff) + ldsw + _i * 8192), 16, 0, 0); } while (0)
; #define PG8_LDA(dst, b, h) do { _Pragma("unroll") for (int m = 0; m < 4; ++m) _Pragma("unroll") for (int k = 0; k < 2; ++k) dst[m][k] = *(const PG8_LAS bf16x8*)(lds + PG8_SA(b, h) + aoff + m * 2048 + k * 1024); } while (0)
; #define PG8_LDB(dst, b, h) do { _Pragma("unroll") for (int n = 0; n < 2; ++n) _Pragma("unroll") for (int k = 0; k < 2; ++k) dst[n][k] = *(const PG8_LAS bf16x8*)(lds + PG8_SB(b, h) + boff + n * 2048 + k * 1024); } while (0)
; #define PG8_MMA(ai, bj, At, Bt) do { __builtin_amdgcn_s_setprio(1); _Pragma("unroll") for (int m = 0; m < 4; ++m) _Pragma("unroll") for (int n = 0; n < 2; ++n) _Pragma("unroll") for (int k = 0; k < 2; ++k) \
;         acc[ai][bj][m][n] = __builtin_amdgcn_mfma_f32_16x16x32_bf16(Bt[n][k], At[m][k], acc[ai][bj][m][n], 0, 0, 0); __builtin_amdgcn_s_setprio(0); } while (0)
; #define PG8_WAIT_V(n) asm volatile("s_waitcnt vmcnt(" #n ")" ::: "memory")
; #define PG8_WAIT_L(n) asm volatile("s_waitcnt lgkmcnt(" #n ")" ::: "memory")
; #define PG8_BAR __builtin_amdgcn_s_barrier()
; #define PG8_SCHED __builtin_amdgcn_sched_barrier(0)
; template <class Epi, class Sched, bool ALIGN_EPI = false, bool SP2 = false>
; __device__ __forceinline__ void gemm_phase(PG8_LAS unsigned char* lds, const Gemm g, const Sched& S, const Epi& E) {
;     ...
;             PG8_WAIT_V(8); PG8_WAIT_L(0); PG8_BAR; PG8_MMA(1, 0, At, B0); PG8_MMA(1, 1, At, B1); PG8_BAR; PG8_SCHED;
;             PG8_LDB(B0, 1, 0); PG8_LDB(B1, 1, 1); PG8_SCHED; PG8_LDA(At, 1, 0); PG8_STAGE(PG8_SA(0, 1), a2 + hstep, voffA);
;             PG8_WAIT_V(8); PG8_WAIT_L(0); PG8_BAR; PG8_MMA(0, 0, At, B0); PG8_MMA(0, 1, At, B1); PG8_BAR; PG8_SCHED;
;             PG8_LDA(At, 1, 1); PG8_STAGE(PG8_SB(1, 0), b3, voffB); PG8_STAGE(PG8_SB(1, 1), b3 + hstep, voffB); PG8_STAGE(PG8_SA(1, 0), a3, voffA);
	s_setprio 0
	s_add_i32 s64, 0, 0x18000
	v_add_u32_e32 v0, s64, v175
	s_add_i32 s65, 0, 0x1c000
	ds_read_b128 v[130:133], v0
	ds_read_b128 v[134:137], v0 offset:1024
	ds_read_b128 v[138:141], v0 offset:2048
	ds_read_b128 v[142:145], v0 offset:3072
	v_add_u32_e32 v0, s65, v175
	ds_read_b128 v[168:171], v0
	ds_read_b128 v[200:203], v0 offset:1024
	ds_read_b128 v[204:207], v0 offset:2048
	ds_read_b128 v[208:211], v0 offset:3072
	s_add_u32 s26, s26, 0x40000
	s_addc_u32 s27, s27, 0
	s_mov_b32 m0, s52
	v_lshl_add_u64 v[244:245], s[26:27], 0, v[160:161]
	ds_read_b128 v[212:215], v177 offset:32768
	ds_read_b128 v[216:219], v177 offset:33792
	ds_read_b128 v[220:223], v177 offset:34816
	ds_read_b128 v[224:227], v177 offset:35840
	ds_read_b128 v[228:231], v177 offset:36864
	ds_read_b128 v[232:235], v177 offset:37888
	ds_read_b128 v[236:239], v177 offset:38912
	ds_read_b128 v[240:243], v177 offset:39936
	global_load_lds_dwordx4 v[244:245], off
	v_lshl_add_u64 v[244:245], s[26:27], 0, v[156:157]
	s_mov_b32 m0, s53
	s_nop 0
	global_load_lds_dwordx4 v[244:245], off
	s_waitcnt vmcnt(8)
	s_waitcnt lgkmcnt(0)
	s_setprio 1
	s_barrier
	v_mfma_f32_16x16x32_bf16 v[126:129], v[130:133], v[212:215], v[126:129]
	v_mfma_f32_16x16x32_bf16 v[122:125], v[138:141], v[212:215], v[122:125]
	v_mfma_f32_16x16x32_bf16 v[114:117], v[130:133], v[220:223], v[114:117]
	v_mfma_f32_16x16x32_bf16 v[106:109], v[138:141], v[220:223], v[106:109]
	v_mfma_f32_16x16x32_bf16 v[94:97], v[130:133], v[228:231], v[94:97]
	v_mfma_f32_16x16x32_bf16 v[90:93], v[138:141], v[228:231], v[90:93]
	v_mfma_f32_16x16x32_bf16 v[82:85], v[130:133], v[236:239], v[82:85]
	v_mfma_f32_16x16x32_bf16 v[74:77], v[138:141], v[236:239], v[74:77]
	v_mfma_f32_16x16x32_bf16 v[126:129], v[134:137], v[216:219], v[126:129]
	v_mfma_f32_16x16x32_bf16 v[122:125], v[142:145], v[216:219], v[122:125]
	v_mfma_f32_16x16x32_bf16 v[114:117], v[134:137], v[224:227], v[114:117]
	v_mfma_f32_16x16x32_bf16 v[106:109], v[142:145], v[224:227], v[106:109]
	v_mfma_f32_16x16x32_bf16 v[94:97], v[134:137], v[232:235], v[94:97]
	v_mfma_f32_16x16x32_bf16 v[90:93], v[142:145], v[232:235], v[90:93]
	v_mfma_f32_16x16x32_bf16 v[82:85], v[134:137], v[240:243], v[82:85]
	v_mfma_f32_16x16x32_bf16 v[74:77], v[142:145], v[240:243], v[74:77]
	s_setprio 0
	s_setprio 1
	v_mfma_f32_16x16x32_bf16 v[118:121], v[168:171], v[212:215], v[118:121]
	v_mfma_f32_16x16x32_bf16 v[110:113], v[204:207], v[212:215], v[110:113]
	v_mfma_f32_16x16x32_bf16 v[102:105], v[168:171], v[220:223], v[102:105]
	v_mfma_f32_16x16x32_bf16 v[98:101], v[204:207], v[220:223], v[98:101]
	v_mfma_f32_16x16x32_bf16 v[86:89], v[168:171], v[228:231], v[86:89]
	v_mfma_f32_16x16x32_bf16 v[78:81], v[204:207], v[228:231], v[78:81]
	v_mfma_f32_16x16x32_bf16 v[70:73], v[168:171], v[236:239], v[70:73]
	v_mfma_f32_16x16x32_bf16 v[66:69], v[204:207], v[236:239], v[66:69]
	v_mfma_f32_16x16x32_bf16 v[118:121], v[200:203], v[216:219], v[118:121]
	v_mfma_f32_16x16x32_bf16 v[110:113], v[208:211], v[216:219], v[110:113]
	v_mfma_f32_16x16x32_bf16 v[102:105], v[200:203], v[224:227], v[102:105]
	v_mfma_f32_16x16x32_bf16 v[98:101], v[208:211], v[224:227], v[98:101]
	v_mfma_f32_16x16x32_bf16 v[86:89], v[200:203], v[232:235], v[86:89]
	v_mfma_f32_16x16x32_bf16 v[78:81], v[208:211], v[232:235], v[78:81]
	v_mfma_f32_16x16x32_bf16 v[70:73], v[200:203], v[240:243], v[70:73]
	v_mfma_f32_16x16x32_bf16 v[66:69], v[208:211], v[240:243], v[66:69]
	s_barrier
	s_setprio 0
	s_add_i32 s26, s64, s30
	v_lshl_add_u64 v[146:147], v[146:147], 0, s[38:39]
	s_mov_b32 m0, s26
	ds_read_b128 v[212:215], v177 offset:49152
	ds_read_b128 v[216:219], v177 offset:50176
	ds_read_b128 v[220:223], v177 offset:51200
	ds_read_b128 v[224:227], v177 offset:52224
	ds_read_b128 v[228:231], v177 offset:53248
	ds_read_b128 v[232:235], v177 offset:54272
	ds_read_b128 v[236:239], v177 offset:55296
	ds_read_b128 v[240:243], v177 offset:56320
	global_load_lds_dwordx4 v[146:147], off
	s_add_i32 m0, s26, 0x2000
	s_add_u32 s24, s24, 0x40080
	v_lshl_add_u64 v[146:147], v[148:149], 0, s[38:39]
	s_addc_u32 s25, s25, 0
	s_add_i32 s26, s65, s30
	global_load_lds_dwordx4 v[146:147], off
	v_lshl_add_u64 v[146:147], s[24:25], 0, v[158:159]
	s_mov_b32 m0, s26
	s_nop 0
	global_load_lds_dwordx4 v[146:147], off
	v_lshl_add_u64 v[146:147], s[24:25], 0, v[154:155]
	s_add_i32 m0, s26, 0x2000
	s_nop 0
	global_load_lds_dwordx4 v[146:147], off
	v_lshl_add_u64 v[146:147], v[172:173], 0, s[38:39]
	s_mov_b32 m0, s55
	s_nop 0
	global_load_lds_dwordx4 v[146:147], off
	v_lshl_add_u64 v[146:147], v[180:181], 0, s[38:39]
	s_mov_b32 m0, s56
	s_nop 0
	global_load_lds_dwordx4 v[146:147], off
	s_waitcnt vmcnt(8)
	s_waitcnt lgkmcnt(0)
	s_setprio 1
	s_barrier
; #define PG8_STAGE(bufoff, gbase, voff) do { _Pragma("unroll") for (int _i = 0; _i < 2; ++_i) \
;         __builtin_amdgcn_global_load_lds((const unsigned*)((const char*)(gbase) + (voff)[_i]), (PG8_LAS unsigned*)(lds + (bufoff) + ldsw + _i * 8192), 16, 0, 0); } while (0)
; #define PG8_LDA(dst, b, h) do { _Pragma("unroll") for (int m = 0; m < 4; ++m) _Pragma("unroll") for (int k = 0; k < 2; ++k) dst[m][k] = *(const PG8_LAS bf16x8*)(lds + PG8_SA(b, h) + aoff + m * 2048 + k * 1024); } while (0)
; #define PG8_LDB(dst, b, h) do { _Pragma("unroll") for (int n = 0; n < 2; ++n) _Pragma("unroll") for (int k = 0; k < 2; ++k) dst[n][k] = *(const PG8_LAS bf16x8*)(lds + PG8_SB(b, h) + boff + n * 2048 + k * 1024); } while (0)
; #define PG8_MMA(ai, bj, At, Bt) do { __builtin_amdgcn_s_setprio(1); _Pragma("unroll") for (int m = 0; m < 4; ++m) _Pragma("unroll") for (int n = 0; n < 2; ++n) _Pragma("unroll") for (int k = 0; k < 2; ++k) \
;         acc[ai][bj][m][n] = __builtin_amdgcn_mfma_f32_16x16x32_bf16(Bt[n][k], At[m][k], acc[ai][bj][m][n], 0, 0, 0); __builtin_amdgcn_s_setprio(0); } while (0)
; #define PG8_WAIT_V(n) asm volatile("s_waitcnt vmcnt(" #n ")" ::: "memory")
; template <class Epi, class Sched, bool ALIGN_EPI = false, bool SP2 = false>
; __device__ __forceinline__ void gemm_phase(PG8_LAS unsigned char* lds, const Gemm g, const Sched& S, const Epi& E) {
;     ...
;             PG8_LDB(B0, 0, 0); PG8_LDB(B1, 0, 1); PG8_SCHED; PG8_LDA(At, 0, 0); PG8_STAGE(PG8_SA(1, 1), a1 + hstep, voffA);
;             PG8_WAIT_V(8); PG8_WAIT_L(0); PG8_BAR; PG8_MMA(0, 0, At, B0); PG8_MMA(0, 1, At, B1); PG8_BAR; PG8_SCHED;
;             PG8_LDA(At, 0, 1); PG8_STAGE(PG8_SB(0, 0), b2, voffB); PG8_STAGE(PG8_SB(0, 1), b2 + hstep, voffB); PG8_STAGE(PG8_SA(0, 0), a2, voffA);
;             PG8_WAIT_V(8); PG8_WAIT_L(0); PG8_BAR; PG8_MMA(1, 0, At, B0); PG8_MMA(1, 1, At, B1); PG8_BAR; PG8_SCHED;
;             PG8_LDB(B0, 1, 0); PG8_LDB(B1, 1, 1); PG8_SCHED; PG8_LDA(At, 1, 0); PG8_STAGE(PG8_SA(0, 1), a2 + hstep, voffA);
;             PG8_WAIT_V(8); PG8_WAIT_L(0); PG8_BAR; PG8_MMA(0, 0, At, B0); PG8_MMA(0, 1, At, B1); PG8_BAR; PG8_SCHED;
;             PG8_LDA(At, 1, 1); PG8_STAGE(PG8_SB(1, 0), b3, voffB); PG8_STAGE(PG8_SB(1, 1), b3 + hstep, voffB); PG8_STAGE(PG8_SA(1, 0), a3, voffA);
;             PG8_WAIT_V(8); PG8_WAIT_L(0); PG8_BAR; PG8_MMA(1, 0, At, B0); PG8_MMA(1, 1, At, B1); PG8_BAR; PG8_SCHED;
	v_mfma_f32_16x16x32_bf16 v[62:65], v[130:133], v[212:215], v[62:65]
	v_mfma_f32_16x16x32_bf16 v[58:61], v[138:141], v[212:215], v[58:61]
	v_mfma_f32_16x16x32_bf16 v[50:53], v[130:133], v[220:223], v[50:53]
	v_mfma_f32_16x16x32_bf16 v[42:45], v[138:141], v[220:223], v[42:45]
	v_mfma_f32_16x16x32_bf16 v[30:33], v[130:133], v[228:231], v[30:33]
	v_mfma_f32_16x16x32_bf16 v[26:29], v[138:141], v[228:231], v[26:29]
	v_mfma_f32_16x16x32_bf16 v[18:21], v[130:133], v[236:239], v[18:21]
	v_mfma_f32_16x16x32_bf16 v[10:13], v[138:141], v[236:239], v[10:13]
	v_mfma_f32_16x16x32_bf16 v[62:65], v[134:137], v[216:219], v[62:65]
	v_mfma_f32_16x16x32_bf16 v[58:61], v[142:145], v[216:219], v[58:61]
	v_mfma_f32_16x16x32_bf16 v[50:53], v[134:137], v[224:227], v[50:53]
	v_mfma_f32_16x16x32_bf16 v[42:45], v[142:145], v[224:227], v[42:45]
	v_mfma_f32_16x16x32_bf16 v[30:33], v[134:137], v[232:235], v[30:33]
	v_mfma_f32_16x16x32_bf16 v[26:29], v[142:145], v[232:235], v[26:29]
	v_mfma_f32_16x16x32_bf16 v[18:21], v[134:137], v[240:243], v[18:21]
	v_mfma_f32_16x16x32_bf16 v[10:13], v[142:145], v[240:243], v[10:13]
	s_setprio 0
	s_setprio 1
	v_mfma_f32_16x16x32_bf16 v[54:57], v[168:171], v[212:215], v[54:57]
	v_mfma_f32_16x16x32_bf16 v[46:49], v[204:207], v[212:215], v[46:49]
	v_mfma_f32_16x16x32_bf16 v[38:41], v[168:171], v[220:223], v[38:41]
	v_mfma_f32_16x16x32_bf16 v[34:37], v[204:207], v[220:223], v[34:37]
	v_mfma_f32_16x16x32_bf16 v[22:25], v[168:171], v[228:231], v[22:25]
	v_mfma_f32_16x16x32_bf16 v[14:17], v[204:207], v[228:231], v[14:17]
	v_mfma_f32_16x16x32_bf16 v[6:9], v[168:171], v[236:239], v[6:9]
	v_mfma_f32_16x16x32_bf16 v[2:5], v[204:207], v[236:239], v[2:5]
	v_mfma_f32_16x16x32_bf16 v[54:57], v[200:203], v[216:219], v[54:57]
	v_mfma_f32_16x16x32_bf16 v[46:49], v[208:211], v[216:219], v[46:49]
	v_mfma_f32_16x16x32_bf16 v[38:41], v[200:203], v[224:227], v[38:41]
	v_mfma_f32_16x16x32_bf16 v[34:37], v[208:211], v[224:227], v[34:37]
	v_mfma_f32_16x16x32_bf16 v[22:25], v[200:203], v[232:235], v[22:25]
	v_mfma_f32_16x16x32_bf16 v[14:17], v[208:211], v[232:235], v[14:17]
	v_mfma_f32_16x16x32_bf16 v[6:9], v[200:203], v[240:243], v[6:9]
	v_mfma_f32_16x16x32_bf16 v[2:5], v[208:211], v[240:243], v[2:5]
	s_barrier
	s_setprio 0
	s_add_i32 s63, s63, 2
	s_add_u32 s22, s22, 0x100
	s_addc_u32 s23, s23, 0
	s_add_u32 s61, s61, 0x100
	s_addc_u32 s62, s62, 0
.LBB0_558:
	s_add_u32 s24, s22, 0xfffc0080
	s_addc_u32 s25, s23, -1
	s_add_i32 s64, 0, 0x10000
	s_cmp_eq_u32 s63, 12
	s_cselect_b32 s27, s15, s25
	s_cselect_b32 s26, s21, s24
	v_add_u32_e32 v0, s64, v175
	s_cselect_b32 s25, s13, s62
	s_cselect_b32 s24, s60, s61
	s_add_i32 s66, 0, 0x14000
	ds_read_b128 v[130:133], v0
	ds_read_b128 v[134:137], v0 offset:1024
	ds_read_b128 v[138:141], v0 offset:2048
	ds_read_b128 v[142:145], v0 offset:3072
	v_add_u32_e32 v0, s66, v175
	ds_read_b128 v[168:171], v0
	ds_read_b128 v[200:203], v0 offset:1024
	ds_read_b128 v[204:207], v0 offset:2048
	ds_read_b128 v[208:211], v0 offset:3072
	v_lshl_add_u64 v[146:147], s[22:23], 0, v[164:165]
	s_add_i32 m0, s50, 0xc000
	ds_read_b128 v[212:215], v177
	ds_read_b128 v[216:219], v177 offset:1024
	ds_read_b128 v[220:223], v177 offset:2048
	ds_read_b128 v[224:227], v177 offset:3072
	ds_read_b128 v[228:231], v177 offset:4096
	ds_read_b128 v[232:235], v177 offset:5120
	ds_read_b128 v[236:239], v177 offset:6144
	ds_read_b128 v[240:243], v177 offset:7168
	global_load_lds_dwordx4 v[146:147], off
	v_lshl_add_u64 v[146:147], s[22:23], 0, v[166:167]
	s_add_i32 m0, s50, 0xe000
	s_nop 0
	global_load_lds_dwordx4 v[146:147], off
	s_waitcnt vmcnt(8)
	s_waitcnt lgkmcnt(0)
	s_setprio 1
	s_barrier
	v_mfma_f32_16x16x32_bf16 v[126:129], v[130:133], v[212:215], v[126:129]
	v_mfma_f32_16x16x32_bf16 v[122:125], v[138:141], v[212:215], v[122:125]
	v_mfma_f32_16x16x32_bf16 v[114:117], v[130:133], v[220:223], v[114:117]
	v_mfma_f32_16x16x32_bf16 v[106:109], v[138:141], v[220:223], v[106:109]
	v_mfma_f32_16x16x32_bf16 v[94:97], v[130:133], v[228:231], v[94:97]
	v_mfma_f32_16x16x32_bf16 v[90:93], v[138:141], v[228:231], v[90:93]
	v_mfma_f32_16x16x32_bf16 v[82:85], v[130:133], v[236:239], v[82:85]
	v_mfma_f32_16x16x32_bf16 v[74:77], v[138:141], v[236:239], v[74:77]
	v_mfma_f32_16x16x32_bf16 v[126:129], v[134:137], v[216:219], v[126:129]
	v_mfma_f32_16x16x32_bf16 v[122:125], v[142:145], v[216:219], v[122:125]
	v_mfma_f32_16x16x32_bf16 v[114:117], v[134:137], v[224:227], v[114:117]
	v_mfma_f32_16x16x32_bf16 v[106:109], v[142:145], v[224:227], v[106:109]
	v_mfma_f32_16x16x32_bf16 v[94:97], v[134:137], v[232:235], v[94:97]
	v_mfma_f32_16x16x32_bf16 v[90:93], v[142:145], v[232:235], v[90:93]
	v_mfma_f32_16x16x32_bf16 v[82:85], v[134:137], v[240:243], v[82:85]
	v_mfma_f32_16x16x32_bf16 v[74:77], v[142:145], v[240:243], v[74:77]
	s_setprio 0
	s_setprio 1
	v_mfma_f32_16x16x32_bf16 v[118:121], v[168:171], v[212:215], v[118:121]
	v_mfma_f32_16x16x32_bf16 v[110:113], v[204:207], v[212:215], v[110:113]
	v_mfma_f32_16x16x32_bf16 v[102:105], v[168:171], v[220:223], v[102:105]
	v_mfma_f32_16x16x32_bf16 v[98:101], v[204:207], v[220:223], v[98:101]
	v_mfma_f32_16x16x32_bf16 v[86:89], v[168:171], v[228:231], v[86:89]
	v_mfma_f32_16x16x32_bf16 v[78:81], v[204:207], v[228:231], v[78:81]
	v_mfma_f32_16x16x32_bf16 v[70:73], v[168:171], v[236:239], v[70:73]
	v_mfma_f32_16x16x32_bf16 v[66:69], v[204:207], v[236:239], v[66:69]
	v_mfma_f32_16x16x32_bf16 v[118:121], v[200:203], v[216:219], v[118:121]
	v_mfma_f32_16x16x32_bf16 v[110:113], v[208:211], v[216:219], v[110:113]
	v_mfma_f32_16x16x32_bf16 v[102:105], v[200:203], v[224:227], v[102:105]
	v_mfma_f32_16x16x32_bf16 v[98:101], v[208:211], v[224:227], v[98:101]
	v_mfma_f32_16x16x32_bf16 v[86:89], v[200:203], v[232:235], v[86:89]
	v_mfma_f32_16x16x32_bf16 v[78:81], v[208:211], v[232:235], v[78:81]
	v_mfma_f32_16x16x32_bf16 v[70:73], v[200:203], v[240:243], v[70:73]
	v_mfma_f32_16x16x32_bf16 v[66:69], v[208:211], v[240:243], v[66:69]
	s_barrier
; #define PG8_STAGE(bufoff, gbase, voff) do { _Pragma("unroll") for (int _i = 0; _i < 2; ++_i) \
;         __builtin_amdgcn_global_load_lds((const unsigned*)((const char*)(gbase) + (voff)[_i]), (PG8_LAS unsigned*)(lds + (bufoff) + ldsw + _i * 8192), 16, 0, 0); } while (0)
; #define PG8_LDA(dst, b, h) do { _Pragma("unroll") for (int m = 0; m < 4; ++m) _Pragma("unroll") for (int k = 0; k < 2; ++k) dst[m][k] = *(const PG8_LAS bf16x8*)(lds + PG8_SA(b, h) + aoff + m * 2048 + k * 1024); } while (0)
; #define PG8_LDB(dst, b, h) do { _Pragma("unroll") for (int n = 0; n < 2; ++n) _Pragma("unroll") for (int k = 0; k < 2; ++k) dst[n][k] = *(const PG8_LAS bf16x8*)(lds + PG8_SB(b, h) + boff + n * 2048 + k * 1024); } while (0)
; #define PG8_MMA(ai, bj, At, Bt) do { __builtin_amdgcn_s_setprio(1); _Pragma("unroll") for (int m = 0; m < 4; ++m) _Pragma("unroll") for (int n = 0; n < 2; ++n) _Pragma("unroll") for (int k = 0; k < 2; ++k) \
;         acc[ai][bj][m][n] = __builtin_amdgcn_mfma_f32_16x16x32_bf16(Bt[n][k], At[m][k], acc[ai][bj][m][n], 0, 0, 0); __builtin_amdgcn_s_setprio(0); } while (0)
; #define PG8_WAIT_V(n) asm volatile("s_waitcnt vmcnt(" #n ")" ::: "memory")
; #define PG8_WAIT_L(n) asm volatile("s_waitcnt lgkmcnt(" #n ")" ::: "memory")
; #define PG8_BAR __builtin_amdgcn_s_barrier()
; #define PG8_SCHED __builtin_amdgcn_sched_barrier(0)
; template <class Epi, class Sched, bool ALIGN_EPI = false, bool SP2 = false>
; __device__ __forceinline__ void gemm_phase(PG8_LAS unsigned char* lds, const Gemm g, const Sched& S, const Epi& E) {
;     ...
;             PG8_LDA(At, 0, 1); PG8_STAGE(PG8_SB(0, 0), b2, voffB); PG8_STAGE(PG8_SB(0, 1), b2 + hstep, voffB); PG8_STAGE(PG8_SA(0, 0), a2, voffA);
;             PG8_WAIT_V(8); PG8_WAIT_L(0); PG8_BAR; PG8_MMA(1, 0, At, B0); PG8_MMA(1, 1, At, B1); PG8_BAR; PG8_SCHED;
;             PG8_LDB(B0, 1, 0); PG8_LDB(B1, 1, 1); PG8_SCHED; PG8_LDA(At, 1, 0); PG8_STAGE(PG8_SA(0, 1), a2 + hstep, voffA);
;             PG8_WAIT_V(8); PG8_WAIT_L(0); PG8_BAR; PG8_MMA(0, 0, At, B0); PG8_MMA(0, 1, At, B1); PG8_BAR; PG8_SCHED;
;             PG8_LDA(At, 1, 1); PG8_STAGE(PG8_SB(1, 0), b3, voffB); PG8_STAGE(PG8_SB(1, 1), b3 + hstep, voffB); PG8_STAGE(PG8_SA(1, 0), a3, voffA);
	s_setprio 0
	s_add_i32 s64, s64, s30
	v_lshl_add_u64 v[146:147], s[24:25], 0, v[158:159]
	s_mov_b32 m0, s64
	ds_read_b128 v[212:215], v177 offset:16384
	ds_read_b128 v[216:219], v177 offset:17408
	ds_read_b128 v[220:223], v177 offset:18432
	ds_read_b128 v[224:227], v177 offset:19456
	ds_read_b128 v[228:231], v177 offset:20480
	ds_read_b128 v[232:235], v177 offset:21504
	ds_read_b128 v[236:239], v177 offset:22528
	ds_read_b128 v[240:243], v177 offset:23552
	global_load_lds_dwordx4 v[146:147], off
	s_add_i32 m0, s64, 0x2000
	s_add_u32 s64, s24, 0x40000
	v_lshl_add_u64 v[148:149], s[24:25], 0, v[154:155]
	s_addc_u32 s65, s25, 0
	s_add_i32 s66, s66, s30
	global_load_lds_dwordx4 v[148:149], off
	v_lshl_add_u64 v[172:173], s[64:65], 0, v[158:159]
	s_mov_b32 m0, s66
	v_lshl_add_u64 v[180:181], s[26:27], 0, v[156:157]
	global_load_lds_dwordx4 v[172:173], off
	v_lshl_add_u64 v[172:173], s[64:65], 0, v[154:155]
	s_add_i32 m0, s66, 0x2000
	s_nop 0
	global_load_lds_dwordx4 v[172:173], off
	v_lshl_add_u64 v[172:173], s[26:27], 0, v[160:161]
	s_mov_b32 m0, s50
	s_nop 0
	global_load_lds_dwordx4 v[172:173], off
	s_mov_b32 m0, s51
	s_nop 0
	global_load_lds_dwordx4 v[180:181], off
	s_waitcnt vmcnt(8)
	s_waitcnt lgkmcnt(0)
	s_setprio 1
	s_barrier
	v_mfma_f32_16x16x32_bf16 v[62:65], v[130:133], v[212:215], v[62:65]
	v_mfma_f32_16x16x32_bf16 v[58:61], v[138:141], v[212:215], v[58:61]
	v_mfma_f32_16x16x32_bf16 v[50:53], v[130:133], v[220:223], v[50:53]
	v_mfma_f32_16x16x32_bf16 v[42:45], v[138:141], v[220:223], v[42:45]
	v_mfma_f32_16x16x32_bf16 v[30:33], v[130:133], v[228:231], v[30:33]
	v_mfma_f32_16x16x32_bf16 v[26:29], v[138:141], v[228:231], v[26:29]
	v_mfma_f32_16x16x32_bf16 v[18:21], v[130:133], v[236:239], v[18:21]
	v_mfma_f32_16x16x32_bf16 v[10:13], v[138:141], v[236:239], v[10:13]
	v_mfma_f32_16x16x32_bf16 v[62:65], v[134:137], v[216:219], v[62:65]
	v_mfma_f32_16x16x32_bf16 v[58:61], v[142:145], v[216:219], v[58:61]
	v_mfma_f32_16x16x32_bf16 v[50:53], v[134:137], v[224:227], v[50:53]
	v_mfma_f32_16x16x32_bf16 v[42:45], v[142:145], v[224:227], v[42:45]
	v_mfma_f32_16x16x32_bf16 v[30:33], v[134:137], v[232:235], v[30:33]
	v_mfma_f32_16x16x32_bf16 v[26:29], v[142:145], v[232:235], v[26:29]
	v_mfma_f32_16x16x32_bf16 v[18:21], v[134:137], v[240:243], v[18:21]
	v_mfma_f32_16x16x32_bf16 v[10:13], v[142:145], v[240:243], v[10:13]
	s_setprio 0
	s_setprio 1
	v_mfma_f32_16x16x32_bf16 v[54:57], v[168:171], v[212:215], v[54:57]
	v_mfma_f32_16x16x32_bf16 v[46:49], v[204:207], v[212:215], v[46:49]
	v_mfma_f32_16x16x32_bf16 v[38:41], v[168:171], v[220:223], v[38:41]
	v_mfma_f32_16x16x32_bf16 v[34:37], v[204:207], v[220:223], v[34:37]
	v_mfma_f32_16x16x32_bf16 v[22:25], v[168:171], v[228:231], v[22:25]
	v_mfma_f32_16x16x32_bf16 v[14:17], v[204:207], v[228:231], v[14:17]
	v_mfma_f32_16x16x32_bf16 v[6:9], v[168:171], v[236:239], v[6:9]
	v_mfma_f32_16x16x32_bf16 v[2:5], v[204:207], v[236:239], v[2:5]
	v_mfma_f32_16x16x32_bf16 v[54:57], v[200:203], v[216:219], v[54:57]
	v_mfma_f32_16x16x32_bf16 v[46:49], v[208:211], v[216:219], v[46:49]
	v_mfma_f32_16x16x32_bf16 v[38:41], v[200:203], v[224:227], v[38:41]
	v_mfma_f32_16x16x32_bf16 v[34:37], v[208:211], v[224:227], v[34:37]
	v_mfma_f32_16x16x32_bf16 v[22:25], v[200:203], v[232:235], v[22:25]
	v_mfma_f32_16x16x32_bf16 v[14:17], v[208:211], v[232:235], v[14:17]
	v_mfma_f32_16x16x32_bf16 v[6:9], v[200:203], v[240:243], v[6:9]
	v_mfma_f32_16x16x32_bf16 v[2:5], v[208:211], v[240:243], v[2:5]
	s_barrier
	s_setprio 0
	s_add_i32 s64, 0, 0x18000
	v_add_u32_e32 v0, s64, v175
	s_add_i32 s65, 0, 0x1c000
	ds_read_b128 v[130:133], v0
	ds_read_b128 v[134:137], v0 offset:1024
	ds_read_b128 v[138:141], v0 offset:2048
	ds_read_b128 v[142:145], v0 offset:3072
	v_add_u32_e32 v0, s65, v175
	ds_read_b128 v[168:171], v0
	ds_read_b128 v[200:203], v0 offset:1024
	ds_read_b128 v[204:207], v0 offset:2048
	ds_read_b128 v[208:211], v0 offset:3072
	s_add_u32 s26, s26, 0x40000
	s_addc_u32 s27, s27, 0
	s_mov_b32 m0, s52
	v_lshl_add_u64 v[244:245], s[26:27], 0, v[160:161]
	ds_read_b128 v[212:215], v177 offset:32768
	ds_read_b128 v[216:219], v177 offset:33792
	ds_read_b128 v[220:223], v177 offset:34816
	ds_read_b128 v[224:227], v177 offset:35840
	ds_read_b128 v[228:231], v177 offset:36864
	ds_read_b128 v[232:235], v177 offset:37888
	ds_read_b128 v[236:239], v177 offset:38912
	ds_read_b128 v[240:243], v177 offset:39936
	global_load_lds_dwordx4 v[244:245], off
	v_lshl_add_u64 v[244:245], s[26:27], 0, v[156:157]
	s_mov_b32 m0, s53
	s_nop 0
	global_load_lds_dwordx4 v[244:245], off
	s_waitcnt vmcnt(8)
	s_waitcnt lgkmcnt(0)
	s_setprio 1
	s_barrier
; #define PG8_STAGE(bufoff, gbase, voff) do { _Pragma("unroll") for (int _i = 0; _i < 2; ++_i) \
;         __builtin_amdgcn_global_load_lds((const unsigned*)((const char*)(gbase) + (voff)[_i]), (PG8_LAS unsigned*)(lds + (bufoff) + ldsw + _i * 8192), 16, 0, 0); } while (0)
; #define PG8_LDA(dst, b, h) do { _Pragma("unroll") for (int m = 0; m < 4; ++m) _Pragma("unroll") for (int k = 0; k < 2; ++k) dst[m][k] = *(const PG8_LAS bf16x8*)(lds + PG8_SA(b, h) + aoff + m * 2048 + k * 1024); } while (0)
; #define PG8_LDB(dst, b, h) do { _Pragma("unroll") for (int n = 0; n < 2; ++n) _Pragma("unroll") for (int k = 0; k < 2; ++k) dst[n][k] = *(const PG8_LAS bf16x8*)(lds + PG8_SB(b, h) + boff + n * 2048 + k * 1024); } while (0)
; #define PG8_MMA(ai, bj, At, Bt) do { __builtin_amdgcn_s_setprio(1); _Pragma("unroll") for (int m = 0; m < 4; ++m) _Pragma("unroll") for (int n = 0; n < 2; ++n) _Pragma("unroll") for (int k = 0; k < 2; ++k) \
;         acc[ai][bj][m][n] = __builtin_amdgcn_mfma_f32_16x16x32_bf16(Bt[n][k], At[m][k], acc[ai][bj][m][n], 0, 0, 0); __builtin_amdgcn_s_setprio(0); } while (0)
; #define PG8_WAIT_V(n) asm volatile("s_waitcnt vmcnt(" #n ")" ::: "memory")
; #define PG8_WAIT_L(n) asm volatile("s_waitcnt lgkmcnt(" #n ")" ::: "memory")
; #define PG8_BAR __builtin_amdgcn_s_barrier()
; #define PG8_SCHED __builtin_amdgcn_sched_barrier(0)
; template <class Epi, class Sched, bool ALIGN_EPI = false, bool SP2 = false>
; __device__ __forceinline__ void gemm_phase(PG8_LAS unsigned char* lds, const Gemm g, const Sched& S, const Epi& E) {
;     ...
;             PG8_LDB(B0, 1, 0); PG8_LDB(B1, 1, 1); PG8_SCHED; PG8_LDA(At, 1, 0); PG8_STAGE(PG8_SA(0, 1), a2 + hstep, voffA);
;             PG8_WAIT_V(8); PG8_WAIT_L(0); PG8_BAR; PG8_MMA(0, 0, At, B0); PG8_MMA(0, 1, At, B1); PG8_BAR; PG8_SCHED;
;             PG8_LDA(At, 1, 1); PG8_STAGE(PG8_SB(1, 0), b3, voffB); PG8_STAGE(PG8_SB(1, 1), b3 + hstep, voffB); PG8_STAGE(PG8_SA(1, 0), a3, voffA);
;             PG8_WAIT_V(8); PG8_WAIT_L(0); PG8_BAR; PG8_MMA(1, 0, At, B0); PG8_MMA(1, 1, At, B1); PG8_BAR; PG8_SCHED;
	v_mfma_f32_16x16x32_bf16 v[126:129], v[130:133], v[212:215], v[126:129]
	v_mfma_f32_16x16x32_bf16 v[122:125], v[138:141], v[212:215], v[122:125]
	v_mfma_f32_16x16x32_bf16 v[114:117], v[130:133], v[220:223], v[114:117]
	v_mfma_f32_16x16x32_bf16 v[106:109], v[138:141], v[220:223], v[106:109]
	v_mfma_f32_16x16x32_bf16 v[94:97], v[130:133], v[228:231], v[94:97]
	v_mfma_f32_16x16x32_bf16 v[90:93], v[138:141], v[228:231], v[90:93]
	v_mfma_f32_16x16x32_bf16 v[82:85], v[130:133], v[236:239], v[82:85]
	v_mfma_f32_16x16x32_bf16 v[74:77], v[138:141], v[236:239], v[74:77]
	v_mfma_f32_16x16x32_bf16 v[126:129], v[134:137], v[216:219], v[126:129]
	v_mfma_f32_16x16x32_bf16 v[122:125], v[142:145], v[216:219], v[122:125]
	v_mfma_f32_16x16x32_bf16 v[114:117], v[134:137], v[224:227], v[114:117]
	v_mfma_f32_16x16x32_bf16 v[106:109], v[142:145], v[224:227], v[106:109]
	v_mfma_f32_16x16x32_bf16 v[94:97], v[134:137], v[232:235], v[94:97]
	v_mfma_f32_16x16x32_bf16 v[90:93], v[142:145], v[232:235], v[90:93]
	v_mfma_f32_16x16x32_bf16 v[82:85], v[134:137], v[240:243], v[82:85]
	v_mfma_f32_16x16x32_bf16 v[74:77], v[142:145], v[240:243], v[74:77]
	s_setprio 0
	s_setprio 1
	v_mfma_f32_16x16x32_bf16 v[118:121], v[168:171], v[212:215], v[118:121]
	v_mfma_f32_16x16x32_bf16 v[110:113], v[204:207], v[212:215], v[110:113]
	v_mfma_f32_16x16x32_bf16 v[102:105], v[168:171], v[220:223], v[102:105]
	v_mfma_f32_16x16x32_bf16 v[98:101], v[204:207], v[220:223], v[98:101]
	v_mfma_f32_16x16x32_bf16 v[86:89], v[168:171], v[228:231], v[86:89]
	v_mfma_f32_16x16x32_bf16 v[78:81], v[204:207], v[228:231], v[78:81]
	v_mfma_f32_16x16x32_bf16 v[70:73], v[168:171], v[236:239], v[70:73]
	v_mfma_f32_16x16x32_bf16 v[66:69], v[204:207], v[236:239], v[66:69]
	v_mfma_f32_16x16x32_bf16 v[118:121], v[200:203], v[216:219], v[118:121]
	v_mfma_f32_16x16x32_bf16 v[110:113], v[208:211], v[216:219], v[110:113]
	v_mfma_f32_16x16x32_bf16 v[102:105], v[200:203], v[224:227], v[102:105]
	v_mfma_f32_16x16x32_bf16 v[98:101], v[208:211], v[224:227], v[98:101]
	v_mfma_f32_16x16x32_bf16 v[86:89], v[200:203], v[232:235], v[86:89]
	v_mfma_f32_16x16x32_bf16 v[78:81], v[208:211], v[232:235], v[78:81]
	v_mfma_f32_16x16x32_bf16 v[70:73], v[200:203], v[240:243], v[70:73]
	v_mfma_f32_16x16x32_bf16 v[66:69], v[208:211], v[240:243], v[66:69]
	s_barrier
	s_setprio 0
	s_add_i32 s26, s64, s30
	v_lshl_add_u64 v[146:147], v[146:147], 0, s[38:39]
	s_mov_b32 m0, s26
	ds_read_b128 v[212:215], v177 offset:49152
	ds_read_b128 v[216:219], v177 offset:50176
	ds_read_b128 v[220:223], v177 offset:51200
	ds_read_b128 v[224:227], v177 offset:52224
	ds_read_b128 v[228:231], v177 offset:53248
	ds_read_b128 v[232:235], v177 offset:54272
	ds_read_b128 v[236:239], v177 offset:55296
	ds_read_b128 v[240:243], v177 offset:56320
	global_load_lds_dwordx4 v[146:147], off
	s_add_i32 m0, s26, 0x2000
	s_add_u32 s24, s24, 0x40080
	v_lshl_add_u64 v[146:147], v[148:149], 0, s[38:39]
	s_addc_u32 s25, s25, 0
	s_add_i32 s26, s65, s30
	global_load_lds_dwordx4 v[146:147], off
	v_lshl_add_u64 v[146:147], s[24:25], 0, v[158:159]
	s_mov_b32 m0, s26
	s_nop 0
	global_load_lds_dwordx4 v[146:147], off
	v_lshl_add_u64 v[146:147], s[24:25], 0, v[154:155]
	s_add_i32 m0, s26, 0x2000
	s_nop 0
	global_load_lds_dwordx4 v[146:147], off
	v_lshl_add_u64 v[146:147], v[172:173], 0, s[38:39]
	s_mov_b32 m0, s55
	s_nop 0
	global_load_lds_dwordx4 v[146:147], off
	v_lshl_add_u64 v[146:147], v[180:181], 0, s[38:39]
	s_mov_b32 m0, s56
	s_nop 0
	global_load_lds_dwordx4 v[146:147], off
	s_waitcnt vmcnt(8)
	s_waitcnt lgkmcnt(0)
	s_setprio 1
	s_barrier
	v_mfma_f32_16x16x32_bf16 v[62:65], v[130:133], v[212:215], v[62:65]
	v_mfma_f32_16x16x32_bf16 v[58:61], v[138:141], v[212:215], v[58:61]
	v_mfma_f32_16x16x32_bf16 v[50:53], v[130:133], v[220:223], v[50:53]
	v_mfma_f32_16x16x32_bf16 v[42:45], v[138:141], v[220:223], v[42:45]
	v_mfma_f32_16x16x32_bf16 v[30:33], v[130:133], v[228:231], v[30:33]
	v_mfma_f32_16x16x32_bf16 v[26:29], v[138:141], v[228:231], v[26:29]
	v_mfma_f32_16x16x32_bf16 v[18:21], v[130:133], v[236:239], v[18:21]
	v_mfma_f32_16x16x32_bf16 v[10:13], v[138:141], v[236:239], v[10:13]
	v_mfma_f32_16x16x32_bf16 v[62:65], v[134:137], v[216:219], v[62:65]
	v_mfma_f32_16x16x32_bf16 v[58:61], v[142:145], v[216:219], v[58:61]
	v_mfma_f32_16x16x32_bf16 v[50:53], v[134:137], v[224:227], v[50:53]
	v_mfma_f32_16x16x32_bf16 v[42:45], v[142:145], v[224:227], v[42:45]
	v_mfma_f32_16x16x32_bf16 v[30:33], v[134:137], v[232:235], v[30:33]
	v_mfma_f32_16x16x32_bf16 v[26:29], v[142:145], v[232:235], v[26:29]
	v_mfma_f32_16x16x32_bf16 v[18:21], v[134:137], v[240:243], v[18:21]
	v_mfma_f32_16x16x32_bf16 v[10:13], v[142:145], v[240:243], v[10:13]
	s_setprio 0
	s_setprio 1
	v_mfma_f32_16x16x32_bf16 v[54:57], v[168:171], v[212:215], v[54:57]
	v_mfma_f32_16x16x32_bf16 v[46:49], v[204:207], v[212:215], v[46:49]
	v_mfma_f32_16x16x32_bf16 v[38:41], v[168:171], v[220:223], v[38:41]
	v_mfma_f32_16x16x32_bf16 v[34:37], v[204:207], v[220:223], v[34:37]
	v_mfma_f32_16x16x32_bf16 v[22:25], v[168:171], v[228:231], v[22:25]
	v_mfma_f32_16x16x32_bf16 v[14:17], v[204:207], v[228:231], v[14:17]
	v_mfma_f32_16x16x32_bf16 v[6:9], v[168:171], v[236:239], v[6:9]
	v_mfma_f32_16x16x32_bf16 v[2:5], v[204:207], v[236:239], v[2:5]
	v_mfma_f32_16x16x32_bf16 v[54:57], v[200:203], v[216:219], v[54:57]
	v_mfma_f32_16x16x32_bf16 v[46:49], v[208:211], v[216:219], v[46:49]
	v_mfma_f32_16x16x32_bf16 v[38:41], v[200:203], v[224:227], v[38:41]
	v_mfma_f32_16x16x32_bf16 v[34:37], v[208:211], v[224:227], v[34:37]
	v_mfma_f32_16x16x32_bf16 v[22:25], v[200:203], v[232:235], v[22:25]
	v_mfma_f32_16x16x32_bf16 v[14:17], v[208:211], v[232:235], v[14:17]
	v_mfma_f32_16x16x32_bf16 v[6:9], v[200:203], v[240:243], v[6:9]
	v_mfma_f32_16x16x32_bf16 v[2:5], v[208:211], v[240:243], v[2:5]
	s_barrier
	s_setprio 0
	s_add_i32 s63, s63, 2
	s_add_u32 s22, s22, 0x100
	s_addc_u32 s23, s23, 0
	s_add_u32 s61, s61, 0x100
	s_addc_u32 s62, s62, 0
	s_cmp_gt_u32 s63, 13
	s_cbranch_scc0 .LBB0_558
	s_and_b64 vcc, exec, s[8:9]
	s_cbranch_vccnz .LBB0_563
	v_lshl_add_u32 v168, s20, 8, v174
	s_cmp_ge_i32 s59, s54
	s_mov_b64 s[20:21], -1
	s_cbranch_scc1 .LBB0_564

; #define PG8_STAGE(bufoff, gbase, voff) do { _Pragma("unroll") for (int _i = 0; _i < 2; ++_i) \
;         __builtin_amdgcn_global_load_lds((const unsigned*)((const char*)(gbase) + (voff)[_i]), (PG8_LAS unsigned*)(lds + (bufoff) + ldsw + _i * 8192), 16, 0, 0); } while (0)
; #define PG8_LDA(dst, b, h) do { _Pragma("unroll") for (int m = 0; m < 4; ++m) _Pragma("unroll") for (int k = 0; k < 2; ++k) dst[m][k] = *(const PG8_LAS bf16x8*)(lds + PG8_SA(b, h) + aoff + m * 2048 + k * 1024); } while (0)
; #define PG8_LDB(dst, b, h) do { _Pragma("unroll") for (int n = 0; n < 2; ++n) _Pragma("unroll") for (int k = 0; k < 2; ++k) dst[n][k] = *(const PG8_LAS bf16x8*)(lds + PG8_SB(b, h) + boff + n * 2048 + k * 1024); } while (0)
; #define PG8_WAIT_V(n) asm volatile("s_waitcnt vmcnt(" #n ")" ::: "memory")
; #define PG8_WAIT_L(n) asm volatile("s_waitcnt lgkmcnt(" #n ")" ::: "memory")
; #define PG8_BAR __builtin_amdgcn_s_barrier()
; #define PG8_SCHED __builtin_amdgcn_sched_barrier(0)
; template <class Epi, class Sched, bool ALIGN_EPI = false, bool SP2 = false>
; __device__ __forceinline__ void gemm_phase(PG8_LAS unsigned char* lds, const Gemm g, const Sched& S, const Epi& E) {
;     ...
;         const bool has_next = S.next(ui + 1, nxt);
;         const char* nA = has_next ? (const char*)g.A + (size_t)nxt.pm * tstep : cA; const char* nB = has_next ? (const char*)g.Bt + (size_t)nxt.pn * tstep : cB;
;         for (int t = 0; t < nt; t += 2) {
;             const bool last = (t == nt - 2);
;             const char* a1 = cA + (size_t)(t + 1) * kstep;
;             const char* a2 = last ? nA : cA + (size_t)(t + 2) * kstep; const char* b2 = last ? nB : cB + (size_t)(t + 2) * kstep;
;             const char* a3 = a2 + kstep; const char* b3 = b2 + kstep;
;             if (last && has_next) S.a_ready(nxt);
;             if constexpr (SP2) {
;             PG8_LDB(B0, 0, 0); PG8_LDB(B1, 0, 1); PG8_SCHED; PG8_LDA(At, 0, 0); PG8_STAGE(PG8_SA(1, 1), a1 + hstep, voffA);
;             PG8_WAIT_V(8); PG8_WAIT_L(0); PG8_BAR; PG8_MMA(0, 0, At, B0); PG8_MMA(0, 1, At, B1); PG8_BAR; PG8_SCHED;
;             PG8_LDA(At, 0, 1); PG8_STAGE(PG8_SB(0, 0), b2, voffB); PG8_STAGE(PG8_SB(0, 1), b2 + hstep, voffB); PG8_STAGE(PG8_SA(0, 0), a2, voffA);
;             PG8_WAIT_V(8); PG8_WAIT_L(0); PG8_BAR; PG8_MMA(1, 0, At, B0); PG8_MMA(1, 1, At, B1); PG8_BAR; PG8_SCHED;
.LBB0_1089:
	s_ashr_i32 s11, s10, 31
	s_lshl_b64 s[12:13], s[10:11], 19
	s_add_u32 s12, s90, s12
	s_addc_u32 s13, s91, s13
	s_and_b64 s[14:15], s[4:5], exec
	s_cselect_b32 s11, s13, s17
	s_cselect_b32 s45, s12, s16
	s_ashr_i32 s9, s8, 31
	s_lshl_b64 s[14:15], s[8:9], 19
	s_add_u32 s14, s22, s14
	s_addc_u32 s15, s23, s15
	s_and_b64 s[20:21], s[4:5], exec
	s_cselect_b32 s9, s15, s19
	s_cselect_b32 s46, s14, s18
	s_add_u32 s16, s16, 0x40080
	s_addc_u32 s17, s17, 0
	s_add_u32 s47, s18, 0x100
	s_addc_u32 s48, s19, 0
	s_mov_b32 s49, -2
	s_add_u32 s18, s16, 0xfffc0080
	s_addc_u32 s19, s17, -1
	s_add_i32 s50, 0, 0x10000
	s_cmp_eq_u32 s49, 12
	s_cselect_b32 s21, s11, s19
	s_cselect_b32 s20, s45, s18
	s_cselect_b32 s19, s9, s48
	s_cselect_b32 s18, s46, s47
	s_add_i32 s52, 0, 0x14000
	v_lshl_add_u64 v[148:149], s[16:17], 0, v[136:137]
	s_add_i32 m0, s25, 0xc000
	global_load_lds_dwordx4 v[148:149], off
	v_lshl_add_u64 v[148:149], s[16:17], 0, v[138:139]
	s_add_i32 m0, s25, 0xe000
	s_nop 0
	global_load_lds_dwordx4 v[148:149], off
	s_waitcnt vmcnt(20)
	s_waitcnt lgkmcnt(0)
	s_setprio 1
	s_barrier
	v_mfma_f32_16x16x32_bf16 v[126:129], v[140:143], v[200:203], 0
	v_mfma_f32_16x16x32_bf16 v[122:125], v[154:157], v[200:203], 0
	v_mfma_f32_16x16x32_bf16 v[118:121], v[140:143], v[208:211], 0
	v_mfma_f32_16x16x32_bf16 v[114:117], v[154:157], v[208:211], 0
	v_mfma_f32_16x16x32_bf16 v[110:113], v[140:143], v[216:219], 0
	v_mfma_f32_16x16x32_bf16 v[106:109], v[154:157], v[216:219], 0
	v_mfma_f32_16x16x32_bf16 v[102:105], v[140:143], v[224:227], 0
	v_mfma_f32_16x16x32_bf16 v[98:101], v[154:157], v[224:227], 0
	v_mfma_f32_16x16x32_bf16 v[126:129], v[144:147], v[204:207], v[126:129]
	v_mfma_f32_16x16x32_bf16 v[122:125], v[158:161], v[204:207], v[122:125]
	v_mfma_f32_16x16x32_bf16 v[118:121], v[144:147], v[212:215], v[118:121]
	v_mfma_f32_16x16x32_bf16 v[114:117], v[158:161], v[212:215], v[114:117]
	v_mfma_f32_16x16x32_bf16 v[110:113], v[144:147], v[220:223], v[110:113]
	v_mfma_f32_16x16x32_bf16 v[106:109], v[158:161], v[220:223], v[106:109]
	v_mfma_f32_16x16x32_bf16 v[102:105], v[144:147], v[228:231], v[102:105]
	v_mfma_f32_16x16x32_bf16 v[98:101], v[158:161], v[228:231], v[98:101]
	s_setprio 0
	s_setprio 1
	v_mfma_f32_16x16x32_bf16 v[62:65], v[162:165], v[200:203], 0
	v_mfma_f32_16x16x32_bf16 v[58:61], v[174:177], v[200:203], 0
	v_mfma_f32_16x16x32_bf16 v[54:57], v[162:165], v[208:211], 0
	v_mfma_f32_16x16x32_bf16 v[50:53], v[174:177], v[208:211], 0
	v_mfma_f32_16x16x32_bf16 v[46:49], v[162:165], v[216:219], 0
	v_mfma_f32_16x16x32_bf16 v[42:45], v[174:177], v[216:219], 0
	v_mfma_f32_16x16x32_bf16 v[38:41], v[162:165], v[224:227], 0
	v_mfma_f32_16x16x32_bf16 v[34:37], v[174:177], v[224:227], 0
	v_mfma_f32_16x16x32_bf16 v[62:65], v[170:173], v[204:207], v[62:65]
	v_mfma_f32_16x16x32_bf16 v[58:61], v[178:181], v[204:207], v[58:61]
	v_mfma_f32_16x16x32_bf16 v[54:57], v[170:173], v[212:215], v[54:57]
	v_mfma_f32_16x16x32_bf16 v[50:53], v[178:181], v[212:215], v[50:53]
	v_mfma_f32_16x16x32_bf16 v[46:49], v[170:173], v[220:223], v[46:49]
	v_mfma_f32_16x16x32_bf16 v[42:45], v[178:181], v[220:223], v[42:45]
	v_mfma_f32_16x16x32_bf16 v[38:41], v[170:173], v[228:231], v[38:41]
	v_mfma_f32_16x16x32_bf16 v[34:37], v[178:181], v[228:231], v[34:37]
	s_barrier
	s_setprio 0
	s_add_i32 s50, s50, s24
	v_lshl_add_u64 v[148:149], s[18:19], 0, v[0:1]
	s_mov_b32 m0, s50
	ds_read_b128 v[200:203], v169 offset:16384
	ds_read_b128 v[204:207], v169 offset:17408
	ds_read_b128 v[208:211], v169 offset:18432
	ds_read_b128 v[212:215], v169 offset:19456
	ds_read_b128 v[216:219], v169 offset:20480
	ds_read_b128 v[220:223], v169 offset:21504
	ds_read_b128 v[224:227], v169 offset:22528
	ds_read_b128 v[228:231], v169 offset:23552
	global_load_lds_dwordx4 v[148:149], off
	s_add_i32 m0, s50, 0x2000
	s_add_u32 s50, s18, 0x40000
	v_lshl_add_u64 v[232:233], s[18:19], 0, v[130:131]
	s_addc_u32 s51, s19, 0
	s_add_i32 s52, s52, s24
	global_load_lds_dwordx4 v[232:233], off
	v_lshl_add_u64 v[234:235], s[50:51], 0, v[0:1]
	s_mov_b32 m0, s52
	v_lshl_add_u64 v[236:237], s[20:21], 0, v[132:133]
	global_load_lds_dwordx4 v[234:235], off
	v_lshl_add_u64 v[234:235], s[50:51], 0, v[130:131]
	s_add_i32 m0, s52, 0x2000
	s_nop 0
	global_load_lds_dwordx4 v[234:235], off
	v_lshl_add_u64 v[234:235], s[20:21], 0, v[134:135]
	s_mov_b32 m0, s25
	s_nop 0
	global_load_lds_dwordx4 v[234:235], off
	s_mov_b32 m0, s26
	s_nop 0
	global_load_lds_dwordx4 v[236:237], off
	s_waitcnt vmcnt(20)
	s_waitcnt lgkmcnt(0)
	s_setprio 1
	s_barrier
	v_mfma_f32_16x16x32_bf16 v[94:97], v[140:143], v[200:203], 0
	v_mfma_f32_16x16x32_bf16 v[90:93], v[154:157], v[200:203], 0
	v_mfma_f32_16x16x32_bf16 v[86:89], v[140:143], v[208:211], 0
	v_mfma_f32_16x16x32_bf16 v[82:85], v[154:157], v[208:211], 0
	v_mfma_f32_16x16x32_bf16 v[78:81], v[140:143], v[216:219], 0
	v_mfma_f32_16x16x32_bf16 v[74:77], v[154:157], v[216:219], 0
	v_mfma_f32_16x16x32_bf16 v[70:73], v[140:143], v[224:227], 0
	v_mfma_f32_16x16x32_bf16 v[66:69], v[154:157], v[224:227], 0
	v_mfma_f32_16x16x32_bf16 v[94:97], v[144:147], v[204:207], v[94:97]
	v_mfma_f32_16x16x32_bf16 v[90:93], v[158:161], v[204:207], v[90:93]
	v_mfma_f32_16x16x32_bf16 v[86:89], v[144:147], v[212:215], v[86:89]
	v_mfma_f32_16x16x32_bf16 v[82:85], v[158:161], v[212:215], v[82:85]
	v_mfma_f32_16x16x32_bf16 v[78:81], v[144:147], v[220:223], v[78:81]
	v_mfma_f32_16x16x32_bf16 v[74:77], v[158:161], v[220:223], v[74:77]
	v_mfma_f32_16x16x32_bf16 v[70:73], v[144:147], v[228:231], v[70:73]
	v_mfma_f32_16x16x32_bf16 v[66:69], v[158:161], v[228:231], v[66:69]
	s_setprio 0
	s_setprio 1
	v_mfma_f32_16x16x32_bf16 v[30:33], v[162:165], v[200:203], 0
	v_mfma_f32_16x16x32_bf16 v[26:29], v[174:177], v[200:203], 0
	v_mfma_f32_16x16x32_bf16 v[22:25], v[162:165], v[208:211], 0
	v_mfma_f32_16x16x32_bf16 v[18:21], v[174:177], v[208:211], 0
	v_mfma_f32_16x16x32_bf16 v[14:17], v[162:165], v[216:219], 0
	v_mfma_f32_16x16x32_bf16 v[10:13], v[174:177], v[216:219], 0
	v_mfma_f32_16x16x32_bf16 v[6:9], v[162:165], v[224:227], 0
	v_mfma_f32_16x16x32_bf16 v[2:5], v[174:177], v[224:227], 0
	v_mfma_f32_16x16x32_bf16 v[30:33], v[170:173], v[204:207], v[30:33]
	v_mfma_f32_16x16x32_bf16 v[26:29], v[178:181], v[204:207], v[26:29]
	v_mfma_f32_16x16x32_bf16 v[22:25], v[170:173], v[212:215], v[22:25]
	v_mfma_f32_16x16x32_bf16 v[18:21], v[178:181], v[212:215], v[18:21]
	v_mfma_f32_16x16x32_bf16 v[14:17], v[170:173], v[220:223], v[14:17]
	v_mfma_f32_16x16x32_bf16 v[10:13], v[178:181], v[220:223], v[10:13]
	v_mfma_f32_16x16x32_bf16 v[6:9], v[170:173], v[228:231], v[6:9]
	v_mfma_f32_16x16x32_bf16 v[2:5], v[178:181], v[228:231], v[2:5]
	s_barrier
; #define PG8_STAGE(bufoff, gbase, voff) do { _Pragma("unroll") for (int _i = 0; _i < 2; ++_i) \
;         __builtin_amdgcn_global_load_lds((const unsigned*)((const char*)(gbase) + (voff)[_i]), (PG8_LAS unsigned*)(lds + (bufoff) + ldsw + _i * 8192), 16, 0, 0); } while (0)
; #define PG8_LDA(dst, b, h) do { _Pragma("unroll") for (int m = 0; m < 4; ++m) _Pragma("unroll") for (int k = 0; k < 2; ++k) dst[m][k] = *(const PG8_LAS bf16x8*)(lds + PG8_SA(b, h) + aoff + m * 2048 + k * 1024); } while (0)
; #define PG8_LDB(dst, b, h) do { _Pragma("unroll") for (int n = 0; n < 2; ++n) _Pragma("unroll") for (int k = 0; k < 2; ++k) dst[n][k] = *(const PG8_LAS bf16x8*)(lds + PG8_SB(b, h) + boff + n * 2048 + k * 1024); } while (0)
; #define PG8_MMA(ai, bj, At, Bt) do { __builtin_amdgcn_s_setprio(1); _Pragma("unroll") for (int m = 0; m < 4; ++m) _Pragma("unroll") for (int n = 0; n < 2; ++n) _Pragma("unroll") for (int k = 0; k < 2; ++k) \
;         acc[ai][bj][m][n] = __builtin_amdgcn_mfma_f32_16x16x32_bf16(Bt[n][k], At[m][k], acc[ai][bj][m][n], 0, 0, 0); __builtin_amdgcn_s_setprio(0); } while (0)
; #define PG8_WAIT_V(n) asm volatile("s_waitcnt vmcnt(" #n ")" ::: "memory")
; #define PG8_WAIT_L(n) asm volatile("s_waitcnt lgkmcnt(" #n ")" ::: "memory")
; #define PG8_BAR __builtin_amdgcn_s_barrier()
; #define PG8_SCHED __builtin_amdgcn_sched_barrier(0)
; template <class Epi, class Sched, bool ALIGN_EPI = false, bool SP2 = false>
; __device__ __forceinline__ void gemm_phase(PG8_LAS unsigned char* lds, const Gemm g, const Sched& S, const Epi& E) {
;     ...
;             PG8_WAIT_V(8); PG8_WAIT_L(0); PG8_BAR; PG8_MMA(1, 0, At, B0); PG8_MMA(1, 1, At, B1); PG8_BAR; PG8_SCHED;
;             PG8_LDB(B0, 1, 0); PG8_LDB(B1, 1, 1); PG8_SCHED; PG8_LDA(At, 1, 0); PG8_STAGE(PG8_SA(0, 1), a2 + hstep, voffA);
;             PG8_WAIT_V(8); PG8_WAIT_L(0); PG8_BAR; PG8_MMA(0, 0, At, B0); PG8_MMA(0, 1, At, B1); PG8_BAR; PG8_SCHED;
;             PG8_LDA(At, 1, 1); PG8_STAGE(PG8_SB(1, 0), b3, voffB); PG8_STAGE(PG8_SB(1, 1), b3 + hstep, voffB); PG8_STAGE(PG8_SA(1, 0), a3, voffA);
	s_setprio 0
	s_add_i32 s50, 0, 0x18000
	s_add_i32 s51, 0, 0x1c000
	v_add_u32_e32 v158, s50, v167
	v_add_u32_e32 v178, s51, v167
	ds_read_b128 v[140:143], v158
	ds_read_b128 v[144:147], v158 offset:1024
	ds_read_b128 v[154:157], v158 offset:2048
	ds_read_b128 v[158:161], v158 offset:3072
	ds_read_b128 v[162:165], v178
	ds_read_b128 v[170:173], v178 offset:1024
	ds_read_b128 v[174:177], v178 offset:2048
	ds_read_b128 v[178:181], v178 offset:3072
	s_add_u32 s20, s20, 0x40000
	s_addc_u32 s21, s21, 0
	s_mov_b32 m0, s27
	v_lshl_add_u64 v[238:239], s[20:21], 0, v[134:135]
	ds_read_b128 v[200:203], v169 offset:32768
	ds_read_b128 v[204:207], v169 offset:33792
	ds_read_b128 v[208:211], v169 offset:34816
	ds_read_b128 v[212:215], v169 offset:35840
	ds_read_b128 v[216:219], v169 offset:36864
	ds_read_b128 v[220:223], v169 offset:37888
	ds_read_b128 v[224:227], v169 offset:38912
	ds_read_b128 v[228:231], v169 offset:39936
	global_load_lds_dwordx4 v[238:239], off
	v_lshl_add_u64 v[238:239], s[20:21], 0, v[132:133]
	s_mov_b32 m0, s28
	s_nop 0
	global_load_lds_dwordx4 v[238:239], off
	s_waitcnt vmcnt(8)
	s_waitcnt lgkmcnt(0)
	s_setprio 1
	s_barrier
	v_mfma_f32_16x16x32_bf16 v[126:129], v[140:143], v[200:203], v[126:129]
	v_mfma_f32_16x16x32_bf16 v[122:125], v[154:157], v[200:203], v[122:125]
	v_mfma_f32_16x16x32_bf16 v[118:121], v[140:143], v[208:211], v[118:121]
	v_mfma_f32_16x16x32_bf16 v[114:117], v[154:157], v[208:211], v[114:117]
	v_mfma_f32_16x16x32_bf16 v[110:113], v[140:143], v[216:219], v[110:113]
	v_mfma_f32_16x16x32_bf16 v[106:109], v[154:157], v[216:219], v[106:109]
	v_mfma_f32_16x16x32_bf16 v[102:105], v[140:143], v[224:227], v[102:105]
	v_mfma_f32_16x16x32_bf16 v[98:101], v[154:157], v[224:227], v[98:101]
	v_mfma_f32_16x16x32_bf16 v[126:129], v[144:147], v[204:207], v[126:129]
	v_mfma_f32_16x16x32_bf16 v[122:125], v[158:161], v[204:207], v[122:125]
	v_mfma_f32_16x16x32_bf16 v[118:121], v[144:147], v[212:215], v[118:121]
	v_mfma_f32_16x16x32_bf16 v[114:117], v[158:161], v[212:215], v[114:117]
	v_mfma_f32_16x16x32_bf16 v[110:113], v[144:147], v[220:223], v[110:113]
	v_mfma_f32_16x16x32_bf16 v[106:109], v[158:161], v[220:223], v[106:109]
	v_mfma_f32_16x16x32_bf16 v[102:105], v[144:147], v[228:231], v[102:105]
	v_mfma_f32_16x16x32_bf16 v[98:101], v[158:161], v[228:231], v[98:101]
	s_setprio 0
	s_setprio 1
	v_mfma_f32_16x16x32_bf16 v[62:65], v[162:165], v[200:203], v[62:65]
	v_mfma_f32_16x16x32_bf16 v[58:61], v[174:177], v[200:203], v[58:61]
	v_mfma_f32_16x16x32_bf16 v[54:57], v[162:165], v[208:211], v[54:57]
	v_mfma_f32_16x16x32_bf16 v[50:53], v[174:177], v[208:211], v[50:53]
	v_mfma_f32_16x16x32_bf16 v[46:49], v[162:165], v[216:219], v[46:49]
	v_mfma_f32_16x16x32_bf16 v[42:45], v[174:177], v[216:219], v[42:45]
	v_mfma_f32_16x16x32_bf16 v[38:41], v[162:165], v[224:227], v[38:41]
	v_mfma_f32_16x16x32_bf16 v[34:37], v[174:177], v[224:227], v[34:37]
	v_mfma_f32_16x16x32_bf16 v[62:65], v[170:173], v[204:207], v[62:65]
	v_mfma_f32_16x16x32_bf16 v[58:61], v[178:181], v[204:207], v[58:61]
	v_mfma_f32_16x16x32_bf16 v[54:57], v[170:173], v[212:215], v[54:57]
	v_mfma_f32_16x16x32_bf16 v[50:53], v[178:181], v[212:215], v[50:53]
	v_mfma_f32_16x16x32_bf16 v[46:49], v[170:173], v[220:223], v[46:49]
	v_mfma_f32_16x16x32_bf16 v[42:45], v[178:181], v[220:223], v[42:45]
	v_mfma_f32_16x16x32_bf16 v[38:41], v[170:173], v[228:231], v[38:41]
	v_mfma_f32_16x16x32_bf16 v[34:37], v[178:181], v[228:231], v[34:37]
	s_barrier
	s_setprio 0
	s_add_i32 s20, s50, s24
	v_lshl_add_u64 v[148:149], v[148:149], 0, s[38:39]
	s_mov_b32 m0, s20
	ds_read_b128 v[200:203], v169 offset:49152
	ds_read_b128 v[204:207], v169 offset:50176
	ds_read_b128 v[208:211], v169 offset:51200
	ds_read_b128 v[212:215], v169 offset:52224
	ds_read_b128 v[216:219], v169 offset:53248
	ds_read_b128 v[220:223], v169 offset:54272
	ds_read_b128 v[224:227], v169 offset:55296
	ds_read_b128 v[228:231], v169 offset:56320
	global_load_lds_dwordx4 v[148:149], off
	s_add_i32 m0, s20, 0x2000
	s_add_u32 s18, s18, 0x40080
	v_lshl_add_u64 v[148:149], v[232:233], 0, s[38:39]
	s_addc_u32 s19, s19, 0
	s_add_i32 s20, s51, s24
	global_load_lds_dwordx4 v[148:149], off
	v_lshl_add_u64 v[148:149], s[18:19], 0, v[0:1]
	s_mov_b32 m0, s20
	s_nop 0
	global_load_lds_dwordx4 v[148:149], off
	v_lshl_add_u64 v[148:149], s[18:19], 0, v[130:131]
	s_add_i32 m0, s20, 0x2000
	s_nop 0
	global_load_lds_dwordx4 v[148:149], off
	v_lshl_add_u64 v[148:149], v[234:235], 0, s[38:39]
	s_mov_b32 m0, s31
	s_nop 0
	global_load_lds_dwordx4 v[148:149], off
	v_lshl_add_u64 v[148:149], v[236:237], 0, s[38:39]
	s_mov_b32 m0, s33
	s_nop 0
	global_load_lds_dwordx4 v[148:149], off
	s_waitcnt vmcnt(8)
	s_waitcnt lgkmcnt(0)
	s_setprio 1
	s_barrier
; #define PG8_STAGE(bufoff, gbase, voff) do { _Pragma("unroll") for (int _i = 0; _i < 2; ++_i) \
;         __builtin_amdgcn_global_load_lds((const unsigned*)((const char*)(gbase) + (voff)[_i]), (PG8_LAS unsigned*)(lds + (bufoff) + ldsw + _i * 8192), 16, 0, 0); } while (0)
; #define PG8_LDA(dst, b, h) do { _Pragma("unroll") for (int m = 0; m < 4; ++m) _Pragma("unroll") for (int k = 0; k < 2; ++k) dst[m][k] = *(const PG8_LAS bf16x8*)(lds + PG8_SA(b, h) + aoff + m * 2048 + k * 1024); } while (0)
; #define PG8_LDB(dst, b, h) do { _Pragma("unroll") for (int n = 0; n < 2; ++n) _Pragma("unroll") for (int k = 0; k < 2; ++k) dst[n][k] = *(const PG8_LAS bf16x8*)(lds + PG8_SB(b, h) + boff + n * 2048 + k * 1024); } while (0)
; #define PG8_MMA(ai, bj, At, Bt) do { __builtin_amdgcn_s_setprio(1); _Pragma("unroll") for (int m = 0; m < 4; ++m) _Pragma("unroll") for (int n = 0; n < 2; ++n) _Pragma("unroll") for (int k = 0; k < 2; ++k) \
;         acc[ai][bj][m][n] = __builtin_amdgcn_mfma_f32_16x16x32_bf16(Bt[n][k], At[m][k], acc[ai][bj][m][n], 0, 0, 0); __builtin_amdgcn_s_setprio(0); } while (0)
; #define PG8_WAIT_V(n) asm volatile("s_waitcnt vmcnt(" #n ")" ::: "memory")
; template <class Epi, class Sched, bool ALIGN_EPI = false, bool SP2 = false>
; __device__ __forceinline__ void gemm_phase(PG8_LAS unsigned char* lds, const Gemm g, const Sched& S, const Epi& E) {
;     ...
;             PG8_LDB(B0, 0, 0); PG8_LDB(B1, 0, 1); PG8_SCHED; PG8_LDA(At, 0, 0); PG8_STAGE(PG8_SA(1, 1), a1 + hstep, voffA);
;             PG8_WAIT_V(8); PG8_WAIT_L(0); PG8_BAR; PG8_MMA(0, 0, At, B0); PG8_MMA(0, 1, At, B1); PG8_BAR; PG8_SCHED;
;             PG8_LDA(At, 0, 1); PG8_STAGE(PG8_SB(0, 0), b2, voffB); PG8_STAGE(PG8_SB(0, 1), b2 + hstep, voffB); PG8_STAGE(PG8_SA(0, 0), a2, voffA);
;             PG8_WAIT_V(8); PG8_WAIT_L(0); PG8_BAR; PG8_MMA(1, 0, At, B0); PG8_MMA(1, 1, At, B1); PG8_BAR; PG8_SCHED;
;             PG8_LDB(B0, 1, 0); PG8_LDB(B1, 1, 1); PG8_SCHED; PG8_LDA(At, 1, 0); PG8_STAGE(PG8_SA(0, 1), a2 + hstep, voffA);
;             PG8_WAIT_V(8); PG8_WAIT_L(0); PG8_BAR; PG8_MMA(0, 0, At, B0); PG8_MMA(0, 1, At, B1); PG8_BAR; PG8_SCHED;
;             PG8_LDA(At, 1, 1); PG8_STAGE(PG8_SB(1, 0), b3, voffB); PG8_STAGE(PG8_SB(1, 1), b3 + hstep, voffB); PG8_STAGE(PG8_SA(1, 0), a3, voffA);
;             PG8_WAIT_V(8); PG8_WAIT_L(0); PG8_BAR; PG8_MMA(1, 0, At, B0); PG8_MMA(1, 1, At, B1); PG8_BAR; PG8_SCHED;
	v_mfma_f32_16x16x32_bf16 v[94:97], v[140:143], v[200:203], v[94:97]
	v_mfma_f32_16x16x32_bf16 v[90:93], v[154:157], v[200:203], v[90:93]
	v_mfma_f32_16x16x32_bf16 v[86:89], v[140:143], v[208:211], v[86:89]
	v_mfma_f32_16x16x32_bf16 v[82:85], v[154:157], v[208:211], v[82:85]
	v_mfma_f32_16x16x32_bf16 v[78:81], v[140:143], v[216:219], v[78:81]
	v_mfma_f32_16x16x32_bf16 v[74:77], v[154:157], v[216:219], v[74:77]
	v_mfma_f32_16x16x32_bf16 v[70:73], v[140:143], v[224:227], v[70:73]
	v_mfma_f32_16x16x32_bf16 v[66:69], v[154:157], v[224:227], v[66:69]
	v_mfma_f32_16x16x32_bf16 v[94:97], v[144:147], v[204:207], v[94:97]
	v_mfma_f32_16x16x32_bf16 v[90:93], v[158:161], v[204:207], v[90:93]
	v_mfma_f32_16x16x32_bf16 v[86:89], v[144:147], v[212:215], v[86:89]
	v_mfma_f32_16x16x32_bf16 v[82:85], v[158:161], v[212:215], v[82:85]
	v_mfma_f32_16x16x32_bf16 v[78:81], v[144:147], v[220:223], v[78:81]
	v_mfma_f32_16x16x32_bf16 v[74:77], v[158:161], v[220:223], v[74:77]
	v_mfma_f32_16x16x32_bf16 v[70:73], v[144:147], v[228:231], v[70:73]
	v_mfma_f32_16x16x32_bf16 v[66:69], v[158:161], v[228:231], v[66:69]
	s_setprio 0
	s_setprio 1
	v_mfma_f32_16x16x32_bf16 v[30:33], v[162:165], v[200:203], v[30:33]
	v_mfma_f32_16x16x32_bf16 v[26:29], v[174:177], v[200:203], v[26:29]
	v_mfma_f32_16x16x32_bf16 v[22:25], v[162:165], v[208:211], v[22:25]
	v_mfma_f32_16x16x32_bf16 v[18:21], v[174:177], v[208:211], v[18:21]
	v_mfma_f32_16x16x32_bf16 v[14:17], v[162:165], v[216:219], v[14:17]
	v_mfma_f32_16x16x32_bf16 v[10:13], v[174:177], v[216:219], v[10:13]
	v_mfma_f32_16x16x32_bf16 v[6:9], v[162:165], v[224:227], v[6:9]
	v_mfma_f32_16x16x32_bf16 v[2:5], v[174:177], v[224:227], v[2:5]
	v_mfma_f32_16x16x32_bf16 v[30:33], v[170:173], v[204:207], v[30:33]
	v_mfma_f32_16x16x32_bf16 v[26:29], v[178:181], v[204:207], v[26:29]
	v_mfma_f32_16x16x32_bf16 v[22:25], v[170:173], v[212:215], v[22:25]
	v_mfma_f32_16x16x32_bf16 v[18:21], v[178:181], v[212:215], v[18:21]
	v_mfma_f32_16x16x32_bf16 v[14:17], v[170:173], v[220:223], v[14:17]
	v_mfma_f32_16x16x32_bf16 v[10:13], v[178:181], v[220:223], v[10:13]
	v_mfma_f32_16x16x32_bf16 v[6:9], v[170:173], v[228:231], v[6:9]
	v_mfma_f32_16x16x32_bf16 v[2:5], v[178:181], v[228:231], v[2:5]
	s_barrier
	s_setprio 0
	s_add_i32 s49, s49, 2
	s_add_u32 s16, s16, 0x100
	s_addc_u32 s17, s17, 0
	s_add_u32 s47, s47, 0x100
	s_addc_u32 s48, s48, 0
.LBB0_1090:
	s_add_u32 s18, s16, 0xfffc0080
	s_addc_u32 s19, s17, -1
	s_add_i32 s50, 0, 0x10000
	s_cmp_eq_u32 s49, 12
	s_cselect_b32 s21, s11, s19
	s_cselect_b32 s20, s45, s18
	v_add_u32_e32 v148, s50, v167
	s_cselect_b32 s19, s9, s48
	s_cselect_b32 s18, s46, s47
	s_add_i32 s52, 0, 0x14000
	ds_read_b128 v[140:143], v148
	ds_read_b128 v[144:147], v148 offset:1024
	ds_read_b128 v[154:157], v148 offset:2048
	ds_read_b128 v[158:161], v148 offset:3072
	v_add_u32_e32 v148, s52, v167
	ds_read_b128 v[162:165], v148
	ds_read_b128 v[170:173], v148 offset:1024
	ds_read_b128 v[174:177], v148 offset:2048
	ds_read_b128 v[178:181], v148 offset:3072
	v_lshl_add_u64 v[148:149], s[16:17], 0, v[136:137]
	s_add_i32 m0, s25, 0xc000
	ds_read_b128 v[200:203], v169
	ds_read_b128 v[204:207], v169 offset:1024
	ds_read_b128 v[208:211], v169 offset:2048
	ds_read_b128 v[212:215], v169 offset:3072
	ds_read_b128 v[216:219], v169 offset:4096
	ds_read_b128 v[220:223], v169 offset:5120
	ds_read_b128 v[224:227], v169 offset:6144
	ds_read_b128 v[228:231], v169 offset:7168
	global_load_lds_dwordx4 v[148:149], off
	v_lshl_add_u64 v[148:149], s[16:17], 0, v[138:139]
	s_add_i32 m0, s25, 0xe000
	s_nop 0
	global_load_lds_dwordx4 v[148:149], off
	s_waitcnt vmcnt(8)
	s_waitcnt lgkmcnt(0)
	s_setprio 1
	s_barrier
	v_mfma_f32_16x16x32_bf16 v[126:129], v[140:143], v[200:203], v[126:129]
	v_mfma_f32_16x16x32_bf16 v[122:125], v[154:157], v[200:203], v[122:125]
	v_mfma_f32_16x16x32_bf16 v[118:121], v[140:143], v[208:211], v[118:121]
	v_mfma_f32_16x16x32_bf16 v[114:117], v[154:157], v[208:211], v[114:117]
	v_mfma_f32_16x16x32_bf16 v[110:113], v[140:143], v[216:219], v[110:113]
	v_mfma_f32_16x16x32_bf16 v[106:109], v[154:157], v[216:219], v[106:109]
	v_mfma_f32_16x16x32_bf16 v[102:105], v[140:143], v[224:227], v[102:105]
	v_mfma_f32_16x16x32_bf16 v[98:101], v[154:157], v[224:227], v[98:101]
	v_mfma_f32_16x16x32_bf16 v[126:129], v[144:147], v[204:207], v[126:129]
	v_mfma_f32_16x16x32_bf16 v[122:125], v[158:161], v[204:207], v[122:125]
	v_mfma_f32_16x16x32_bf16 v[118:121], v[144:147], v[212:215], v[118:121]
	v_mfma_f32_16x16x32_bf16 v[114:117], v[158:161], v[212:215], v[114:117]
	v_mfma_f32_16x16x32_bf16 v[110:113], v[144:147], v[220:223], v[110:113]
	v_mfma_f32_16x16x32_bf16 v[106:109], v[158:161], v[220:223], v[106:109]
	v_mfma_f32_16x16x32_bf16 v[102:105], v[144:147], v[228:231], v[102:105]
	v_mfma_f32_16x16x32_bf16 v[98:101], v[158:161], v[228:231], v[98:101]
	s_setprio 0
	s_setprio 1
	v_mfma_f32_16x16x32_bf16 v[62:65], v[162:165], v[200:203], v[62:65]
	v_mfma_f32_16x16x32_bf16 v[58:61], v[174:177], v[200:203], v[58:61]
	v_mfma_f32_16x16x32_bf16 v[54:57], v[162:165], v[208:211], v[54:57]
	v_mfma_f32_16x16x32_bf16 v[50:53], v[174:177], v[208:211], v[50:53]
	v_mfma_f32_16x16x32_bf16 v[46:49], v[162:165], v[216:219], v[46:49]
	v_mfma_f32_16x16x32_bf16 v[42:45], v[174:177], v[216:219], v[42:45]
	v_mfma_f32_16x16x32_bf16 v[38:41], v[162:165], v[224:227], v[38:41]
	v_mfma_f32_16x16x32_bf16 v[34:37], v[174:177], v[224:227], v[34:37]
	v_mfma_f32_16x16x32_bf16 v[62:65], v[170:173], v[204:207], v[62:65]
	v_mfma_f32_16x16x32_bf16 v[58:61], v[178:181], v[204:207], v[58:61]
	v_mfma_f32_16x16x32_bf16 v[54:57], v[170:173], v[212:215], v[54:57]
	v_mfma_f32_16x16x32_bf16 v[50:53], v[178:181], v[212:215], v[50:53]
	v_mfma_f32_16x16x32_bf16 v[46:49], v[170:173], v[220:223], v[46:49]
	v_mfma_f32_16x16x32_bf16 v[42:45], v[178:181], v[220:223], v[42:45]
	v_mfma_f32_16x16x32_bf16 v[38:41], v[170:173], v[228:231], v[38:41]
	v_mfma_f32_16x16x32_bf16 v[34:37], v[178:181], v[228:231], v[34:37]
	s_barrier
; #define PG8_STAGE(bufoff, gbase, voff) do { _Pragma("unroll") for (int _i = 0; _i < 2; ++_i) \
;         __builtin_amdgcn_global_load_lds((const unsigned*)((const char*)(gbase) + (voff)[_i]), (PG8_LAS unsigned*)(lds + (bufoff) + ldsw + _i * 8192), 16, 0, 0); } while (0)
; #define PG8_LDA(dst, b, h) do { _Pragma("unroll") for (int m = 0; m < 4; ++m) _Pragma("unroll") for (int k = 0; k < 2; ++k) dst[m][k] = *(const PG8_LAS bf16x8*)(lds + PG8_SA(b, h) + aoff + m * 2048 + k * 1024); } while (0)
; #define PG8_LDB(dst, b, h) do { _Pragma("unroll") for (int n = 0; n < 2; ++n) _Pragma("unroll") for (int k = 0; k < 2; ++k) dst[n][k] = *(const PG8_LAS bf16x8*)(lds + PG8_SB(b, h) + boff + n * 2048 + k * 1024); } while (0)
; #define PG8_MMA(ai, bj, At, Bt) do { __builtin_amdgcn_s_setprio(1); _Pragma("unroll") for (int m = 0; m < 4; ++m) _Pragma("unroll") for (int n = 0; n < 2; ++n) _Pragma("unroll") for (int k = 0; k < 2; ++k) \
;         acc[ai][bj][m][n] = __builtin_amdgcn_mfma_f32_16x16x32_bf16(Bt[n][k], At[m][k], acc[ai][bj][m][n], 0, 0, 0); __builtin_amdgcn_s_setprio(0); } while (0)
; #define PG8_WAIT_V(n) asm volatile("s_waitcnt vmcnt(" #n ")" ::: "memory")
; #define PG8_WAIT_L(n) asm volatile("s_waitcnt lgkmcnt(" #n ")" ::: "memory")
; #define PG8_BAR __builtin_amdgcn_s_barrier()
; #define PG8_SCHED __builtin_amdgcn_sched_barrier(0)
; template <class Epi, class Sched, bool ALIGN_EPI = false, bool SP2 = false>
; __device__ __forceinline__ void gemm_phase(PG8_LAS unsigned char* lds, const Gemm g, const Sched& S, const Epi& E) {
;     ...
;             PG8_LDA(At, 0, 1); PG8_STAGE(PG8_SB(0, 0), b2, voffB); PG8_STAGE(PG8_SB(0, 1), b2 + hstep, voffB); PG8_STAGE(PG8_SA(0, 0), a2, voffA);
;             PG8_WAIT_V(8); PG8_WAIT_L(0); PG8_BAR; PG8_MMA(1, 0, At, B0); PG8_MMA(1, 1, At, B1); PG8_BAR; PG8_SCHED;
;             PG8_LDB(B0, 1, 0); PG8_LDB(B1, 1, 1); PG8_SCHED; PG8_LDA(At, 1, 0); PG8_STAGE(PG8_SA(0, 1), a2 + hstep, voffA);
;             PG8_WAIT_V(8); PG8_WAIT_L(0); PG8_BAR; PG8_MMA(0, 0, At, B0); PG8_MMA(0, 1, At, B1); PG8_BAR; PG8_SCHED;
;             PG8_LDA(At, 1, 1); PG8_STAGE(PG8_SB(1, 0), b3, voffB); PG8_STAGE(PG8_SB(1, 1), b3 + hstep, voffB); PG8_STAGE(PG8_SA(1, 0), a3, voffA);
	s_setprio 0
	s_add_i32 s50, s50, s24
	v_lshl_add_u64 v[148:149], s[18:19], 0, v[0:1]
	s_mov_b32 m0, s50
	ds_read_b128 v[200:203], v169 offset:16384
	ds_read_b128 v[204:207], v169 offset:17408
	ds_read_b128 v[208:211], v169 offset:18432
	ds_read_b128 v[212:215], v169 offset:19456
	ds_read_b128 v[216:219], v169 offset:20480
	ds_read_b128 v[220:223], v169 offset:21504
	ds_read_b128 v[224:227], v169 offset:22528
	ds_read_b128 v[228:231], v169 offset:23552
	global_load_lds_dwordx4 v[148:149], off
	s_add_i32 m0, s50, 0x2000
	s_add_u32 s50, s18, 0x40000
	v_lshl_add_u64 v[232:233], s[18:19], 0, v[130:131]
	s_addc_u32 s51, s19, 0
	s_add_i32 s52, s52, s24
	global_load_lds_dwordx4 v[232:233], off
	v_lshl_add_u64 v[234:235], s[50:51], 0, v[0:1]
	s_mov_b32 m0, s52
	v_lshl_add_u64 v[236:237], s[20:21], 0, v[132:133]
	global_load_lds_dwordx4 v[234:235], off
	v_lshl_add_u64 v[234:235], s[50:51], 0, v[130:131]
	s_add_i32 m0, s52, 0x2000
	s_nop 0
	global_load_lds_dwordx4 v[234:235], off
	v_lshl_add_u64 v[234:235], s[20:21], 0, v[134:135]
	s_mov_b32 m0, s25
	s_nop 0
	global_load_lds_dwordx4 v[234:235], off
	s_mov_b32 m0, s26
	s_nop 0
	global_load_lds_dwordx4 v[236:237], off
	s_waitcnt vmcnt(8)
	s_waitcnt lgkmcnt(0)
	s_setprio 1
	s_barrier
	v_mfma_f32_16x16x32_bf16 v[94:97], v[140:143], v[200:203], v[94:97]
	v_mfma_f32_16x16x32_bf16 v[90:93], v[154:157], v[200:203], v[90:93]
	v_mfma_f32_16x16x32_bf16 v[86:89], v[140:143], v[208:211], v[86:89]
	v_mfma_f32_16x16x32_bf16 v[82:85], v[154:157], v[208:211], v[82:85]
	v_mfma_f32_16x16x32_bf16 v[78:81], v[140:143], v[216:219], v[78:81]
	v_mfma_f32_16x16x32_bf16 v[74:77], v[154:157], v[216:219], v[74:77]
	v_mfma_f32_16x16x32_bf16 v[70:73], v[140:143], v[224:227], v[70:73]
	v_mfma_f32_16x16x32_bf16 v[66:69], v[154:157], v[224:227], v[66:69]
	v_mfma_f32_16x16x32_bf16 v[94:97], v[144:147], v[204:207], v[94:97]
	v_mfma_f32_16x16x32_bf16 v[90:93], v[158:161], v[204:207], v[90:93]
	v_mfma_f32_16x16x32_bf16 v[86:89], v[144:147], v[212:215], v[86:89]
	v_mfma_f32_16x16x32_bf16 v[82:85], v[158:161], v[212:215], v[82:85]
	v_mfma_f32_16x16x32_bf16 v[78:81], v[144:147], v[220:223], v[78:81]
	v_mfma_f32_16x16x32_bf16 v[74:77], v[158:161], v[220:223], v[74:77]
	v_mfma_f32_16x16x32_bf16 v[70:73], v[144:147], v[228:231], v[70:73]
	v_mfma_f32_16x16x32_bf16 v[66:69], v[158:161], v[228:231], v[66:69]
	s_setprio 0
	s_setprio 1
	v_mfma_f32_16x16x32_bf16 v[30:33], v[162:165], v[200:203], v[30:33]
	v_mfma_f32_16x16x32_bf16 v[26:29], v[174:177], v[200:203], v[26:29]
	v_mfma_f32_16x16x32_bf16 v[22:25], v[162:165], v[208:211], v[22:25]
	v_mfma_f32_16x16x32_bf16 v[18:21], v[174:177], v[208:211], v[18:21]
	v_mfma_f32_16x16x32_bf16 v[14:17], v[162:165], v[216:219], v[14:17]
	v_mfma_f32_16x16x32_bf16 v[10:13], v[174:177], v[216:219], v[10:13]
	v_mfma_f32_16x16x32_bf16 v[6:9], v[162:165], v[224:227], v[6:9]
	v_mfma_f32_16x16x32_bf16 v[2:5], v[174:177], v[224:227], v[2:5]
	v_mfma_f32_16x16x32_bf16 v[30:33], v[170:173], v[204:207], v[30:33]
	v_mfma_f32_16x16x32_bf16 v[26:29], v[178:181], v[204:207], v[26:29]
	v_mfma_f32_16x16x32_bf16 v[22:25], v[170:173], v[212:215], v[22:25]
	v_mfma_f32_16x16x32_bf16 v[18:21], v[178:181], v[212:215], v[18:21]
	v_mfma_f32_16x16x32_bf16 v[14:17], v[170:173], v[220:223], v[14:17]
	v_mfma_f32_16x16x32_bf16 v[10:13], v[178:181], v[220:223], v[10:13]
	v_mfma_f32_16x16x32_bf16 v[6:9], v[170:173], v[228:231], v[6:9]
	v_mfma_f32_16x16x32_bf16 v[2:5], v[178:181], v[228:231], v[2:5]
	s_barrier
	s_setprio 0
	s_add_i32 s50, 0, 0x18000
	s_add_i32 s51, 0, 0x1c000
	v_add_u32_e32 v158, s50, v167
	v_add_u32_e32 v178, s51, v167
	ds_read_b128 v[140:143], v158
	ds_read_b128 v[144:147], v158 offset:1024
	ds_read_b128 v[154:157], v158 offset:2048
	ds_read_b128 v[158:161], v158 offset:3072
	ds_read_b128 v[162:165], v178
	ds_read_b128 v[170:173], v178 offset:1024
	ds_read_b128 v[174:177], v178 offset:2048
	ds_read_b128 v[178:181], v178 offset:3072
	s_add_u32 s20, s20, 0x40000
	s_addc_u32 s21, s21, 0
	s_mov_b32 m0, s27
	v_lshl_add_u64 v[238:239], s[20:21], 0, v[134:135]
	ds_read_b128 v[200:203], v169 offset:32768
	ds_read_b128 v[204:207], v169 offset:33792
	ds_read_b128 v[208:211], v169 offset:34816
	ds_read_b128 v[212:215], v169 offset:35840
	ds_read_b128 v[216:219], v169 offset:36864
	ds_read_b128 v[220:223], v169 offset:37888
	ds_read_b128 v[224:227], v169 offset:38912
	ds_read_b128 v[228:231], v169 offset:39936
	global_load_lds_dwordx4 v[238:239], off
	v_lshl_add_u64 v[238:239], s[20:21], 0, v[132:133]
	s_mov_b32 m0, s28
	s_nop 0
	global_load_lds_dwordx4 v[238:239], off
	s_waitcnt vmcnt(8)
	s_waitcnt lgkmcnt(0)
	s_setprio 1
	s_barrier
; #define PG8_STAGE(bufoff, gbase, voff) do { _Pragma("unroll") for (int _i = 0; _i < 2; ++_i) \
;         __builtin_amdgcn_global_load_lds((const unsigned*)((const char*)(gbase) + (voff)[_i]), (PG8_LAS unsigned*)(lds + (bufoff) + ldsw + _i * 8192), 16, 0, 0); } while (0)
; #define PG8_LDA(dst, b, h) do { _Pragma("unroll") for (int m = 0; m < 4; ++m) _Pragma("unroll") for (int k = 0; k < 2; ++k) dst[m][k] = *(const PG8_LAS bf16x8*)(lds + PG8_SA(b, h) + aoff + m * 2048 + k * 1024); } while (0)
; #define PG8_LDB(dst, b, h) do { _Pragma("unroll") for (int n = 0; n < 2; ++n) _Pragma("unroll") for (int k = 0; k < 2; ++k) dst[n][k] = *(const PG8_LAS bf16x8*)(lds + PG8_SB(b, h) + boff + n * 2048 + k * 1024); } while (0)
; #define PG8_MMA(ai, bj, At, Bt) do { __builtin_amdgcn_s_setprio(1); _Pragma("unroll") for (int m = 0; m < 4; ++m) _Pragma("unroll") for (int n = 0; n < 2; ++n) _Pragma("unroll") for (int k = 0; k < 2; ++k) \
;         acc[ai][bj][m][n] = __builtin_amdgcn_mfma_f32_16x16x32_bf16(Bt[n][k], At[m][k], acc[ai][bj][m][n], 0, 0, 0); __builtin_amdgcn_s_setprio(0); } while (0)
; #define PG8_WAIT_V(n) asm volatile("s_waitcnt vmcnt(" #n ")" ::: "memory")
; #define PG8_WAIT_L(n) asm volatile("s_waitcnt lgkmcnt(" #n ")" ::: "memory")
; #define PG8_BAR __builtin_amdgcn_s_barrier()
; #define PG8_SCHED __builtin_amdgcn_sched_barrier(0)
; template <class Epi, class Sched, bool ALIGN_EPI = false, bool SP2 = false>
; __device__ __forceinline__ void gemm_phase(PG8_LAS unsigned char* lds, const Gemm g, const Sched& S, const Epi& E) {
;     ...
;             PG8_LDB(B0, 1, 0); PG8_LDB(B1, 1, 1); PG8_SCHED; PG8_LDA(At, 1, 0); PG8_STAGE(PG8_SA(0, 1), a2 + hstep, voffA);
;             PG8_WAIT_V(8); PG8_WAIT_L(0); PG8_BAR; PG8_MMA(0, 0, At, B0); PG8_MMA(0, 1, At, B1); PG8_BAR; PG8_SCHED;
;             PG8_LDA(At, 1, 1); PG8_STAGE(PG8_SB(1, 0), b3, voffB); PG8_STAGE(PG8_SB(1, 1), b3 + hstep, voffB); PG8_STAGE(PG8_SA(1, 0), a3, voffA);
;             PG8_WAIT_V(8); PG8_WAIT_L(0); PG8_BAR; PG8_MMA(1, 0, At, B0); PG8_MMA(1, 1, At, B1); PG8_BAR; PG8_SCHED;
;     ...
;         if constexpr (ALIGN_EPI) { if (wr == 0) PG8_BAR; }
	v_mfma_f32_16x16x32_bf16 v[126:129], v[140:143], v[200:203], v[126:129]
	v_mfma_f32_16x16x32_bf16 v[122:125], v[154:157], v[200:203], v[122:125]
	v_mfma_f32_16x16x32_bf16 v[118:121], v[140:143], v[208:211], v[118:121]
	v_mfma_f32_16x16x32_bf16 v[114:117], v[154:157], v[208:211], v[114:117]
	v_mfma_f32_16x16x32_bf16 v[110:113], v[140:143], v[216:219], v[110:113]
	v_mfma_f32_16x16x32_bf16 v[106:109], v[154:157], v[216:219], v[106:109]
	v_mfma_f32_16x16x32_bf16 v[102:105], v[140:143], v[224:227], v[102:105]
	v_mfma_f32_16x16x32_bf16 v[98:101], v[154:157], v[224:227], v[98:101]
	v_mfma_f32_16x16x32_bf16 v[126:129], v[144:147], v[204:207], v[126:129]
	v_mfma_f32_16x16x32_bf16 v[122:125], v[158:161], v[204:207], v[122:125]
	v_mfma_f32_16x16x32_bf16 v[118:121], v[144:147], v[212:215], v[118:121]
	v_mfma_f32_16x16x32_bf16 v[114:117], v[158:161], v[212:215], v[114:117]
	v_mfma_f32_16x16x32_bf16 v[110:113], v[144:147], v[220:223], v[110:113]
	v_mfma_f32_16x16x32_bf16 v[106:109], v[158:161], v[220:223], v[106:109]
	v_mfma_f32_16x16x32_bf16 v[102:105], v[144:147], v[228:231], v[102:105]
	v_mfma_f32_16x16x32_bf16 v[98:101], v[158:161], v[228:231], v[98:101]
	s_setprio 0
	s_setprio 1
	v_mfma_f32_16x16x32_bf16 v[62:65], v[162:165], v[200:203], v[62:65]
	v_mfma_f32_16x16x32_bf16 v[58:61], v[174:177], v[200:203], v[58:61]
	v_mfma_f32_16x16x32_bf16 v[54:57], v[162:165], v[208:211], v[54:57]
	v_mfma_f32_16x16x32_bf16 v[50:53], v[174:177], v[208:211], v[50:53]
	v_mfma_f32_16x16x32_bf16 v[46:49], v[162:165], v[216:219], v[46:49]
	v_mfma_f32_16x16x32_bf16 v[42:45], v[174:177], v[216:219], v[42:45]
	v_mfma_f32_16x16x32_bf16 v[38:41], v[162:165], v[224:227], v[38:41]
	v_mfma_f32_16x16x32_bf16 v[34:37], v[174:177], v[224:227], v[34:37]
	v_mfma_f32_16x16x32_bf16 v[62:65], v[170:173], v[204:207], v[62:65]
	v_mfma_f32_16x16x32_bf16 v[58:61], v[178:181], v[204:207], v[58:61]
	v_mfma_f32_16x16x32_bf16 v[54:57], v[170:173], v[212:215], v[54:57]
	v_mfma_f32_16x16x32_bf16 v[50:53], v[178:181], v[212:215], v[50:53]
	v_mfma_f32_16x16x32_bf16 v[46:49], v[170:173], v[220:223], v[46:49]
	v_mfma_f32_16x16x32_bf16 v[42:45], v[178:181], v[220:223], v[42:45]
	v_mfma_f32_16x16x32_bf16 v[38:41], v[170:173], v[228:231], v[38:41]
	v_mfma_f32_16x16x32_bf16 v[34:37], v[178:181], v[228:231], v[34:37]
	s_barrier
	s_setprio 0
	s_add_i32 s20, s50, s24
	v_lshl_add_u64 v[148:149], v[148:149], 0, s[38:39]
	s_mov_b32 m0, s20
	ds_read_b128 v[200:203], v169 offset:49152
	ds_read_b128 v[204:207], v169 offset:50176
	ds_read_b128 v[208:211], v169 offset:51200
	ds_read_b128 v[212:215], v169 offset:52224
	ds_read_b128 v[216:219], v169 offset:53248
	ds_read_b128 v[220:223], v169 offset:54272
	ds_read_b128 v[224:227], v169 offset:55296
	ds_read_b128 v[228:231], v169 offset:56320
	global_load_lds_dwordx4 v[148:149], off
	s_add_i32 m0, s20, 0x2000
	s_add_u32 s18, s18, 0x40080
	v_lshl_add_u64 v[148:149], v[232:233], 0, s[38:39]
	s_addc_u32 s19, s19, 0
	s_add_i32 s20, s51, s24
	global_load_lds_dwordx4 v[148:149], off
	v_lshl_add_u64 v[148:149], s[18:19], 0, v[0:1]
	s_mov_b32 m0, s20
	s_nop 0
	global_load_lds_dwordx4 v[148:149], off
	v_lshl_add_u64 v[148:149], s[18:19], 0, v[130:131]
	s_add_i32 m0, s20, 0x2000
	s_nop 0
	global_load_lds_dwordx4 v[148:149], off
	v_lshl_add_u64 v[148:149], v[234:235], 0, s[38:39]
	s_mov_b32 m0, s31
	s_nop 0
	global_load_lds_dwordx4 v[148:149], off
	v_lshl_add_u64 v[148:149], v[236:237], 0, s[38:39]
	s_mov_b32 m0, s33
	s_nop 0
	global_load_lds_dwordx4 v[148:149], off
	s_waitcnt vmcnt(8)
	s_waitcnt lgkmcnt(0)
	s_setprio 1
	s_barrier
	v_mfma_f32_16x16x32_bf16 v[94:97], v[140:143], v[200:203], v[94:97]
	v_mfma_f32_16x16x32_bf16 v[90:93], v[154:157], v[200:203], v[90:93]
	v_mfma_f32_16x16x32_bf16 v[86:89], v[140:143], v[208:211], v[86:89]
	v_mfma_f32_16x16x32_bf16 v[82:85], v[154:157], v[208:211], v[82:85]
	v_mfma_f32_16x16x32_bf16 v[78:81], v[140:143], v[216:219], v[78:81]
	v_mfma_f32_16x16x32_bf16 v[74:77], v[154:157], v[216:219], v[74:77]
	v_mfma_f32_16x16x32_bf16 v[70:73], v[140:143], v[224:227], v[70:73]
	v_mfma_f32_16x16x32_bf16 v[66:69], v[154:157], v[224:227], v[66:69]
	v_mfma_f32_16x16x32_bf16 v[94:97], v[144:147], v[204:207], v[94:97]
	v_mfma_f32_16x16x32_bf16 v[90:93], v[158:161], v[204:207], v[90:93]
	v_mfma_f32_16x16x32_bf16 v[86:89], v[144:147], v[212:215], v[86:89]
	v_mfma_f32_16x16x32_bf16 v[82:85], v[158:161], v[212:215], v[82:85]
	v_mfma_f32_16x16x32_bf16 v[78:81], v[144:147], v[220:223], v[78:81]
	v_mfma_f32_16x16x32_bf16 v[74:77], v[158:161], v[220:223], v[74:77]
	v_mfma_f32_16x16x32_bf16 v[70:73], v[144:147], v[228:231], v[70:73]
	v_mfma_f32_16x16x32_bf16 v[66:69], v[158:161], v[228:231], v[66:69]
	s_setprio 0
	s_setprio 1
	v_mfma_f32_16x16x32_bf16 v[30:33], v[162:165], v[200:203], v[30:33]
	v_mfma_f32_16x16x32_bf16 v[26:29], v[174:177], v[200:203], v[26:29]
	v_mfma_f32_16x16x32_bf16 v[22:25], v[162:165], v[208:211], v[22:25]
	v_mfma_f32_16x16x32_bf16 v[18:21], v[174:177], v[208:211], v[18:21]
	v_mfma_f32_16x16x32_bf16 v[14:17], v[162:165], v[216:219], v[14:17]
	v_mfma_f32_16x16x32_bf16 v[10:13], v[174:177], v[216:219], v[10:13]
	v_mfma_f32_16x16x32_bf16 v[6:9], v[162:165], v[224:227], v[6:9]
	v_mfma_f32_16x16x32_bf16 v[2:5], v[174:177], v[224:227], v[2:5]
	v_mfma_f32_16x16x32_bf16 v[30:33], v[170:173], v[204:207], v[30:33]
	v_mfma_f32_16x16x32_bf16 v[26:29], v[178:181], v[204:207], v[26:29]
	v_mfma_f32_16x16x32_bf16 v[22:25], v[170:173], v[212:215], v[22:25]
	v_mfma_f32_16x16x32_bf16 v[18:21], v[178:181], v[212:215], v[18:21]
	v_mfma_f32_16x16x32_bf16 v[14:17], v[170:173], v[220:223], v[14:17]
	v_mfma_f32_16x16x32_bf16 v[10:13], v[178:181], v[220:223], v[10:13]
	v_mfma_f32_16x16x32_bf16 v[6:9], v[170:173], v[228:231], v[6:9]
	v_mfma_f32_16x16x32_bf16 v[2:5], v[178:181], v[228:231], v[2:5]
	s_barrier
	s_setprio 0
	s_add_i32 s49, s49, 2
	s_add_u32 s16, s16, 0x100
	s_addc_u32 s17, s17, 0
	s_add_u32 s47, s47, 0x100
	s_addc_u32 s48, s48, 0
	s_cmp_gt_u32 s49, 13
	s_cbranch_scc0 .LBB0_1090
	s_and_b64 vcc, exec, s[6:7]
	s_cbranch_vccz .LBB0_1093
	s_barrier
